# GEMM K-loops: per-segment s_setprio toggles removed, one static priority raise for the trailing four-wave half
# speedup vs baseline: 1.0103x; 1.0103x over previous
; __device__ __forceinline__ int otid() { int t = threadIdx.x; asm volatile("" : "+v"(t)); return t; }
; #define PG8_STAGE(bufoff, gbase, voff) do { _Pragma("unroll") for (int _i = 0; _i < 2; ++_i) \
;         __builtin_amdgcn_global_load_lds((const unsigned*)((const char*)(gbase) + (voff)[_i]), (LAS unsigned*)(lds + (bufoff) + ldsw + _i * 8192), 16, 0, 0); } while (0)
; #define PG8_BAR __builtin_amdgcn_s_barrier()
; template <class Epi, bool SEG>
; __device__ __forceinline__ void gemm_phase(LAS unsigned char* lds, const Gemm g, const StaticOrder& S, const Epi& E) {
;     const int tid = otid(), wid = __builtin_amdgcn_readfirstlane(tid >> 6), lane = tid & 63, wr = wid >> 2, wc = wid & 3, fr = lane & 15, fq = lane >> 4;
;     const int K = g.K, nt = K / BK, lda = g.lda;
;     unsigned voffA[2], voffB[2];
; #pragma unroll
;     for (int i = 0; i < 2; ++i) { int R, C; stage_rc(tid * 16 + i * 8192, R, C); const int Rb = Epi::PERM ? ((R & ~31) + perm32(R & 31)) : R;
;         voffA[i] = (unsigned)(R * lda + C) * 2u; voffB[i] = (unsigned)(Rb * K + C) * 2u; }
;     const size_t kstep = (size_t)(BK * 2);
;     const size_t hstepA = (size_t)HALF * lda * 2, hstepB = (size_t)HALF * K * 2;
;     const size_t tstepA = 2 * hstepA, tstepB = 2 * hstepB;
;     const unsigned ldsw = (unsigned)wid * 1024u;
;     const int aoff = lds_byte(wr * 64 + fr, fq * 8), boff = lds_byte(wc * 32 + fr, fq * 8);
;     ...
;     Unit cur, nxt; int ui = 0;
;     if (!S.next(0, cur)) return;
;     f32x4 acc[2][2][4][2];
; #pragma unroll
;     for (int a = 0; a < 2; ++a)
; #pragma unroll
;         for (int b = 0; b < 2; ++b)
; #pragma unroll
;             for (int m = 0; m < 4; ++m)
; #pragma unroll
;                 for (int n = 0; n < 2; ++n) acc[a][b][m][n] = (f32x4){0.f, 0.f, 0.f, 0.f};
;     bf16x8 At[4][2], B0[2][2], B1[2][2];
;     const char* cA = (const char*)g.A + (size_t)cur.pm * tstepA; const char* cB = (const char*)g.Bt + (size_t)cur.pn * tstepB;
;     PG8_STAGE(PG8_SB(0, 0), cB, voffB); PG8_STAGE(PG8_SA(0, 0), cA, voffA); PG8_STAGE(PG8_SB(0, 1), cB + hstepB, voffB); PG8_STAGE(PG8_SA(0, 1), cA + hstepA, voffA);
;     if (wr == 1) PG8_BAR;
.LBB0_39:
	s_and_b64 vcc, exec, s[0:1]
	s_cbranch_vccz .LBB0_52
	v_readlane_b32 s20, v253, 0
	s_waitcnt vmcnt(0)
	v_mov_b32_e32 v8, v160
	s_cmpk_gt_i32 s20, 0x3ff
	v_readfirstlane_b32 s21, v8
	s_cbranch_scc1 .LBB0_52
	v_lshlrev_b32_e32 v0, 4, v8
	s_waitcnt vmcnt(0)
	v_add_u32_e32 v3, 0x2000, v0
	v_ashrrev_i32_e32 v2, 31, v3
	v_lshrrev_b32_e32 v2, 22, v2
	v_add_u32_e32 v2, v3, v2
	v_ashrrev_i32_e32 v2, 10, v2
	v_mul_i32_i24_e32 v4, 0x400, v2
	v_sub_u32_e32 v3, v3, v4
	v_lshrrev_b32_e32 v4, 4, v3
	v_bitop3_b32 v4, v4, v3, 32 bitop3:0x6c
	v_ashrrev_i32_e32 v3, 31, v4
	v_lshrrev_b32_e32 v3, 26, v3
	v_add_u32_e32 v5, v4, v3
	v_lshlrev_b32_e32 v6, 3, v2
	v_ashrrev_i32_e32 v3, 6, v5
	v_and_b32_e32 v6, -16, v6
	v_add_u32_e32 v6, v3, v6
	v_and_b32_e32 v7, 3, v3
	s_mov_b32 s0, 0x3ffe0
	v_lshrrev_b32_e32 v9, 2, v6
	v_lshlrev_b32_e32 v10, 1, v6
	v_and_b32_e32 v5, 0xc0, v5
	v_and_or_b32 v7, v6, s0, v7
	v_and_b32_e32 v9, 4, v9
	v_and_b32_e32 v10, 24, v10
	v_sub_u32_e32 v4, v4, v5
	v_or3_b32 v7, v7, v9, v10
	v_lshlrev_b32_e32 v9, 5, v2
	v_ashrrev_i16_sdwa v4, v172, sext(v4) dst_sel:DWORD dst_unused:UNUSED_PAD src0_sel:DWORD src1_sel:BYTE_0
	v_and_b32_e32 v9, 32, v9
	v_bfe_i32 v4, v4, 0, 16
	v_add_lshl_u32 v5, v9, v4, 1
	v_lshl_add_u32 v142, v7, 14, v5
	v_lshl_add_u32 v144, v6, 14, v5
	v_bfe_i32 v5, v8, 27, 1
	v_lshrrev_b32_e32 v5, 22, v5
	v_add_u32_e32 v5, v0, v5
	v_and_b32_e32 v5, 0xfffffc00, v5
	v_sub_u32_e32 v0, v0, v5
	v_lshrrev_b32_e32 v5, 4, v0
	v_bitop3_b32 v7, v5, v0, 32 bitop3:0x6c
	v_ashrrev_i32_e32 v0, 31, v0
	v_lshrrev_b32_e32 v0, 26, v0
	v_add_u32_e32 v0, v7, v0
	v_ashrrev_i32_e32 v5, 6, v0
	v_ashrrev_i32_e32 v0, 31, v8
	v_lshrrev_b32_e32 v0, 26, v0
	v_add_u32_e32 v0, v8, v0
	v_ashrrev_i32_e32 v6, 6, v0
	v_lshlrev_b32_e32 v0, 3, v6
	v_and_b32_e32 v0, -16, v0
	v_add_u32_e32 v9, v5, v0
	v_and_b32_e32 v0, 3, v5
	s_ashr_i32 s24, s20, 31
	v_and_or_b32 v0, v9, s0, v0
	s_lshr_b32 s0, s24, 29
	s_add_i32 s0, s20, s0
	s_ashr_i32 s1, s21, 6
	s_ashr_i32 s3, s0, 3
	s_and_b32 s0, s0, -8
	s_ashr_i32 s2, s21, 8
	s_lshl_b32 s23, s1, 10
	s_sub_i32 s0, s20, s0
	s_cmp_lt_i32 s0, 0
	s_movk_i32 s4, 0x81
	s_cselect_b32 s4, s4, 0x80
	s_mul_i32 s0, s4, s0
	s_add_i32 s0, s0, s3
	s_ashr_i32 s3, s0, 31
	s_lshr_b32 s3, s3, 26
	s_add_i32 s3, s0, s3
	s_ashr_i32 s4, s3, 6
	s_and_b32 s3, s3, 0xffc0
	s_sub_i32 s3, s0, s3
	s_bfe_i32 s0, s3, 0x80000
	s_bfe_u32 s0, s0, 0x3000c
	s_add_i32 s5, s3, s0
	s_bfe_i32 s0, s5, 0x80000
	s_and_b32 s5, s5, 0xf8
	v_lshrrev_b32_e32 v10, 2, v9
	v_lshlrev_b32_e32 v11, 1, v9
	s_sub_i32 s3, s3, s5
	v_and_b32_e32 v10, 4, v10
	v_and_b32_e32 v11, 24, v11
	s_lshl_b32 s4, s4, 3
	s_sext_i32_i16 s0, s0
	s_sext_i32_i8 s3, s3
	v_or3_b32 v0, v0, v10, v11
	v_mul_i32_i24_e32 v11, 64, v5
	s_lshr_b32 s0, s0, 3
	s_add_i32 s8, s4, s3
	v_sub_u32_e32 v7, v7, v11
	s_ashr_i32 s9, s8, 31
	s_bfe_i64 s[6:7], s[0:1], 0x100000
	v_lshlrev_b32_e32 v10, 5, v6
	v_ashrrev_i16_sdwa v7, v172, sext(v7) dst_sel:DWORD dst_unused:UNUSED_PAD src0_sel:DWORD src1_sel:BYTE_0
	s_lshl_b64 s[4:5], s[8:9], 22
	s_lshl_b64 s[6:7], s[6:7], 22
	v_readlane_b32 s10, v253, 8
	v_and_b32_e32 v10, 32, v10
	v_bfe_i32 v7, v7, 0, 16
	v_readlane_b32 s11, v253, 9
	s_add_u32 s14, s10, s6
	v_add_lshl_u32 v10, v10, v7, 1
	s_addc_u32 s15, s11, s7
	s_add_i32 s9, s23, 0
	v_lshl_add_u32 v0, v0, 14, v10
	s_add_i32 m0, s9, 0x10000
	v_lshl_add_u32 v146, v9, 14, v10
	global_load_lds_dwordx4 v0, s[14:15]
	s_add_i32 m0, s9, 0x12000
	s_add_u32 s12, s78, s4
	global_load_lds_dwordx4 v142, s[14:15]
	s_addc_u32 s13, s79, s5
	s_mov_b32 m0, s9
	s_add_i32 s25, s9, 0x2000
	global_load_lds_dwordx4 v146, s[12:13]
	s_mov_b32 m0, s25
	s_add_u32 s4, s14, 0x200000
	global_load_lds_dwordx4 v144, s[12:13]
	s_addc_u32 s5, s15, 0
	s_add_i32 m0, s9, 0x14000
	s_nop 0
	global_load_lds_dwordx4 v0, s[4:5]
	s_add_i32 m0, s9, 0x16000
	s_nop 0
	global_load_lds_dwordx4 v142, s[4:5]
	s_add_u32 s4, s12, 0x200000
	s_addc_u32 s5, s13, 0
	s_add_i32 s26, s9, 0x4000
	s_mov_b32 m0, s26
	s_add_i32 s27, s9, 0x6000
	global_load_lds_dwordx4 v146, s[4:5]
	s_mov_b32 m0, s27
	s_cmp_lg_u32 s2, 1
	global_load_lds_dwordx4 v144, s[4:5]
	s_cbranch_scc1 .LBB0_43
	s_setprio 1
	s_barrier

; #define PG8_STAGE(bufoff, gbase, voff) do { _Pragma("unroll") for (int _i = 0; _i < 2; ++_i) \
;         __builtin_amdgcn_global_load_lds((const unsigned*)((const char*)(gbase) + (voff)[_i]), (LAS unsigned*)(lds + (bufoff) + ldsw + _i * 8192), 16, 0, 0); } while (0)
; #define PG8_LDA(dst, b, h) do { _Pragma("unroll") for (int m = 0; m < 4; ++m) _Pragma("unroll") for (int k = 0; k < 2; ++k) dst[m][k] = *(const LAS bf16x8*)(lds + PG8_SA(b, h) + aoff + m * 2048 + k * 1024); } while (0)
; #define PG8_LDB(dst, b, h) do { _Pragma("unroll") for (int n = 0; n < 2; ++n) _Pragma("unroll") for (int k = 0; k < 2; ++k) dst[n][k] = *(const LAS bf16x8*)(lds + PG8_SB(b, h) + boff + n * 2048 + k * 1024); } while (0)
; #define PG8_MMA(ai, bj, At, Bt) do { __builtin_amdgcn_s_setprio(1); _Pragma("unroll") for (int m = 0; m < 4; ++m) _Pragma("unroll") for (int n = 0; n < 2; ++n) _Pragma("unroll") for (int k = 0; k < 2; ++k) \
;         acc[ai][bj][m][n] = __builtin_amdgcn_mfma_f32_16x16x32_bf16(Bt[n][k], At[m][k], acc[ai][bj][m][n], 0, 0, 0); __builtin_amdgcn_s_setprio(0); } while (0)
; #define PG8_WAIT_L(n) asm volatile("s_waitcnt lgkmcnt(" #n ")" ::: "memory")
; #define PG8_BAR __builtin_amdgcn_s_barrier()
; #define PG8_SCHED __builtin_amdgcn_sched_barrier(0)
; template <class Epi, bool SEG>
; __device__ __forceinline__ void gemm_phase(LAS unsigned char* lds, const Gemm g, const StaticOrder& S, const Epi& E) {
;     ...
;         for (int t = 0; t < nt; t += 2) {
;             const bool last = (t == nt - 2);
;             const char* a1 = cA + akoff<SEG>(t) + kstep;
;             const char* a2 = last ? nA : cA + akoff<SEG>(t + 2); const char* b2 = last ? nB : cB + (size_t)(t + 2) * kstep;
;             const char* a3 = a2 + kstep; const char* b3 = b2 + kstep;
;             PG8_LDB(B0, 0, 0); PG8_SCHED; PG8_LDA(At, 0, 0); PG8_STAGE(PG8_SA(1, 1), a1 + hstepA, voffA);
;             PG8_WAIT_L(8); PG8_BAR; PG8_WAIT_L(0); PG8_MMA(0, 0, At, B0); PG8_BAR; PG8_SCHED;
;             PG8_LDB(B1, 0, 1); PG8_STAGE(PG8_SB(0, 0), b2, voffB);
;             PG8_BAR; PG8_WAIT_L(0); PG8_MMA(0, 1, At, B1); PG8_BAR;
;             PG8_LDA(At, 0, 1); PG8_STAGE(PG8_SA(0, 0), a2, voffA);
;             PG8_BAR; PG8_WAIT_L(0); PG8_MMA(1, 0, At, B0); PG8_BAR; PG8_SCHED;
.LBB0_47:
	s_add_u32 s14, s12, 0xffe00080
	s_addc_u32 s15, s13, -1
	s_add_i32 s39, 0, 0x10000
	v_add_u32_e32 v152, s39, v155
	ds_read_b128 v[180:183], v152
	ds_read_b128 v[184:187], v152 offset:1024
	ds_read_b128 v[188:191], v152 offset:2048
	ds_read_b128 v[198:201], v152 offset:3072
	s_cmpk_eq_i32 s38, 0x7c
	s_cselect_b32 s17, s5, s15
	s_cselect_b32 s16, s34, s14
	s_cselect_b32 s15, s1, s37
	s_cselect_b32 s14, s35, s36
	v_lshl_add_u64 v[152:153], s[12:13], 0, v[148:149]
	s_add_i32 m0, s9, 0xc000
	ds_read_b128 v[202:205], v157
	ds_read_b128 v[206:209], v157 offset:1024
	ds_read_b128 v[210:213], v157 offset:2048
	ds_read_b128 v[214:217], v157 offset:3072
	ds_read_b128 v[218:221], v157 offset:4096
	ds_read_b128 v[222:225], v157 offset:5120
	ds_read_b128 v[226:229], v157 offset:6144
	ds_read_b128 v[230:233], v157 offset:7168
	global_load_lds_dwordx4 v[152:153], off
	v_lshl_add_u64 v[152:153], s[12:13], 0, v[150:151]
	s_add_i32 m0, s9, 0xe000
	s_nop 0
	global_load_lds_dwordx4 v[152:153], off
	s_waitcnt lgkmcnt(8)
	s_barrier
	s_waitcnt lgkmcnt(0)
	s_waitcnt lgkmcnt(0)
	v_mfma_f32_16x16x32_bf16 v[126:129], v[180:183], v[202:205], v[126:129]
	v_mfma_f32_16x16x32_bf16 v[122:125], v[188:191], v[202:205], v[122:125]
	v_mfma_f32_16x16x32_bf16 v[118:121], v[180:183], v[210:213], v[118:121]
	v_mfma_f32_16x16x32_bf16 v[110:113], v[188:191], v[210:213], v[110:113]
	v_mfma_f32_16x16x32_bf16 v[102:105], v[180:183], v[218:221], v[102:105]
	v_mfma_f32_16x16x32_bf16 v[94:97], v[188:191], v[218:221], v[94:97]
	v_mfma_f32_16x16x32_bf16 v[82:85], v[180:183], v[226:229], v[82:85]
	v_mfma_f32_16x16x32_bf16 v[74:77], v[188:191], v[226:229], v[74:77]
	v_mfma_f32_16x16x32_bf16 v[126:129], v[184:187], v[206:209], v[126:129]
	v_mfma_f32_16x16x32_bf16 v[122:125], v[198:201], v[206:209], v[122:125]
	v_mfma_f32_16x16x32_bf16 v[118:121], v[184:187], v[214:217], v[118:121]
	v_mfma_f32_16x16x32_bf16 v[110:113], v[198:201], v[214:217], v[110:113]
	v_mfma_f32_16x16x32_bf16 v[102:105], v[184:187], v[222:225], v[102:105]
	v_mfma_f32_16x16x32_bf16 v[94:97], v[198:201], v[222:225], v[94:97]
	v_mfma_f32_16x16x32_bf16 v[82:85], v[184:187], v[230:233], v[82:85]
	v_mfma_f32_16x16x32_bf16 v[74:77], v[198:201], v[230:233], v[74:77]
	s_barrier
	s_add_i32 s42, 0, 0x14000
	v_add_u32_e32 v152, s42, v155
	s_add_i32 s39, s39, s23
	ds_read_b128 v[234:237], v152
	ds_read_b128 v[238:241], v152 offset:1024
	ds_read_b128 v[242:245], v152 offset:2048
	ds_read_b128 v[246:249], v152 offset:3072
	v_lshl_add_u64 v[152:153], s[14:15], 0, v[0:1]
	s_mov_b32 m0, s39
	v_lshl_add_u64 v[158:159], s[14:15], 0, v[142:143]
	global_load_lds_dwordx4 v[152:153], off
	s_add_i32 m0, s39, 0x2000
	s_nop 0
	global_load_lds_dwordx4 v[158:159], off
	s_barrier
	s_waitcnt lgkmcnt(0)
	s_waitcnt lgkmcnt(0)
	v_mfma_f32_16x16x32_bf16 v[114:117], v[234:237], v[202:205], v[114:117]
	v_mfma_f32_16x16x32_bf16 v[106:109], v[242:245], v[202:205], v[106:109]
	v_mfma_f32_16x16x32_bf16 v[98:101], v[234:237], v[210:213], v[98:101]
	v_mfma_f32_16x16x32_bf16 v[90:93], v[242:245], v[210:213], v[90:93]
	v_mfma_f32_16x16x32_bf16 v[86:89], v[234:237], v[218:221], v[86:89]
	v_mfma_f32_16x16x32_bf16 v[78:81], v[242:245], v[218:221], v[78:81]
	v_mfma_f32_16x16x32_bf16 v[70:73], v[234:237], v[226:229], v[70:73]
	v_mfma_f32_16x16x32_bf16 v[66:69], v[242:245], v[226:229], v[66:69]
	v_mfma_f32_16x16x32_bf16 v[114:117], v[238:241], v[206:209], v[114:117]
	v_mfma_f32_16x16x32_bf16 v[106:109], v[246:249], v[206:209], v[106:109]
	v_mfma_f32_16x16x32_bf16 v[98:101], v[238:241], v[214:217], v[98:101]
	v_mfma_f32_16x16x32_bf16 v[90:93], v[246:249], v[214:217], v[90:93]
	v_mfma_f32_16x16x32_bf16 v[86:89], v[238:241], v[222:225], v[86:89]
	v_mfma_f32_16x16x32_bf16 v[78:81], v[246:249], v[222:225], v[78:81]
	v_mfma_f32_16x16x32_bf16 v[70:73], v[238:241], v[230:233], v[70:73]
	v_mfma_f32_16x16x32_bf16 v[66:69], v[246:249], v[230:233], v[66:69]
	s_mov_b32 m0, s9
	v_lshl_add_u64 v[192:193], s[16:17], 0, v[146:147]
	s_barrier
	ds_read_b128 v[202:205], v157 offset:16384
	ds_read_b128 v[206:209], v157 offset:17408
	ds_read_b128 v[210:213], v157 offset:18432
	ds_read_b128 v[214:217], v157 offset:19456
	ds_read_b128 v[218:221], v157 offset:20480
	ds_read_b128 v[222:225], v157 offset:21504
	ds_read_b128 v[226:229], v157 offset:22528
	ds_read_b128 v[230:233], v157 offset:23552
	global_load_lds_dwordx4 v[192:193], off
	v_lshl_add_u64 v[250:251], s[16:17], 0, v[144:145]
	s_mov_b32 m0, s25
	s_nop 0
	global_load_lds_dwordx4 v[250:251], off
	s_barrier
	s_waitcnt lgkmcnt(0)
	s_waitcnt lgkmcnt(0)
	v_mfma_f32_16x16x32_bf16 v[62:65], v[180:183], v[202:205], v[62:65]
	v_mfma_f32_16x16x32_bf16 v[58:61], v[188:191], v[202:205], v[58:61]
	v_mfma_f32_16x16x32_bf16 v[54:57], v[180:183], v[210:213], v[54:57]
	v_mfma_f32_16x16x32_bf16 v[46:49], v[188:191], v[210:213], v[46:49]
	v_mfma_f32_16x16x32_bf16 v[38:41], v[180:183], v[218:221], v[38:41]
	v_mfma_f32_16x16x32_bf16 v[30:33], v[188:191], v[218:221], v[30:33]
	v_mfma_f32_16x16x32_bf16 v[22:25], v[180:183], v[226:229], v[22:25]
	v_mfma_f32_16x16x32_bf16 v[14:17], v[188:191], v[226:229], v[14:17]
	v_mfma_f32_16x16x32_bf16 v[62:65], v[184:187], v[206:209], v[62:65]
	v_mfma_f32_16x16x32_bf16 v[58:61], v[198:201], v[206:209], v[58:61]
	v_mfma_f32_16x16x32_bf16 v[54:57], v[184:187], v[214:217], v[54:57]
	v_mfma_f32_16x16x32_bf16 v[46:49], v[198:201], v[214:217], v[46:49]
	v_mfma_f32_16x16x32_bf16 v[38:41], v[184:187], v[222:225], v[38:41]
	v_mfma_f32_16x16x32_bf16 v[30:33], v[198:201], v[222:225], v[30:33]
	v_mfma_f32_16x16x32_bf16 v[22:25], v[184:187], v[230:233], v[22:25]
	v_mfma_f32_16x16x32_bf16 v[14:17], v[198:201], v[230:233], v[14:17]
	s_barrier
; #define PG8_STAGE(bufoff, gbase, voff) do { _Pragma("unroll") for (int _i = 0; _i < 2; ++_i) \
;         __builtin_amdgcn_global_load_lds((const unsigned*)((const char*)(gbase) + (voff)[_i]), (LAS unsigned*)(lds + (bufoff) + ldsw + _i * 8192), 16, 0, 0); } while (0)
; #define PG8_LDA(dst, b, h) do { _Pragma("unroll") for (int m = 0; m < 4; ++m) _Pragma("unroll") for (int k = 0; k < 2; ++k) dst[m][k] = *(const LAS bf16x8*)(lds + PG8_SA(b, h) + aoff + m * 2048 + k * 1024); } while (0)
; #define PG8_LDB(dst, b, h) do { _Pragma("unroll") for (int n = 0; n < 2; ++n) _Pragma("unroll") for (int k = 0; k < 2; ++k) dst[n][k] = *(const LAS bf16x8*)(lds + PG8_SB(b, h) + boff + n * 2048 + k * 1024); } while (0)
; #define PG8_MMA(ai, bj, At, Bt) do { __builtin_amdgcn_s_setprio(1); _Pragma("unroll") for (int m = 0; m < 4; ++m) _Pragma("unroll") for (int n = 0; n < 2; ++n) _Pragma("unroll") for (int k = 0; k < 2; ++k) \
;         acc[ai][bj][m][n] = __builtin_amdgcn_mfma_f32_16x16x32_bf16(Bt[n][k], At[m][k], acc[ai][bj][m][n], 0, 0, 0); __builtin_amdgcn_s_setprio(0); } while (0)
; #define PG8_WAIT_V(n) asm volatile("s_waitcnt vmcnt(" #n ")" ::: "memory")
; #define PG8_WAIT_L(n) asm volatile("s_waitcnt lgkmcnt(" #n ")" ::: "memory")
; #define PG8_BAR __builtin_amdgcn_s_barrier()
; #define PG8_SCHED __builtin_amdgcn_sched_barrier(0)
; template <class Epi, bool SEG>
; __device__ __forceinline__ void gemm_phase(LAS unsigned char* lds, const Gemm g, const StaticOrder& S, const Epi& E) {
;     ...
;             PG8_STAGE(PG8_SB(0, 1), b2 + hstepB, voffB);
;             PG8_WAIT_V(6); PG8_BAR; PG8_MMA(1, 1, At, B1); PG8_BAR;
;             PG8_LDB(B0, 1, 0); PG8_SCHED; PG8_LDA(At, 1, 0); PG8_STAGE(PG8_SA(0, 1), a2 + hstepA, voffA);
;             PG8_WAIT_L(8); PG8_BAR; PG8_WAIT_L(0); PG8_MMA(0, 0, At, B0); PG8_BAR; PG8_SCHED;
;             PG8_LDB(B1, 1, 1); PG8_STAGE(PG8_SB(1, 0), b3, voffB);
;             PG8_BAR; PG8_WAIT_L(0); PG8_MMA(0, 1, At, B1); PG8_BAR;
;             PG8_LDA(At, 1, 1); PG8_STAGE(PG8_SA(1, 0), a3, voffA);
;             PG8_BAR; PG8_WAIT_L(0); PG8_MMA(1, 0, At, B0); PG8_BAR; PG8_SCHED;
	s_add_u32 s40, s14, 0x200000
	s_addc_u32 s41, s15, 0
	s_add_i32 s39, s42, s23
	v_lshl_add_u64 v[180:181], s[40:41], 0, v[0:1]
	s_mov_b32 m0, s39
	s_nop 0
	global_load_lds_dwordx4 v[180:181], off
	v_lshl_add_u64 v[180:181], s[40:41], 0, v[142:143]
	s_add_i32 m0, s39, 0x2000
	s_nop 0
	global_load_lds_dwordx4 v[180:181], off
	s_waitcnt vmcnt(6)
	s_barrier
	v_mfma_f32_16x16x32_bf16 v[50:53], v[234:237], v[202:205], v[50:53]
	v_mfma_f32_16x16x32_bf16 v[42:45], v[242:245], v[202:205], v[42:45]
	v_mfma_f32_16x16x32_bf16 v[34:37], v[234:237], v[210:213], v[34:37]
	v_mfma_f32_16x16x32_bf16 v[26:29], v[242:245], v[210:213], v[26:29]
	v_mfma_f32_16x16x32_bf16 v[18:21], v[234:237], v[218:221], v[18:21]
	v_mfma_f32_16x16x32_bf16 v[10:13], v[242:245], v[218:221], v[10:13]
	v_mfma_f32_16x16x32_bf16 v[6:9], v[234:237], v[226:229], v[6:9]
	v_mfma_f32_16x16x32_bf16 v[2:5], v[242:245], v[226:229], v[2:5]
	v_mfma_f32_16x16x32_bf16 v[50:53], v[238:241], v[206:209], v[50:53]
	v_mfma_f32_16x16x32_bf16 v[42:45], v[246:249], v[206:209], v[42:45]
	v_mfma_f32_16x16x32_bf16 v[34:37], v[238:241], v[214:217], v[34:37]
	v_mfma_f32_16x16x32_bf16 v[26:29], v[246:249], v[214:217], v[26:29]
	v_mfma_f32_16x16x32_bf16 v[18:21], v[238:241], v[222:225], v[18:21]
	v_mfma_f32_16x16x32_bf16 v[10:13], v[246:249], v[222:225], v[10:13]
	v_mfma_f32_16x16x32_bf16 v[6:9], v[238:241], v[230:233], v[6:9]
	v_mfma_f32_16x16x32_bf16 v[2:5], v[246:249], v[230:233], v[2:5]
	s_add_i32 s39, 0, 0x18000
	v_add_u32_e32 v179, s39, v155
	s_barrier
	ds_read_b128 v[180:183], v179
	ds_read_b128 v[184:187], v179 offset:1024
	ds_read_b128 v[188:191], v179 offset:2048
	ds_read_b128 v[198:201], v179 offset:3072
	s_add_u32 s16, s16, 0x200000
	s_addc_u32 s17, s17, 0
	s_mov_b32 m0, s26
	v_lshl_add_u64 v[234:235], s[16:17], 0, v[146:147]
	ds_read_b128 v[202:205], v157 offset:32768
	ds_read_b128 v[206:209], v157 offset:33792
	ds_read_b128 v[210:213], v157 offset:34816
	ds_read_b128 v[214:217], v157 offset:35840
	ds_read_b128 v[218:221], v157 offset:36864
	ds_read_b128 v[222:225], v157 offset:37888
	ds_read_b128 v[226:229], v157 offset:38912
	ds_read_b128 v[230:233], v157 offset:39936
	global_load_lds_dwordx4 v[234:235], off
	v_lshl_add_u64 v[234:235], s[16:17], 0, v[144:145]
	s_mov_b32 m0, s27
	s_nop 0
	global_load_lds_dwordx4 v[234:235], off
	s_waitcnt lgkmcnt(8)
	s_barrier
	s_waitcnt lgkmcnt(0)
	s_waitcnt lgkmcnt(0)
	v_mfma_f32_16x16x32_bf16 v[126:129], v[180:183], v[202:205], v[126:129]
	v_mfma_f32_16x16x32_bf16 v[122:125], v[188:191], v[202:205], v[122:125]
	v_mfma_f32_16x16x32_bf16 v[118:121], v[180:183], v[210:213], v[118:121]
	v_mfma_f32_16x16x32_bf16 v[110:113], v[188:191], v[210:213], v[110:113]
	v_mfma_f32_16x16x32_bf16 v[102:105], v[180:183], v[218:221], v[102:105]
	v_mfma_f32_16x16x32_bf16 v[94:97], v[188:191], v[218:221], v[94:97]
	v_mfma_f32_16x16x32_bf16 v[82:85], v[180:183], v[226:229], v[82:85]
	v_mfma_f32_16x16x32_bf16 v[74:77], v[188:191], v[226:229], v[74:77]
	v_mfma_f32_16x16x32_bf16 v[126:129], v[184:187], v[206:209], v[126:129]
	v_mfma_f32_16x16x32_bf16 v[122:125], v[198:201], v[206:209], v[122:125]
	v_mfma_f32_16x16x32_bf16 v[118:121], v[184:187], v[214:217], v[118:121]
	v_mfma_f32_16x16x32_bf16 v[110:113], v[198:201], v[214:217], v[110:113]
	v_mfma_f32_16x16x32_bf16 v[102:105], v[184:187], v[222:225], v[102:105]
	v_mfma_f32_16x16x32_bf16 v[94:97], v[198:201], v[222:225], v[94:97]
	v_mfma_f32_16x16x32_bf16 v[82:85], v[184:187], v[230:233], v[82:85]
	v_mfma_f32_16x16x32_bf16 v[74:77], v[198:201], v[230:233], v[74:77]
	s_barrier
	s_add_i32 s16, 0, 0x1c000
	s_add_i32 s17, s39, s23
	v_add_u32_e32 v179, s16, v155
	v_lshl_add_u64 v[152:153], v[152:153], 0, s[96:97]
	s_mov_b32 m0, s17
	ds_read_b128 v[234:237], v179
	ds_read_b128 v[238:241], v179 offset:1024
	ds_read_b128 v[242:245], v179 offset:2048
	ds_read_b128 v[246:249], v179 offset:3072
	global_load_lds_dwordx4 v[152:153], off
	v_lshl_add_u64 v[152:153], v[158:159], 0, s[96:97]
	s_add_i32 m0, s17, 0x2000
	s_nop 0
	global_load_lds_dwordx4 v[152:153], off
	s_barrier
	s_waitcnt lgkmcnt(0)
	s_waitcnt lgkmcnt(0)
	v_mfma_f32_16x16x32_bf16 v[114:117], v[234:237], v[202:205], v[114:117]
	v_mfma_f32_16x16x32_bf16 v[106:109], v[242:245], v[202:205], v[106:109]
	v_mfma_f32_16x16x32_bf16 v[98:101], v[234:237], v[210:213], v[98:101]
	v_mfma_f32_16x16x32_bf16 v[90:93], v[242:245], v[210:213], v[90:93]
	v_mfma_f32_16x16x32_bf16 v[86:89], v[234:237], v[218:221], v[86:89]
	v_mfma_f32_16x16x32_bf16 v[78:81], v[242:245], v[218:221], v[78:81]
	v_mfma_f32_16x16x32_bf16 v[70:73], v[234:237], v[226:229], v[70:73]
	v_mfma_f32_16x16x32_bf16 v[66:69], v[242:245], v[226:229], v[66:69]
	v_mfma_f32_16x16x32_bf16 v[114:117], v[238:241], v[206:209], v[114:117]
	v_mfma_f32_16x16x32_bf16 v[106:109], v[246:249], v[206:209], v[106:109]
	v_mfma_f32_16x16x32_bf16 v[98:101], v[238:241], v[214:217], v[98:101]
	v_mfma_f32_16x16x32_bf16 v[90:93], v[246:249], v[214:217], v[90:93]
	v_mfma_f32_16x16x32_bf16 v[86:89], v[238:241], v[222:225], v[86:89]
	v_mfma_f32_16x16x32_bf16 v[78:81], v[246:249], v[222:225], v[78:81]
	v_mfma_f32_16x16x32_bf16 v[70:73], v[238:241], v[230:233], v[70:73]
	v_mfma_f32_16x16x32_bf16 v[66:69], v[246:249], v[230:233], v[66:69]
	s_mov_b32 m0, s28
	v_lshl_add_u64 v[152:153], v[192:193], 0, s[96:97]
	s_barrier
	ds_read_b128 v[202:205], v157 offset:49152
	ds_read_b128 v[206:209], v157 offset:50176
	ds_read_b128 v[210:213], v157 offset:51200
	ds_read_b128 v[214:217], v157 offset:52224
	ds_read_b128 v[218:221], v157 offset:53248
	ds_read_b128 v[222:225], v157 offset:54272
	ds_read_b128 v[226:229], v157 offset:55296
	ds_read_b128 v[230:233], v157 offset:56320
	global_load_lds_dwordx4 v[152:153], off
	v_lshl_add_u64 v[152:153], v[250:251], 0, s[96:97]
	s_mov_b32 m0, s29
	s_nop 0
	global_load_lds_dwordx4 v[152:153], off
	s_barrier
; #define PG8_STAGE(bufoff, gbase, voff) do { _Pragma("unroll") for (int _i = 0; _i < 2; ++_i) \
;         __builtin_amdgcn_global_load_lds((const unsigned*)((const char*)(gbase) + (voff)[_i]), (LAS unsigned*)(lds + (bufoff) + ldsw + _i * 8192), 16, 0, 0); } while (0)
; #define PG8_MMA(ai, bj, At, Bt) do { __builtin_amdgcn_s_setprio(1); _Pragma("unroll") for (int m = 0; m < 4; ++m) _Pragma("unroll") for (int n = 0; n < 2; ++n) _Pragma("unroll") for (int k = 0; k < 2; ++k) \
;         acc[ai][bj][m][n] = __builtin_amdgcn_mfma_f32_16x16x32_bf16(Bt[n][k], At[m][k], acc[ai][bj][m][n], 0, 0, 0); __builtin_amdgcn_s_setprio(0); } while (0)
; #define PG8_WAIT_V(n) asm volatile("s_waitcnt vmcnt(" #n ")" ::: "memory")
; #define PG8_WAIT_L(n) asm volatile("s_waitcnt lgkmcnt(" #n ")" ::: "memory")
; #define PG8_BAR __builtin_amdgcn_s_barrier()
; #define PG8_SCHED __builtin_amdgcn_sched_barrier(0)
; template <class Epi, bool SEG>
; __device__ __forceinline__ void gemm_phase(LAS unsigned char* lds, const Gemm g, const StaticOrder& S, const Epi& E) {
;     ...
;             PG8_BAR; PG8_WAIT_L(0); PG8_MMA(1, 0, At, B0); PG8_BAR; PG8_SCHED;
;             PG8_STAGE(PG8_SB(1, 1), b3 + hstepB, voffB);
;             PG8_WAIT_V(6); PG8_BAR; PG8_MMA(1, 1, At, B1); PG8_BAR;
;         }
	s_waitcnt lgkmcnt(0)
	s_waitcnt lgkmcnt(0)
	v_mfma_f32_16x16x32_bf16 v[62:65], v[180:183], v[202:205], v[62:65]
	v_mfma_f32_16x16x32_bf16 v[58:61], v[188:191], v[202:205], v[58:61]
	v_mfma_f32_16x16x32_bf16 v[54:57], v[180:183], v[210:213], v[54:57]
	v_mfma_f32_16x16x32_bf16 v[46:49], v[188:191], v[210:213], v[46:49]
	v_mfma_f32_16x16x32_bf16 v[38:41], v[180:183], v[218:221], v[38:41]
	v_mfma_f32_16x16x32_bf16 v[30:33], v[188:191], v[218:221], v[30:33]
	v_mfma_f32_16x16x32_bf16 v[22:25], v[180:183], v[226:229], v[22:25]
	v_mfma_f32_16x16x32_bf16 v[14:17], v[188:191], v[226:229], v[14:17]
	v_mfma_f32_16x16x32_bf16 v[62:65], v[184:187], v[206:209], v[62:65]
	v_mfma_f32_16x16x32_bf16 v[58:61], v[198:201], v[206:209], v[58:61]
	v_mfma_f32_16x16x32_bf16 v[54:57], v[184:187], v[214:217], v[54:57]
	v_mfma_f32_16x16x32_bf16 v[46:49], v[198:201], v[214:217], v[46:49]
	v_mfma_f32_16x16x32_bf16 v[38:41], v[184:187], v[222:225], v[38:41]
	v_mfma_f32_16x16x32_bf16 v[30:33], v[198:201], v[222:225], v[30:33]
	v_mfma_f32_16x16x32_bf16 v[22:25], v[184:187], v[230:233], v[22:25]
	v_mfma_f32_16x16x32_bf16 v[14:17], v[198:201], v[230:233], v[14:17]
	s_barrier
	s_add_u32 s14, s14, 0x200080
	s_addc_u32 s15, s15, 0
	s_add_i32 s16, s16, s23
	v_lshl_add_u64 v[152:153], s[14:15], 0, v[0:1]
	s_mov_b32 m0, s16
	s_nop 0
	global_load_lds_dwordx4 v[152:153], off
	v_lshl_add_u64 v[152:153], s[14:15], 0, v[142:143]
	s_add_i32 m0, s16, 0x2000
	s_nop 0
	global_load_lds_dwordx4 v[152:153], off
	s_waitcnt vmcnt(6)
	s_barrier
	v_mfma_f32_16x16x32_bf16 v[50:53], v[234:237], v[202:205], v[50:53]
	v_mfma_f32_16x16x32_bf16 v[42:45], v[242:245], v[202:205], v[42:45]
	v_mfma_f32_16x16x32_bf16 v[34:37], v[234:237], v[210:213], v[34:37]
	v_mfma_f32_16x16x32_bf16 v[26:29], v[242:245], v[210:213], v[26:29]
	v_mfma_f32_16x16x32_bf16 v[18:21], v[234:237], v[218:221], v[18:21]
	v_mfma_f32_16x16x32_bf16 v[10:13], v[242:245], v[218:221], v[10:13]
	v_mfma_f32_16x16x32_bf16 v[6:9], v[234:237], v[226:229], v[6:9]
	v_mfma_f32_16x16x32_bf16 v[2:5], v[242:245], v[226:229], v[2:5]
	v_mfma_f32_16x16x32_bf16 v[50:53], v[238:241], v[206:209], v[50:53]
	v_mfma_f32_16x16x32_bf16 v[42:45], v[246:249], v[206:209], v[42:45]
	v_mfma_f32_16x16x32_bf16 v[34:37], v[238:241], v[214:217], v[34:37]
	v_mfma_f32_16x16x32_bf16 v[26:29], v[246:249], v[214:217], v[26:29]
	v_mfma_f32_16x16x32_bf16 v[18:21], v[238:241], v[222:225], v[18:21]
	v_mfma_f32_16x16x32_bf16 v[10:13], v[246:249], v[222:225], v[10:13]
	v_mfma_f32_16x16x32_bf16 v[6:9], v[238:241], v[230:233], v[6:9]
	v_mfma_f32_16x16x32_bf16 v[2:5], v[246:249], v[230:233], v[2:5]
	s_add_i32 s38, s38, 2
	s_add_u32 s12, s12, 0x100
	s_addc_u32 s13, s13, 0
	s_add_u32 s36, s36, 0x100
	s_addc_u32 s37, s37, 0
	s_cmpk_gt_u32 s38, 0x7d
	s_barrier
	s_cbranch_scc0 .LBB0_47
; __device__ __forceinline__ unsigned cvt_pk_bf16(float lo, float hi) { unsigned r; asm("v_cvt_pk_bf16_f32 %0, %1, %2" : "=v"(r) : "v"(lo), "v"(hi)); return r; }
; #define PG8_WAIT_V(n) asm volatile("s_waitcnt vmcnt(" #n ")" ::: "memory")
; #define PG8_BAR __builtin_amdgcn_s_barrier()
;     __device__ __forceinline__ void operator()(const f32x4 (&acc)[2][2][4][2], const Unit& u, int wr, int wc, int fr, int fq) const {
;         const int row0 = u.pm * BM + wr * 64 + fr, col0 = u.pn * BM + wc * 32 + 8 * fq;
; #pragma unroll
;         for (int ai = 0; ai < 2; ++ai)
; #pragma unroll
;             for (int m = 0; m < 4; ++m) { bf16_t* rowp = O + (size_t)(row0 + ai * HALF + m * 16) * ldc + col0;
; #pragma unroll
;                 for (int bj = 0; bj < 2; ++bj) { f32x4 v0 = acc[ai][bj][m][0], v1 = acc[ai][bj][m][1];
;                     if (ACT == 1) {
; #pragma unroll
;                         for (int j = 0; j < 4; ++j) { const float a = fmaxf(v0[j], 0.f), b = fmaxf(v1[j], 0.f); v0[j] = a * a; v1[j] = b * b; } }
;                     u32x4 w; w.x = cvt_pk_bf16(v0[0], v0[1]); w.y = cvt_pk_bf16(v0[2], v0[3]); w.z = cvt_pk_bf16(v1[0], v1[1]); w.w = cvt_pk_bf16(v1[2], v1[3]);
;                     *(u32x4*)(rowp + bj * HALF) = w; } }
; template <class Epi, bool SEG>
; __device__ __forceinline__ void gemm_phase(LAS unsigned char* lds, const Gemm g, const StaticOrder& S, const Epi& E) {
;     ...
;         E(acc, cur, wr, wc, fr, fq);
;         if (!has_next) break;
; #pragma unroll
;         for (int a = 0; a < 2; ++a)
; #pragma unroll
;             for (int b = 0; b < 2; ++b)
; #pragma unroll
;                 for (int m = 0; m < 4; ++m)
; #pragma unroll
;                     for (int n = 0; n < 2; ++n) acc[a][b][m][n] = (f32x4){0.f, 0.f, 0.f, 0.f};
;         cur = nxt; cA = nA; cB = nB; ++ui;
;     }
;     PG8_WAIT_V(0);
;     if (wr == 0) PG8_BAR;
;     PG8_BAR;
	v_lshl_add_u32 v158, s8, 8, v154
	v_lshl_or_b32 v152, s31, 8, v156
	v_ashrrev_i32_e32 v159, 31, v158
	v_readlane_b32 s12, v253, 6
	v_ashrrev_i32_e32 v153, 31, v152
	v_lshlrev_b64 v[180:181], 12, v[158:159]
	v_readlane_b32 s13, v253, 7
	v_lshlrev_b64 v[182:183], 1, v[152:153]
	s_mov_b32 s1, 0x80000
	v_lshl_add_u64 v[180:181], s[12:13], 0, v[180:181]
	v_lshl_add_u64 v[152:153], v[180:181], 0, v[182:183]
	v_cvt_pk_bf16_f32 v62, v62, v63
	v_cvt_pk_bf16_f32 v63, v64, v65
	v_cvt_pk_bf16_f32 v64, v58, v59
	v_add_co_u32_e32 v58, vcc, s1, v152
	v_cvt_pk_bf16_f32 v114, v114, v115
	v_cvt_pk_bf16_f32 v115, v116, v117
	v_cvt_pk_bf16_f32 v116, v106, v107
	v_or_b32_e32 v106, 16, v158
	v_cvt_pk_bf16_f32 v98, v98, v99
	v_cvt_pk_bf16_f32 v99, v100, v101
	v_cvt_pk_bf16_f32 v100, v90, v91
	v_or_b32_e32 v90, 32, v158
	v_cvt_pk_bf16_f32 v86, v86, v87
	v_cvt_pk_bf16_f32 v87, v88, v89
	v_cvt_pk_bf16_f32 v88, v78, v79
	v_or_b32_e32 v78, 48, v158
	v_addc_co_u32_e32 v59, vcc, 0, v153, vcc
	s_mov_b32 s1, 0x90000
	v_ashrrev_i32_e32 v107, 31, v106
	v_ashrrev_i32_e32 v91, 31, v90
	v_ashrrev_i32_e32 v79, 31, v78
	v_cvt_pk_bf16_f32 v50, v50, v51
	v_cvt_pk_bf16_f32 v51, v52, v53
	v_cvt_pk_bf16_f32 v53, v44, v45
	v_cvt_pk_bf16_f32 v44, v46, v47
	v_add_co_u32_e32 v46, vcc, s1, v152
	v_lshlrev_b64 v[106:107], 12, v[106:107]
	v_lshlrev_b64 v[90:91], 12, v[90:91]
	v_lshlrev_b64 v[78:79], 12, v[78:79]
	v_addc_co_u32_e32 v47, vcc, 0, v153, vcc
	s_mov_b32 s1, 0xa0000
	v_lshl_add_u64 v[106:107], s[12:13], 0, v[106:107]
	v_lshl_add_u64 v[90:91], s[12:13], 0, v[90:91]
	v_lshl_add_u64 v[78:79], s[12:13], 0, v[78:79]
	s_mov_b64 s[12:13], 0x80000
	v_cvt_pk_bf16_f32 v34, v34, v35
	v_cvt_pk_bf16_f32 v35, v36, v37
	v_cvt_pk_bf16_f32 v37, v28, v29
	v_cvt_pk_bf16_f32 v28, v30, v31
	v_add_co_u32_e32 v30, vcc, s1, v152
	v_cvt_pk_bf16_f32 v70, v70, v71
	v_cvt_pk_bf16_f32 v71, v72, v73
	v_cvt_pk_bf16_f32 v72, v66, v67
	v_lshl_add_u64 v[66:67], v[152:153], 0, s[12:13]
	s_mov_b64 s[12:13], 0x90000
	v_addc_co_u32_e32 v31, vcc, 0, v153, vcc
	s_mov_b32 s1, 0xb0000
	v_cvt_pk_bf16_f32 v117, v108, v109
	global_store_dwordx4 v[152:153], v[114:117], off offset:256
	v_cvt_pk_bf16_f32 v52, v42, v43
	global_store_dwordx4 v[66:67], v[50:53], off offset:256
	v_cvt_pk_bf16_f32 v18, v18, v19
	v_cvt_pk_bf16_f32 v19, v20, v21
	v_cvt_pk_bf16_f32 v21, v12, v13
	s_nop 0
	v_lshl_add_u64 v[114:115], v[106:107], 0, v[182:183]
	v_cvt_pk_bf16_f32 v12, v14, v15
	v_lshl_add_u64 v[50:51], v[152:153], 0, s[12:13]
	s_mov_b64 s[12:13], 0xa0000
	v_add_co_u32_e32 v14, vcc, s1, v152
	v_cvt_pk_bf16_f32 v101, v92, v93
	global_store_dwordx4 v[114:115], v[98:101], off offset:256
	v_cvt_pk_bf16_f32 v36, v26, v27
	global_store_dwordx4 v[50:51], v[34:37], off offset:256
	v_addc_co_u32_e32 v15, vcc, 0, v153, vcc
	v_lshl_add_u64 v[98:99], v[90:91], 0, v[182:183]
	v_lshl_add_u64 v[34:35], v[152:153], 0, s[12:13]
	s_mov_b64 s[12:13], 0xb0000
	v_cvt_pk_bf16_f32 v89, v80, v81
	global_store_dwordx4 v[98:99], v[86:89], off offset:256
	v_cvt_pk_bf16_f32 v20, v10, v11
	global_store_dwordx4 v[34:35], v[18:21], off offset:256
	s_and_b64 vcc, exec, s[2:3]
	v_lshl_add_u64 v[86:87], v[78:79], 0, v[182:183]
	v_lshl_add_u64 v[18:19], v[152:153], 0, s[12:13]
	s_mov_b32 s31, s0
	s_mov_b32 s8, s4
	s_mov_b64 s[14:15], s[10:11]
	s_mov_b64 s[12:13], s[6:7]
	v_cvt_pk_bf16_f32 v126, v126, v127
	v_cvt_pk_bf16_f32 v127, v128, v129
	v_cvt_pk_bf16_f32 v128, v122, v123
	v_cvt_pk_bf16_f32 v129, v124, v125
	global_store_dwordx4 v[152:153], v[126:129], off
	v_cvt_pk_bf16_f32 v106, v118, v119
	v_cvt_pk_bf16_f32 v107, v120, v121
	v_cvt_pk_bf16_f32 v108, v110, v111
	v_cvt_pk_bf16_f32 v109, v112, v113
	global_store_dwordx4 v[114:115], v[106:109], off
	v_cvt_pk_bf16_f32 v90, v102, v103
	v_cvt_pk_bf16_f32 v91, v104, v105
	v_cvt_pk_bf16_f32 v92, v94, v95
	v_cvt_pk_bf16_f32 v93, v96, v97
	global_store_dwordx4 v[98:99], v[90:93], off
	v_cvt_pk_bf16_f32 v78, v82, v83
	v_cvt_pk_bf16_f32 v79, v84, v85
	v_cvt_pk_bf16_f32 v80, v74, v75
	v_cvt_pk_bf16_f32 v81, v76, v77
	global_store_dwordx4 v[86:87], v[78:81], off
	v_cvt_pk_bf16_f32 v73, v68, v69
	global_store_dwordx4 v[86:87], v[70:73], off offset:256
	v_cvt_pk_bf16_f32 v65, v60, v61
	global_store_dwordx4 v[58:59], v[62:65], off
	v_cvt_pk_bf16_f32 v42, v54, v55
	v_cvt_pk_bf16_f32 v43, v56, v57
	v_cvt_pk_bf16_f32 v45, v48, v49
	global_store_dwordx4 v[46:47], v[42:45], off
	v_cvt_pk_bf16_f32 v26, v38, v39
	v_cvt_pk_bf16_f32 v27, v40, v41
	v_cvt_pk_bf16_f32 v29, v32, v33
	global_store_dwordx4 v[30:31], v[26:29], off
	v_cvt_pk_bf16_f32 v10, v22, v23
	v_cvt_pk_bf16_f32 v11, v24, v25
	v_cvt_pk_bf16_f32 v13, v16, v17
	global_store_dwordx4 v[14:15], v[10:13], off
	v_cvt_pk_bf16_f32 v6, v6, v7
	v_cvt_pk_bf16_f32 v7, v8, v9
	v_cvt_pk_bf16_f32 v8, v2, v3
	v_cvt_pk_bf16_f32 v9, v4, v5
	global_store_dwordx4 v[18:19], v[6:9], off offset:256
	s_cbranch_vccz .LBB0_44
	s_waitcnt vmcnt(0)
	s_cmpk_gt_u32 s21, 0xff
	v_readlane_b32 s29, v254, 8
	s_cbranch_scc1 .LBB0_51
	s_barrier
.LBB0_51:
	v_readlane_b32 s28, v254, 6
	s_setprio 0
	s_barrier

; __device__ __forceinline__ int otid() { int t = threadIdx.x; asm volatile("" : "+v"(t)); return t; }
; #define PG8_STAGE(bufoff, gbase, voff) do { _Pragma("unroll") for (int _i = 0; _i < 2; ++_i) \
;         __builtin_amdgcn_global_load_lds((const unsigned*)((const char*)(gbase) + (voff)[_i]), (LAS unsigned*)(lds + (bufoff) + ldsw + _i * 8192), 16, 0, 0); } while (0)
; #define PG8_BAR __builtin_amdgcn_s_barrier()
; template <class Epi, bool SEG>
; __device__ __forceinline__ void gemm_phase(LAS unsigned char* lds, const Gemm g, const StaticOrder& S, const Epi& E) {
;     const int tid = otid(), wid = __builtin_amdgcn_readfirstlane(tid >> 6), lane = tid & 63, wr = wid >> 2, wc = wid & 3, fr = lane & 15, fq = lane >> 4;
;     const int K = g.K, nt = K / BK, lda = g.lda;
;     unsigned voffA[2], voffB[2];
; #pragma unroll
;     for (int i = 0; i < 2; ++i) { int R, C; stage_rc(tid * 16 + i * 8192, R, C); const int Rb = Epi::PERM ? ((R & ~31) + perm32(R & 31)) : R;
;         voffA[i] = (unsigned)(R * lda + C) * 2u; voffB[i] = (unsigned)(Rb * K + C) * 2u; }
;     const size_t kstep = (size_t)(BK * 2);
;     const size_t hstepA = (size_t)HALF * lda * 2, hstepB = (size_t)HALF * K * 2;
;     const size_t tstepA = 2 * hstepA, tstepB = 2 * hstepB;
;     const unsigned ldsw = (unsigned)wid * 1024u;
;     const int aoff = lds_byte(wr * 64 + fr, fq * 8), boff = lds_byte(wc * 32 + fr, fq * 8);
;     ...
;     Unit cur, nxt; int ui = 0;
;     if (!S.next(0, cur)) return;
;     f32x4 acc[2][2][4][2];
; #pragma unroll
;     for (int a = 0; a < 2; ++a)
; #pragma unroll
;         for (int b = 0; b < 2; ++b)
; #pragma unroll
;             for (int m = 0; m < 4; ++m)
; #pragma unroll
;                 for (int n = 0; n < 2; ++n) acc[a][b][m][n] = (f32x4){0.f, 0.f, 0.f, 0.f};
;     bf16x8 At[4][2], B0[2][2], B1[2][2];
;     const char* cA = (const char*)g.A + (size_t)cur.pm * tstepA; const char* cB = (const char*)g.Bt + (size_t)cur.pn * tstepB;
;     PG8_STAGE(PG8_SB(0, 0), cB, voffB); PG8_STAGE(PG8_SA(0, 0), cA, voffA); PG8_STAGE(PG8_SB(0, 1), cB + hstepB, voffB); PG8_STAGE(PG8_SA(0, 1), cA + hstepA, voffA);
;     if (wr == 1) PG8_BAR;
.LBB0_59:
	v_ashrrev_i32_e32 v0, 31, v8
	v_lshrrev_b32_e32 v0, 26, v0
	v_add_u32_e32 v0, v8, v0
	v_ashrrev_i32_e32 v2, 6, v0
	v_bfe_i32 v0, v8, 27, 1
	v_lshlrev_b32_e32 v5, 4, v8
	v_lshrrev_b32_e32 v0, 22, v0
	v_add_u32_e32 v0, v5, v0
	v_and_b32_e32 v0, 0xfffffc00, v0
	v_sub_u32_e32 v0, v5, v0
	v_lshrrev_b32_e32 v3, 4, v0
	v_bitop3_b32 v4, v3, v0, 32 bitop3:0x6c
	v_ashrrev_i32_e32 v0, 31, v0
	v_lshrrev_b32_e32 v0, 26, v0
	v_lshlrev_b32_e32 v3, 3, v2
	v_add_u32_e32 v0, v4, v0
	v_and_b32_e32 v6, -16, v3
	v_ashrrev_i32_e32 v3, 6, v0
	v_mul_i32_i24_e32 v7, 64, v3
	v_add_u32_e32 v0, v3, v6
	v_sub_u32_e32 v4, v4, v7
	v_lshlrev_b32_e32 v6, 5, v2
	v_ashrrev_i16_sdwa v4, v172, sext(v4) dst_sel:DWORD dst_unused:UNUSED_PAD src0_sel:DWORD src1_sel:BYTE_0
	v_lshlrev_b32_e32 v7, 1, v0
	v_lshrrev_b32_e32 v9, 2, v0
	v_and_b32_e32 v10, 3, v3
	s_mov_b32 s2, 0xfffe0
	v_and_b32_e32 v6, 32, v6
	v_bfe_i32 v4, v4, 0, 16
	v_and_b32_e32 v7, 24, v7
	v_and_b32_e32 v9, 4, v9
	v_and_or_b32 v10, v0, s2, v10
	v_or3_b32 v7, v10, v9, v7
	v_add_lshl_u32 v6, v6, v4, 1
	v_lshl_add_u32 v142, v0, 12, v6
	v_lshl_add_u32 v0, v7, 12, v6
	v_add_u32_e32 v6, 0x2000, v5
	v_ashrrev_i32_e32 v5, 31, v6
	s_add_i32 s0, s3, s0
	v_lshrrev_b32_e32 v5, 22, v5
	s_ashr_i32 s3, s0, 31
	v_add_u32_e32 v5, v6, v5
	s_lshr_b32 s3, s3, 24
	v_ashrrev_i32_e32 v5, 10, v5
	s_add_i32 s3, s0, s3
	v_mul_i32_i24_e32 v7, 0x400, v5
	s_ashr_i32 s4, s3, 8
	s_and_b32 s3, s3, 0xff00
	v_sub_u32_e32 v6, v6, v7
	s_sub_i32 s3, s0, s3
	v_lshrrev_b32_e32 v7, 4, v6
	s_sext_i32_i16 s0, s3
	v_bitop3_b32 v7, v7, v6, 32 bitop3:0x6c
	v_lshlrev_b32_e32 v6, 3, v5
	s_bfe_u32 s0, s0, 0x3001c
	v_and_b32_e32 v9, -16, v6
	v_ashrrev_i32_e32 v6, 31, v7
	s_add_i32 s5, s3, s0
	v_lshrrev_b32_e32 v6, 26, v6
	s_sext_i32_i16 s0, s5
	s_and_b32 s5, s5, 0xfff8
	v_add_u32_e32 v10, v7, v6
	s_sub_i32 s3, s3, s5
	v_ashrrev_i32_e32 v6, 6, v10
	s_lshl_b32 s4, s4, 3
	s_sext_i32_i16 s3, s3
	s_ashr_i32 s1, s21, 8
	v_add_u32_e32 v9, v6, v9
	v_and_b32_e32 v13, 3, v6
	s_lshr_b32 s0, s0, 3
	s_add_i32 s10, s4, s3
	v_and_or_b32 v13, v9, s2, v13
	s_ashr_i32 s2, s21, 6
	s_ashr_i32 s11, s10, 31
	s_bfe_i64 s[6:7], s[0:1], 0x100000
	v_and_b32_e32 v10, 0xc0, v10
	s_lshl_b32 s24, s2, 10
	s_lshl_b64 s[4:5], s[10:11], 20
	s_lshl_b64 s[6:7], s[6:7], 20
	v_readlane_b32 s8, v253, 10
	v_sub_u32_e32 v7, v7, v10
	v_readlane_b32 s9, v253, 11
	s_add_u32 s14, s8, s6
	v_lshlrev_b32_e32 v11, 5, v5
	v_ashrrev_i16_sdwa v7, v172, sext(v7) dst_sel:DWORD dst_unused:UNUSED_PAD src0_sel:DWORD src1_sel:BYTE_0
	v_lshlrev_b32_e32 v10, 1, v9
	v_lshrrev_b32_e32 v12, 2, v9
	s_addc_u32 s15, s9, s7
	s_add_i32 s11, s24, 0
	v_and_b32_e32 v11, 32, v11
	v_bfe_i32 v7, v7, 0, 16
	v_and_b32_e32 v10, 24, v10
	v_and_b32_e32 v12, 4, v12
	s_add_i32 m0, s11, 0x10000
	v_or3_b32 v10, v13, v12, v10
	v_add_lshl_u32 v11, v11, v7, 1
	global_load_lds_dwordx4 v0, s[14:15]
	s_add_i32 m0, s11, 0x12000
	v_readlane_b32 s6, v253, 4
	v_lshl_add_u32 v146, v10, 12, v11
	v_readlane_b32 s7, v253, 5
	s_add_u32 s12, s6, s4
	global_load_lds_dwordx4 v146, s[14:15]
	s_addc_u32 s13, s7, s5
	s_mov_b32 m0, s11
	s_add_i32 s25, s11, 0x2000
	v_lshl_add_u32 v144, v9, 12, v11
	global_load_lds_dwordx4 v142, s[12:13]
	s_mov_b32 m0, s25
	s_add_u32 s4, s14, 0x80000
	global_load_lds_dwordx4 v144, s[12:13]
	s_addc_u32 s5, s15, 0
	s_add_i32 m0, s11, 0x14000
	s_nop 0
	global_load_lds_dwordx4 v0, s[4:5]
	s_add_i32 m0, s11, 0x16000
	s_nop 0
	global_load_lds_dwordx4 v146, s[4:5]
	s_add_u32 s4, s12, 0x80000
	s_addc_u32 s5, s13, 0
	s_add_i32 s26, s11, 0x4000
	s_mov_b32 m0, s26
	s_add_i32 s27, s11, 0x6000
	global_load_lds_dwordx4 v142, s[4:5]
	s_mov_b32 m0, s27
	s_cmp_lg_u32 s1, 1
	global_load_lds_dwordx4 v144, s[4:5]
	s_cbranch_scc1 .LBB0_61
	s_setprio 1
	s_barrier

; #define PG8_STAGE(bufoff, gbase, voff) do { _Pragma("unroll") for (int _i = 0; _i < 2; ++_i) \
;         __builtin_amdgcn_global_load_lds((const unsigned*)((const char*)(gbase) + (voff)[_i]), (LAS unsigned*)(lds + (bufoff) + ldsw + _i * 8192), 16, 0, 0); } while (0)
; #define PG8_LDA(dst, b, h) do { _Pragma("unroll") for (int m = 0; m < 4; ++m) _Pragma("unroll") for (int k = 0; k < 2; ++k) dst[m][k] = *(const LAS bf16x8*)(lds + PG8_SA(b, h) + aoff + m * 2048 + k * 1024); } while (0)
; #define PG8_LDB(dst, b, h) do { _Pragma("unroll") for (int n = 0; n < 2; ++n) _Pragma("unroll") for (int k = 0; k < 2; ++k) dst[n][k] = *(const LAS bf16x8*)(lds + PG8_SB(b, h) + boff + n * 2048 + k * 1024); } while (0)
; #define PG8_MMA(ai, bj, At, Bt) do { __builtin_amdgcn_s_setprio(1); _Pragma("unroll") for (int m = 0; m < 4; ++m) _Pragma("unroll") for (int n = 0; n < 2; ++n) _Pragma("unroll") for (int k = 0; k < 2; ++k) \
;         acc[ai][bj][m][n] = __builtin_amdgcn_mfma_f32_16x16x32_bf16(Bt[n][k], At[m][k], acc[ai][bj][m][n], 0, 0, 0); __builtin_amdgcn_s_setprio(0); } while (0)
; #define PG8_WAIT_L(n) asm volatile("s_waitcnt lgkmcnt(" #n ")" ::: "memory")
; #define PG8_BAR __builtin_amdgcn_s_barrier()
; #define PG8_SCHED __builtin_amdgcn_sched_barrier(0)
; template <class Epi, bool SEG>
; __device__ __forceinline__ void gemm_phase(LAS unsigned char* lds, const Gemm g, const StaticOrder& S, const Epi& E) {
;     ...
;         for (int t = 0; t < nt; t += 2) {
;             const bool last = (t == nt - 2);
;             const char* a1 = cA + akoff<SEG>(t) + kstep;
;             const char* a2 = last ? nA : cA + akoff<SEG>(t + 2); const char* b2 = last ? nB : cB + (size_t)(t + 2) * kstep;
;             const char* a3 = a2 + kstep; const char* b3 = b2 + kstep;
;             PG8_LDB(B0, 0, 0); PG8_SCHED; PG8_LDA(At, 0, 0); PG8_STAGE(PG8_SA(1, 1), a1 + hstepA, voffA);
;             PG8_WAIT_L(8); PG8_BAR; PG8_WAIT_L(0); PG8_MMA(0, 0, At, B0); PG8_BAR; PG8_SCHED;
;             PG8_LDB(B1, 0, 1); PG8_STAGE(PG8_SB(0, 0), b2, voffB);
;             PG8_BAR; PG8_WAIT_L(0); PG8_MMA(0, 1, At, B1); PG8_BAR;
;             PG8_LDA(At, 0, 1); PG8_STAGE(PG8_SA(0, 0), a2, voffA);
;             PG8_BAR; PG8_WAIT_L(0); PG8_MMA(1, 0, At, B0); PG8_BAR; PG8_SCHED;
.LBB0_69:
	s_add_u32 s14, s12, 0xfff80080
	s_addc_u32 s15, s13, -1
	s_add_i32 s39, 0, 0x10000
	v_add_u32_e32 v152, s39, v155
	ds_read_b128 v[180:183], v152
	ds_read_b128 v[184:187], v152 offset:1024
	ds_read_b128 v[188:191], v152 offset:2048
	ds_read_b128 v[198:201], v152 offset:3072
	s_cmp_eq_u32 s38, 28
	s_cselect_b32 s17, s5, s15
	s_cselect_b32 s16, s34, s14
	s_cselect_b32 s15, s1, s37
	s_cselect_b32 s14, s35, s36
	v_lshl_add_u64 v[152:153], s[12:13], 0, v[148:149]
	s_add_i32 m0, s11, 0xc000
	ds_read_b128 v[202:205], v157
	ds_read_b128 v[206:209], v157 offset:1024
	ds_read_b128 v[210:213], v157 offset:2048
	ds_read_b128 v[214:217], v157 offset:3072
	ds_read_b128 v[218:221], v157 offset:4096
	ds_read_b128 v[222:225], v157 offset:5120
	ds_read_b128 v[226:229], v157 offset:6144
	ds_read_b128 v[230:233], v157 offset:7168
	global_load_lds_dwordx4 v[152:153], off
	v_lshl_add_u64 v[152:153], s[12:13], 0, v[150:151]
	s_add_i32 m0, s11, 0xe000
	s_nop 0
	global_load_lds_dwordx4 v[152:153], off
	s_waitcnt lgkmcnt(8)
	s_barrier
	s_waitcnt lgkmcnt(0)
	s_waitcnt lgkmcnt(0)
	v_mfma_f32_16x16x32_bf16 v[126:129], v[180:183], v[202:205], v[126:129]
	v_mfma_f32_16x16x32_bf16 v[122:125], v[188:191], v[202:205], v[122:125]
	v_mfma_f32_16x16x32_bf16 v[110:113], v[180:183], v[210:213], v[110:113]
	v_mfma_f32_16x16x32_bf16 v[106:109], v[188:191], v[210:213], v[106:109]
	v_mfma_f32_16x16x32_bf16 v[94:97], v[180:183], v[218:221], v[94:97]
	v_mfma_f32_16x16x32_bf16 v[90:93], v[188:191], v[218:221], v[90:93]
	v_mfma_f32_16x16x32_bf16 v[78:81], v[180:183], v[226:229], v[78:81]
	v_mfma_f32_16x16x32_bf16 v[74:77], v[188:191], v[226:229], v[74:77]
	v_mfma_f32_16x16x32_bf16 v[126:129], v[184:187], v[206:209], v[126:129]
	v_mfma_f32_16x16x32_bf16 v[122:125], v[198:201], v[206:209], v[122:125]
	v_mfma_f32_16x16x32_bf16 v[110:113], v[184:187], v[214:217], v[110:113]
	v_mfma_f32_16x16x32_bf16 v[106:109], v[198:201], v[214:217], v[106:109]
	v_mfma_f32_16x16x32_bf16 v[94:97], v[184:187], v[222:225], v[94:97]
	v_mfma_f32_16x16x32_bf16 v[90:93], v[198:201], v[222:225], v[90:93]
	v_mfma_f32_16x16x32_bf16 v[78:81], v[184:187], v[230:233], v[78:81]
	v_mfma_f32_16x16x32_bf16 v[74:77], v[198:201], v[230:233], v[74:77]
	s_barrier
	s_add_i32 s42, 0, 0x14000
	v_add_u32_e32 v152, s42, v155
	s_add_i32 s39, s39, s24
	ds_read_b128 v[234:237], v152
	ds_read_b128 v[238:241], v152 offset:1024
	ds_read_b128 v[242:245], v152 offset:2048
	ds_read_b128 v[246:249], v152 offset:3072
	v_lshl_add_u64 v[152:153], s[14:15], 0, v[0:1]
	s_mov_b32 m0, s39
	v_lshl_add_u64 v[158:159], s[14:15], 0, v[146:147]
	global_load_lds_dwordx4 v[152:153], off
	s_add_i32 m0, s39, 0x2000
	s_nop 0
	global_load_lds_dwordx4 v[158:159], off
	s_barrier
	s_waitcnt lgkmcnt(0)
	s_waitcnt lgkmcnt(0)
	v_mfma_f32_16x16x32_bf16 v[118:121], v[234:237], v[202:205], v[118:121]
	v_mfma_f32_16x16x32_bf16 v[114:117], v[242:245], v[202:205], v[114:117]
	v_mfma_f32_16x16x32_bf16 v[102:105], v[234:237], v[210:213], v[102:105]
	v_mfma_f32_16x16x32_bf16 v[98:101], v[242:245], v[210:213], v[98:101]
	v_mfma_f32_16x16x32_bf16 v[86:89], v[234:237], v[218:221], v[86:89]
	v_mfma_f32_16x16x32_bf16 v[82:85], v[242:245], v[218:221], v[82:85]
	v_mfma_f32_16x16x32_bf16 v[70:73], v[234:237], v[226:229], v[70:73]
	v_mfma_f32_16x16x32_bf16 v[66:69], v[242:245], v[226:229], v[66:69]
	v_mfma_f32_16x16x32_bf16 v[118:121], v[238:241], v[206:209], v[118:121]
	v_mfma_f32_16x16x32_bf16 v[114:117], v[246:249], v[206:209], v[114:117]
	v_mfma_f32_16x16x32_bf16 v[102:105], v[238:241], v[214:217], v[102:105]
	v_mfma_f32_16x16x32_bf16 v[98:101], v[246:249], v[214:217], v[98:101]
	v_mfma_f32_16x16x32_bf16 v[86:89], v[238:241], v[222:225], v[86:89]
	v_mfma_f32_16x16x32_bf16 v[82:85], v[246:249], v[222:225], v[82:85]
	v_mfma_f32_16x16x32_bf16 v[70:73], v[238:241], v[230:233], v[70:73]
	v_mfma_f32_16x16x32_bf16 v[66:69], v[246:249], v[230:233], v[66:69]
	s_mov_b32 m0, s11
	v_lshl_add_u64 v[192:193], s[16:17], 0, v[142:143]
	s_barrier
	ds_read_b128 v[202:205], v157 offset:16384
	ds_read_b128 v[206:209], v157 offset:17408
	ds_read_b128 v[210:213], v157 offset:18432
	ds_read_b128 v[214:217], v157 offset:19456
	ds_read_b128 v[218:221], v157 offset:20480
	ds_read_b128 v[222:225], v157 offset:21504
	ds_read_b128 v[226:229], v157 offset:22528
	ds_read_b128 v[230:233], v157 offset:23552
	global_load_lds_dwordx4 v[192:193], off
	v_lshl_add_u64 v[250:251], s[16:17], 0, v[144:145]
	s_mov_b32 m0, s25
	s_nop 0
	global_load_lds_dwordx4 v[250:251], off
	s_barrier
	s_waitcnt lgkmcnt(0)
	s_waitcnt lgkmcnt(0)
	v_mfma_f32_16x16x32_bf16 v[62:65], v[180:183], v[202:205], v[62:65]
	v_mfma_f32_16x16x32_bf16 v[58:61], v[188:191], v[202:205], v[58:61]
	v_mfma_f32_16x16x32_bf16 v[46:49], v[180:183], v[210:213], v[46:49]
	v_mfma_f32_16x16x32_bf16 v[42:45], v[188:191], v[210:213], v[42:45]
	v_mfma_f32_16x16x32_bf16 v[30:33], v[180:183], v[218:221], v[30:33]
	v_mfma_f32_16x16x32_bf16 v[26:29], v[188:191], v[218:221], v[26:29]
	v_mfma_f32_16x16x32_bf16 v[14:17], v[180:183], v[226:229], v[14:17]
	v_mfma_f32_16x16x32_bf16 v[10:13], v[188:191], v[226:229], v[10:13]
	v_mfma_f32_16x16x32_bf16 v[62:65], v[184:187], v[206:209], v[62:65]
	v_mfma_f32_16x16x32_bf16 v[58:61], v[198:201], v[206:209], v[58:61]
	v_mfma_f32_16x16x32_bf16 v[46:49], v[184:187], v[214:217], v[46:49]
	v_mfma_f32_16x16x32_bf16 v[42:45], v[198:201], v[214:217], v[42:45]
	v_mfma_f32_16x16x32_bf16 v[30:33], v[184:187], v[222:225], v[30:33]
	v_mfma_f32_16x16x32_bf16 v[26:29], v[198:201], v[222:225], v[26:29]
	v_mfma_f32_16x16x32_bf16 v[14:17], v[184:187], v[230:233], v[14:17]
	v_mfma_f32_16x16x32_bf16 v[10:13], v[198:201], v[230:233], v[10:13]
	s_barrier
; #define PG8_STAGE(bufoff, gbase, voff) do { _Pragma("unroll") for (int _i = 0; _i < 2; ++_i) \
;         __builtin_amdgcn_global_load_lds((const unsigned*)((const char*)(gbase) + (voff)[_i]), (LAS unsigned*)(lds + (bufoff) + ldsw + _i * 8192), 16, 0, 0); } while (0)
; #define PG8_LDA(dst, b, h) do { _Pragma("unroll") for (int m = 0; m < 4; ++m) _Pragma("unroll") for (int k = 0; k < 2; ++k) dst[m][k] = *(const LAS bf16x8*)(lds + PG8_SA(b, h) + aoff + m * 2048 + k * 1024); } while (0)
; #define PG8_LDB(dst, b, h) do { _Pragma("unroll") for (int n = 0; n < 2; ++n) _Pragma("unroll") for (int k = 0; k < 2; ++k) dst[n][k] = *(const LAS bf16x8*)(lds + PG8_SB(b, h) + boff + n * 2048 + k * 1024); } while (0)
; #define PG8_MMA(ai, bj, At, Bt) do { __builtin_amdgcn_s_setprio(1); _Pragma("unroll") for (int m = 0; m < 4; ++m) _Pragma("unroll") for (int n = 0; n < 2; ++n) _Pragma("unroll") for (int k = 0; k < 2; ++k) \
;         acc[ai][bj][m][n] = __builtin_amdgcn_mfma_f32_16x16x32_bf16(Bt[n][k], At[m][k], acc[ai][bj][m][n], 0, 0, 0); __builtin_amdgcn_s_setprio(0); } while (0)
; #define PG8_WAIT_V(n) asm volatile("s_waitcnt vmcnt(" #n ")" ::: "memory")
; #define PG8_WAIT_L(n) asm volatile("s_waitcnt lgkmcnt(" #n ")" ::: "memory")
; #define PG8_BAR __builtin_amdgcn_s_barrier()
; #define PG8_SCHED __builtin_amdgcn_sched_barrier(0)
; template <class Epi, bool SEG>
; __device__ __forceinline__ void gemm_phase(LAS unsigned char* lds, const Gemm g, const StaticOrder& S, const Epi& E) {
;     ...
;             PG8_STAGE(PG8_SB(0, 1), b2 + hstepB, voffB);
;             PG8_WAIT_V(6); PG8_BAR; PG8_MMA(1, 1, At, B1); PG8_BAR;
;             PG8_LDB(B0, 1, 0); PG8_SCHED; PG8_LDA(At, 1, 0); PG8_STAGE(PG8_SA(0, 1), a2 + hstepA, voffA);
;             PG8_WAIT_L(8); PG8_BAR; PG8_WAIT_L(0); PG8_MMA(0, 0, At, B0); PG8_BAR; PG8_SCHED;
;             PG8_LDB(B1, 1, 1); PG8_STAGE(PG8_SB(1, 0), b3, voffB);
;             PG8_BAR; PG8_WAIT_L(0); PG8_MMA(0, 1, At, B1); PG8_BAR;
;             PG8_LDA(At, 1, 1); PG8_STAGE(PG8_SA(1, 0), a3, voffA);
;             PG8_BAR; PG8_WAIT_L(0); PG8_MMA(1, 0, At, B0); PG8_BAR; PG8_SCHED;
	s_add_u32 s40, s14, 0x80000
	s_addc_u32 s41, s15, 0
	s_add_i32 s39, s42, s24
	v_lshl_add_u64 v[180:181], s[40:41], 0, v[0:1]
	s_mov_b32 m0, s39
	s_nop 0
	global_load_lds_dwordx4 v[180:181], off
	v_lshl_add_u64 v[180:181], s[40:41], 0, v[146:147]
	s_add_i32 m0, s39, 0x2000
	s_nop 0
	global_load_lds_dwordx4 v[180:181], off
	s_waitcnt vmcnt(6)
	s_barrier
	v_mfma_f32_16x16x32_bf16 v[54:57], v[234:237], v[202:205], v[54:57]
	v_mfma_f32_16x16x32_bf16 v[50:53], v[242:245], v[202:205], v[50:53]
	v_mfma_f32_16x16x32_bf16 v[38:41], v[234:237], v[210:213], v[38:41]
	v_mfma_f32_16x16x32_bf16 v[34:37], v[242:245], v[210:213], v[34:37]
	v_mfma_f32_16x16x32_bf16 v[22:25], v[234:237], v[218:221], v[22:25]
	v_mfma_f32_16x16x32_bf16 v[18:21], v[242:245], v[218:221], v[18:21]
	v_mfma_f32_16x16x32_bf16 v[6:9], v[234:237], v[226:229], v[6:9]
	v_mfma_f32_16x16x32_bf16 v[2:5], v[242:245], v[226:229], v[2:5]
	v_mfma_f32_16x16x32_bf16 v[54:57], v[238:241], v[206:209], v[54:57]
	v_mfma_f32_16x16x32_bf16 v[50:53], v[246:249], v[206:209], v[50:53]
	v_mfma_f32_16x16x32_bf16 v[38:41], v[238:241], v[214:217], v[38:41]
	v_mfma_f32_16x16x32_bf16 v[34:37], v[246:249], v[214:217], v[34:37]
	v_mfma_f32_16x16x32_bf16 v[22:25], v[238:241], v[222:225], v[22:25]
	v_mfma_f32_16x16x32_bf16 v[18:21], v[246:249], v[222:225], v[18:21]
	v_mfma_f32_16x16x32_bf16 v[6:9], v[238:241], v[230:233], v[6:9]
	v_mfma_f32_16x16x32_bf16 v[2:5], v[246:249], v[230:233], v[2:5]
	s_add_i32 s39, 0, 0x18000
	v_add_u32_e32 v179, s39, v155
	s_barrier
	ds_read_b128 v[180:183], v179
	ds_read_b128 v[184:187], v179 offset:1024
	ds_read_b128 v[188:191], v179 offset:2048
	ds_read_b128 v[198:201], v179 offset:3072
	s_add_u32 s16, s16, 0x80000
	s_addc_u32 s17, s17, 0
	s_mov_b32 m0, s26
	v_lshl_add_u64 v[234:235], s[16:17], 0, v[142:143]
	ds_read_b128 v[202:205], v157 offset:32768
	ds_read_b128 v[206:209], v157 offset:33792
	ds_read_b128 v[210:213], v157 offset:34816
	ds_read_b128 v[214:217], v157 offset:35840
	ds_read_b128 v[218:221], v157 offset:36864
	ds_read_b128 v[222:225], v157 offset:37888
	ds_read_b128 v[226:229], v157 offset:38912
	ds_read_b128 v[230:233], v157 offset:39936
	global_load_lds_dwordx4 v[234:235], off
	v_lshl_add_u64 v[234:235], s[16:17], 0, v[144:145]
	s_mov_b32 m0, s27
	s_nop 0
	global_load_lds_dwordx4 v[234:235], off
	s_waitcnt lgkmcnt(8)
	s_barrier
	s_waitcnt lgkmcnt(0)
	s_waitcnt lgkmcnt(0)
	v_mfma_f32_16x16x32_bf16 v[126:129], v[180:183], v[202:205], v[126:129]
	v_mfma_f32_16x16x32_bf16 v[122:125], v[188:191], v[202:205], v[122:125]
	v_mfma_f32_16x16x32_bf16 v[110:113], v[180:183], v[210:213], v[110:113]
	v_mfma_f32_16x16x32_bf16 v[106:109], v[188:191], v[210:213], v[106:109]
	v_mfma_f32_16x16x32_bf16 v[94:97], v[180:183], v[218:221], v[94:97]
	v_mfma_f32_16x16x32_bf16 v[90:93], v[188:191], v[218:221], v[90:93]
	v_mfma_f32_16x16x32_bf16 v[78:81], v[180:183], v[226:229], v[78:81]
	v_mfma_f32_16x16x32_bf16 v[74:77], v[188:191], v[226:229], v[74:77]
	v_mfma_f32_16x16x32_bf16 v[126:129], v[184:187], v[206:209], v[126:129]
	v_mfma_f32_16x16x32_bf16 v[122:125], v[198:201], v[206:209], v[122:125]
	v_mfma_f32_16x16x32_bf16 v[110:113], v[184:187], v[214:217], v[110:113]
	v_mfma_f32_16x16x32_bf16 v[106:109], v[198:201], v[214:217], v[106:109]
	v_mfma_f32_16x16x32_bf16 v[94:97], v[184:187], v[222:225], v[94:97]
	v_mfma_f32_16x16x32_bf16 v[90:93], v[198:201], v[222:225], v[90:93]
	v_mfma_f32_16x16x32_bf16 v[78:81], v[184:187], v[230:233], v[78:81]
	v_mfma_f32_16x16x32_bf16 v[74:77], v[198:201], v[230:233], v[74:77]
	s_barrier
	s_add_i32 s16, 0, 0x1c000
	s_add_i32 s17, s39, s24
	v_add_u32_e32 v179, s16, v155
	v_lshl_add_u64 v[152:153], v[152:153], 0, s[96:97]
	s_mov_b32 m0, s17
	ds_read_b128 v[234:237], v179
	ds_read_b128 v[238:241], v179 offset:1024
	ds_read_b128 v[242:245], v179 offset:2048
	ds_read_b128 v[246:249], v179 offset:3072
	global_load_lds_dwordx4 v[152:153], off
	v_lshl_add_u64 v[152:153], v[158:159], 0, s[96:97]
	s_add_i32 m0, s17, 0x2000
	s_nop 0
	global_load_lds_dwordx4 v[152:153], off
	s_barrier
	s_waitcnt lgkmcnt(0)
	s_waitcnt lgkmcnt(0)
	v_mfma_f32_16x16x32_bf16 v[118:121], v[234:237], v[202:205], v[118:121]
	v_mfma_f32_16x16x32_bf16 v[114:117], v[242:245], v[202:205], v[114:117]
	v_mfma_f32_16x16x32_bf16 v[102:105], v[234:237], v[210:213], v[102:105]
	v_mfma_f32_16x16x32_bf16 v[98:101], v[242:245], v[210:213], v[98:101]
	v_mfma_f32_16x16x32_bf16 v[86:89], v[234:237], v[218:221], v[86:89]
	v_mfma_f32_16x16x32_bf16 v[82:85], v[242:245], v[218:221], v[82:85]
	v_mfma_f32_16x16x32_bf16 v[70:73], v[234:237], v[226:229], v[70:73]
	v_mfma_f32_16x16x32_bf16 v[66:69], v[242:245], v[226:229], v[66:69]
	v_mfma_f32_16x16x32_bf16 v[118:121], v[238:241], v[206:209], v[118:121]
	v_mfma_f32_16x16x32_bf16 v[114:117], v[246:249], v[206:209], v[114:117]
	v_mfma_f32_16x16x32_bf16 v[102:105], v[238:241], v[214:217], v[102:105]
	v_mfma_f32_16x16x32_bf16 v[98:101], v[246:249], v[214:217], v[98:101]
	v_mfma_f32_16x16x32_bf16 v[86:89], v[238:241], v[222:225], v[86:89]
	v_mfma_f32_16x16x32_bf16 v[82:85], v[246:249], v[222:225], v[82:85]
	v_mfma_f32_16x16x32_bf16 v[70:73], v[238:241], v[230:233], v[70:73]
	v_mfma_f32_16x16x32_bf16 v[66:69], v[246:249], v[230:233], v[66:69]
	s_mov_b32 m0, s28
	v_lshl_add_u64 v[152:153], v[192:193], 0, s[96:97]
	s_barrier
	ds_read_b128 v[202:205], v157 offset:49152
	ds_read_b128 v[206:209], v157 offset:50176
	ds_read_b128 v[210:213], v157 offset:51200
	ds_read_b128 v[214:217], v157 offset:52224
	ds_read_b128 v[218:221], v157 offset:53248
	ds_read_b128 v[222:225], v157 offset:54272
	ds_read_b128 v[226:229], v157 offset:55296
	ds_read_b128 v[230:233], v157 offset:56320
	global_load_lds_dwordx4 v[152:153], off
	v_lshl_add_u64 v[152:153], v[250:251], 0, s[96:97]
	s_mov_b32 m0, s29
	s_nop 0
	global_load_lds_dwordx4 v[152:153], off
	s_barrier
; __device__ __forceinline__ unsigned cvt_pk_bf16(float lo, float hi) { unsigned r; asm("v_cvt_pk_bf16_f32 %0, %1, %2" : "=v"(r) : "v"(lo), "v"(hi)); return r; }
; #define PG8_STAGE(bufoff, gbase, voff) do { _Pragma("unroll") for (int _i = 0; _i < 2; ++_i) \
;         __builtin_amdgcn_global_load_lds((const unsigned*)((const char*)(gbase) + (voff)[_i]), (LAS unsigned*)(lds + (bufoff) + ldsw + _i * 8192), 16, 0, 0); } while (0)
; #define PG8_LDA(dst, b, h) do { _Pragma("unroll") for (int m = 0; m < 4; ++m) _Pragma("unroll") for (int k = 0; k < 2; ++k) dst[m][k] = *(const LAS bf16x8*)(lds + PG8_SA(b, h) + aoff + m * 2048 + k * 1024); } while (0)
; #define PG8_WAIT_V(n) asm volatile("s_waitcnt vmcnt(" #n ")" ::: "memory")
; #define PG8_WAIT_L(n) asm volatile("s_waitcnt lgkmcnt(" #n ")" ::: "memory")
; #define PG8_BAR __builtin_amdgcn_s_barrier()
;     __device__ __forceinline__ void operator()(const f32x4 (&acc)[2][2][4][2], const Unit& u, int wr, int wc, int fr, int fq) const {
;         const int row0 = u.pm * BM + wr * 64 + fr, col0 = u.pn * BM + wc * 32 + 8 * fq;
; #pragma unroll
;         for (int ai = 0; ai < 2; ++ai)
; #pragma unroll
;             for (int m = 0; m < 4; ++m) { bf16_t* rowp = O + (size_t)(row0 + ai * HALF + m * 16) * ldc + col0;
; #pragma unroll
;                 for (int bj = 0; bj < 2; ++bj) { f32x4 v0 = acc[ai][bj][m][0], v1 = acc[ai][bj][m][1];
;                     if (ACT == 1) {
; #pragma unroll
;                         for (int j = 0; j < 4; ++j) { const float a = fmaxf(v0[j], 0.f), b = fmaxf(v1[j], 0.f); v0[j] = a * a; v1[j] = b * b; } }
;                     u32x4 w; w.x = cvt_pk_bf16(v0[0], v0[1]); w.y = cvt_pk_bf16(v0[2], v0[3]); w.z = cvt_pk_bf16(v1[0], v1[1]); w.w = cvt_pk_bf16(v1[2], v1[3]);
;                     *(u32x4*)(rowp + bj * HALF) = w; } }
; template <class Epi, bool SEG>
; __device__ __forceinline__ void gemm_phase(LAS unsigned char* lds, const Gemm g, const StaticOrder& S, const Epi& E) {
;     ...
;             PG8_LDB(B1, 1, 1); PG8_STAGE(PG8_SB(1, 0), b3, voffB);
;             PG8_BAR; PG8_WAIT_L(0); PG8_MMA(0, 1, At, B1); PG8_BAR;
;             PG8_LDA(At, 1, 1); PG8_STAGE(PG8_SA(1, 0), a3, voffA);
;             PG8_BAR; PG8_WAIT_L(0); PG8_MMA(1, 0, At, B0); PG8_BAR; PG8_SCHED;
;             PG8_STAGE(PG8_SB(1, 1), b3 + hstepB, voffB);
;             PG8_WAIT_V(6); PG8_BAR; PG8_MMA(1, 1, At, B1); PG8_BAR;
	s_waitcnt lgkmcnt(0)
	s_waitcnt lgkmcnt(0)
	v_mfma_f32_16x16x32_bf16 v[62:65], v[180:183], v[202:205], v[62:65]
	v_mfma_f32_16x16x32_bf16 v[58:61], v[188:191], v[202:205], v[58:61]
	v_mfma_f32_16x16x32_bf16 v[46:49], v[180:183], v[210:213], v[46:49]
	v_mfma_f32_16x16x32_bf16 v[42:45], v[188:191], v[210:213], v[42:45]
	v_mfma_f32_16x16x32_bf16 v[30:33], v[180:183], v[218:221], v[30:33]
	v_mfma_f32_16x16x32_bf16 v[26:29], v[188:191], v[218:221], v[26:29]
	v_mfma_f32_16x16x32_bf16 v[14:17], v[180:183], v[226:229], v[14:17]
	v_mfma_f32_16x16x32_bf16 v[10:13], v[188:191], v[226:229], v[10:13]
	v_mfma_f32_16x16x32_bf16 v[62:65], v[184:187], v[206:209], v[62:65]
	v_mfma_f32_16x16x32_bf16 v[58:61], v[198:201], v[206:209], v[58:61]
	v_mfma_f32_16x16x32_bf16 v[46:49], v[184:187], v[214:217], v[46:49]
	v_mfma_f32_16x16x32_bf16 v[42:45], v[198:201], v[214:217], v[42:45]
	v_mfma_f32_16x16x32_bf16 v[30:33], v[184:187], v[222:225], v[30:33]
	v_mfma_f32_16x16x32_bf16 v[26:29], v[198:201], v[222:225], v[26:29]
	v_mfma_f32_16x16x32_bf16 v[14:17], v[184:187], v[230:233], v[14:17]
	v_mfma_f32_16x16x32_bf16 v[10:13], v[198:201], v[230:233], v[10:13]
	s_barrier
	s_add_u32 s14, s14, 0x80080
	s_addc_u32 s15, s15, 0
	s_add_i32 s16, s16, s24
	v_lshl_add_u64 v[152:153], s[14:15], 0, v[0:1]
	s_mov_b32 m0, s16
	s_nop 0
	global_load_lds_dwordx4 v[152:153], off
	v_lshl_add_u64 v[152:153], s[14:15], 0, v[146:147]
	s_add_i32 m0, s16, 0x2000
	s_nop 0
	global_load_lds_dwordx4 v[152:153], off
	s_waitcnt vmcnt(6)
	s_barrier
	v_mfma_f32_16x16x32_bf16 v[54:57], v[234:237], v[202:205], v[54:57]
	v_mfma_f32_16x16x32_bf16 v[50:53], v[242:245], v[202:205], v[50:53]
	v_mfma_f32_16x16x32_bf16 v[38:41], v[234:237], v[210:213], v[38:41]
	v_mfma_f32_16x16x32_bf16 v[34:37], v[242:245], v[210:213], v[34:37]
	v_mfma_f32_16x16x32_bf16 v[22:25], v[234:237], v[218:221], v[22:25]
	v_mfma_f32_16x16x32_bf16 v[18:21], v[242:245], v[218:221], v[18:21]
	v_mfma_f32_16x16x32_bf16 v[6:9], v[234:237], v[226:229], v[6:9]
	v_mfma_f32_16x16x32_bf16 v[2:5], v[242:245], v[226:229], v[2:5]
	v_mfma_f32_16x16x32_bf16 v[54:57], v[238:241], v[206:209], v[54:57]
	v_mfma_f32_16x16x32_bf16 v[50:53], v[246:249], v[206:209], v[50:53]
	v_mfma_f32_16x16x32_bf16 v[38:41], v[238:241], v[214:217], v[38:41]
	v_mfma_f32_16x16x32_bf16 v[34:37], v[246:249], v[214:217], v[34:37]
	v_mfma_f32_16x16x32_bf16 v[22:25], v[238:241], v[222:225], v[22:25]
	v_mfma_f32_16x16x32_bf16 v[18:21], v[246:249], v[222:225], v[18:21]
	v_mfma_f32_16x16x32_bf16 v[6:9], v[238:241], v[230:233], v[6:9]
	v_mfma_f32_16x16x32_bf16 v[2:5], v[246:249], v[230:233], v[2:5]
	s_add_i32 s38, s38, 2
	s_add_u32 s12, s12, 0x100
	s_addc_u32 s13, s13, 0
	s_add_u32 s36, s36, 0x100
	s_addc_u32 s37, s37, 0
	s_cmp_gt_u32 s38, 29
	s_barrier
	s_cbranch_scc0 .LBB0_69
	v_lshl_add_u32 v158, s10, 8, v154
	v_max_f32_e32 v122, v122, v122
	v_ashrrev_i32_e32 v159, 31, v158
	v_max_f32_e32 v122, 0, v122
	v_max_f32_e32 v123, v123, v123
	v_max_f32_e32 v124, v124, v124
	v_lshl_or_b32 v152, s31, 8, v156
	v_lshlrev_b64 v[180:181], 14, v[158:159]
	v_mul_f32_e32 v159, v122, v122
	v_max_f32_e32 v122, v127, v127
	v_max_f32_e32 v123, 0, v123
	v_max_f32_e32 v124, 0, v124
	v_ashrrev_i32_e32 v153, 31, v152
	v_max_f32_e32 v126, v126, v126
	v_max_f32_e32 v122, 0, v122
	v_mul_f32_e32 v127, v123, v123
	v_max_f32_e32 v123, v128, v128
	v_mul_f32_e32 v128, v124, v124
	v_max_f32_e32 v124, v129, v129
	v_max_f32_e32 v125, v125, v125
	v_lshl_add_u64 v[180:181], s[78:79], 0, v[180:181]
	v_lshlrev_b64 v[182:183], 1, v[152:153]
	v_max_f32_e32 v126, 0, v126
	v_mul_f32_e32 v122, v122, v122
	v_max_f32_e32 v123, 0, v123
	v_max_f32_e32 v124, 0, v124
	v_max_f32_e32 v125, 0, v125
	v_max_f32_e32 v114, v114, v114
	v_lshl_add_u64 v[152:153], v[180:181], 0, v[182:183]
	v_mul_f32_e32 v126, v126, v126
	v_mul_f32_e32 v123, v123, v123
	v_mul_f32_e32 v124, v124, v124
	v_mul_f32_e32 v125, v125, v125
	v_cvt_pk_bf16_f32 v122, v126, v122
	v_max_f32_e32 v114, 0, v114
	v_max_f32_e32 v115, v115, v115
	v_max_f32_e32 v116, v116, v116
	v_cvt_pk_bf16_f32 v123, v123, v124
	v_cvt_pk_bf16_f32 v124, v159, v127
	v_cvt_pk_bf16_f32 v125, v128, v125
	global_store_dwordx4 v[152:153], v[122:125], off
	v_max_f32_e32 v115, 0, v115
	v_max_f32_e32 v116, 0, v116
	v_mul_f32_e32 v122, v114, v114
	v_max_f32_e32 v114, v119, v119
	v_max_f32_e32 v118, v118, v118
	v_max_f32_e32 v114, 0, v114
	v_mul_f32_e32 v119, v115, v115
	v_max_f32_e32 v115, v120, v120
	v_mul_f32_e32 v120, v116, v116
	v_max_f32_e32 v116, v121, v121
	v_max_f32_e32 v117, v117, v117
	v_max_f32_e32 v118, 0, v118
	v_mul_f32_e32 v114, v114, v114
	v_max_f32_e32 v115, 0, v115
	v_max_f32_e32 v116, 0, v116
	v_max_f32_e32 v117, 0, v117
	v_mul_f32_e32 v118, v118, v118
	v_mul_f32_e32 v115, v115, v115
	v_mul_f32_e32 v116, v116, v116
	v_mul_f32_e32 v117, v117, v117
	v_cvt_pk_bf16_f32 v114, v118, v114
	v_max_f32_e32 v106, v106, v106
	v_cvt_pk_bf16_f32 v115, v115, v116
	v_cvt_pk_bf16_f32 v116, v122, v119
	v_cvt_pk_bf16_f32 v117, v120, v117
	global_store_dwordx4 v[152:153], v[114:117], off offset:256
	v_max_f32_e32 v106, 0, v106
	v_max_f32_e32 v107, v107, v107
	v_or_b32_e32 v114, 16, v158
	v_max_f32_e32 v108, v108, v108
	v_ashrrev_i32_e32 v115, 31, v114
	v_mul_f32_e32 v116, v106, v106
	v_max_f32_e32 v106, v111, v111
	v_max_f32_e32 v107, 0, v107
	v_max_f32_e32 v108, 0, v108
	v_lshlrev_b64 v[114:115], 14, v[114:115]
	v_max_f32_e32 v110, v110, v110
	v_max_f32_e32 v106, 0, v106
	v_mul_f32_e32 v111, v107, v107
	v_max_f32_e32 v107, v112, v112
	v_mul_f32_e32 v112, v108, v108
	v_max_f32_e32 v108, v113, v113
	v_max_f32_e32 v109, v109, v109
	v_lshl_add_u64 v[114:115], s[78:79], 0, v[114:115]
	v_max_f32_e32 v110, 0, v110
; __device__ __forceinline__ unsigned cvt_pk_bf16(float lo, float hi) { unsigned r; asm("v_cvt_pk_bf16_f32 %0, %1, %2" : "=v"(r) : "v"(lo), "v"(hi)); return r; }
;     __device__ __forceinline__ void operator()(const f32x4 (&acc)[2][2][4][2], const Unit& u, int wr, int wc, int fr, int fq) const {
;     ...
;             for (int m = 0; m < 4; ++m) { bf16_t* rowp = O + (size_t)(row0 + ai * HALF + m * 16) * ldc + col0;
; #pragma unroll
;                 for (int bj = 0; bj < 2; ++bj) { f32x4 v0 = acc[ai][bj][m][0], v1 = acc[ai][bj][m][1];
;                     if (ACT == 1) {
; #pragma unroll
;                         for (int j = 0; j < 4; ++j) { const float a = fmaxf(v0[j], 0.f), b = fmaxf(v1[j], 0.f); v0[j] = a * a; v1[j] = b * b; } }
;                     u32x4 w; w.x = cvt_pk_bf16(v0[0], v0[1]); w.y = cvt_pk_bf16(v0[2], v0[3]); w.z = cvt_pk_bf16(v1[0], v1[1]); w.w = cvt_pk_bf16(v1[2], v1[3]);
;                     *(u32x4*)(rowp + bj * HALF) = w; } }
	v_mul_f32_e32 v106, v106, v106
	v_max_f32_e32 v107, 0, v107
	v_max_f32_e32 v108, 0, v108
	v_max_f32_e32 v109, 0, v109
	v_max_f32_e32 v98, v98, v98
	v_lshl_add_u64 v[114:115], v[114:115], 0, v[182:183]
	v_mul_f32_e32 v110, v110, v110
	v_mul_f32_e32 v107, v107, v107
	v_mul_f32_e32 v108, v108, v108
	v_mul_f32_e32 v109, v109, v109
	v_cvt_pk_bf16_f32 v106, v110, v106
	v_max_f32_e32 v98, 0, v98
	v_max_f32_e32 v99, v99, v99
	v_max_f32_e32 v100, v100, v100
	v_cvt_pk_bf16_f32 v107, v107, v108
	v_cvt_pk_bf16_f32 v108, v116, v111
	v_cvt_pk_bf16_f32 v109, v112, v109
	global_store_dwordx4 v[114:115], v[106:109], off
	v_max_f32_e32 v99, 0, v99
	v_max_f32_e32 v100, 0, v100
	v_mul_f32_e32 v106, v98, v98
	v_max_f32_e32 v98, v103, v103
	v_max_f32_e32 v102, v102, v102
	v_max_f32_e32 v98, 0, v98
	v_mul_f32_e32 v103, v99, v99
	v_max_f32_e32 v99, v104, v104
	v_mul_f32_e32 v104, v100, v100
	v_max_f32_e32 v100, v105, v105
	v_max_f32_e32 v101, v101, v101
	v_max_f32_e32 v102, 0, v102
	v_mul_f32_e32 v98, v98, v98
	v_max_f32_e32 v99, 0, v99
	v_max_f32_e32 v100, 0, v100
	v_max_f32_e32 v101, 0, v101
	v_mul_f32_e32 v102, v102, v102
	v_mul_f32_e32 v99, v99, v99
	v_mul_f32_e32 v100, v100, v100
	v_mul_f32_e32 v101, v101, v101
	v_cvt_pk_bf16_f32 v98, v102, v98
	v_max_f32_e32 v90, v90, v90
	v_cvt_pk_bf16_f32 v99, v99, v100
	v_cvt_pk_bf16_f32 v100, v106, v103
	v_cvt_pk_bf16_f32 v101, v104, v101
	global_store_dwordx4 v[114:115], v[98:101], off offset:256
	v_max_f32_e32 v90, 0, v90
	v_max_f32_e32 v91, v91, v91
	v_or_b32_e32 v98, 32, v158
	v_max_f32_e32 v92, v92, v92
	v_ashrrev_i32_e32 v99, 31, v98
	v_mul_f32_e32 v100, v90, v90
	v_max_f32_e32 v90, v95, v95
	v_max_f32_e32 v91, 0, v91
	v_max_f32_e32 v92, 0, v92
	v_lshlrev_b64 v[98:99], 14, v[98:99]
	v_max_f32_e32 v94, v94, v94
	v_max_f32_e32 v90, 0, v90
	v_mul_f32_e32 v95, v91, v91
	v_max_f32_e32 v91, v96, v96
	v_mul_f32_e32 v96, v92, v92
	v_max_f32_e32 v92, v97, v97
	v_max_f32_e32 v93, v93, v93
	v_lshl_add_u64 v[98:99], s[78:79], 0, v[98:99]
	v_max_f32_e32 v94, 0, v94
	v_mul_f32_e32 v90, v90, v90
	v_max_f32_e32 v91, 0, v91
	v_max_f32_e32 v92, 0, v92
	v_max_f32_e32 v93, 0, v93
	v_max_f32_e32 v82, v82, v82
	v_lshl_add_u64 v[98:99], v[98:99], 0, v[182:183]
	v_mul_f32_e32 v94, v94, v94
	v_mul_f32_e32 v91, v91, v91
	v_mul_f32_e32 v92, v92, v92
	v_mul_f32_e32 v93, v93, v93
	v_cvt_pk_bf16_f32 v90, v94, v90
	v_max_f32_e32 v82, 0, v82
	v_max_f32_e32 v83, v83, v83
	v_max_f32_e32 v84, v84, v84
	v_cvt_pk_bf16_f32 v91, v91, v92
	v_cvt_pk_bf16_f32 v92, v100, v95
	v_cvt_pk_bf16_f32 v93, v96, v93
	global_store_dwordx4 v[98:99], v[90:93], off
	v_max_f32_e32 v83, 0, v83
	v_max_f32_e32 v84, 0, v84
	v_mul_f32_e32 v90, v82, v82
	v_max_f32_e32 v82, v87, v87
	v_max_f32_e32 v86, v86, v86
	v_max_f32_e32 v82, 0, v82
	v_mul_f32_e32 v87, v83, v83
	v_max_f32_e32 v83, v88, v88
	v_mul_f32_e32 v88, v84, v84
	v_max_f32_e32 v84, v89, v89
	v_max_f32_e32 v85, v85, v85
	v_max_f32_e32 v86, 0, v86
	v_mul_f32_e32 v82, v82, v82
	v_max_f32_e32 v83, 0, v83
	v_max_f32_e32 v84, 0, v84
	v_max_f32_e32 v85, 0, v85
	v_mul_f32_e32 v86, v86, v86
	v_mul_f32_e32 v83, v83, v83
	v_mul_f32_e32 v84, v84, v84
	v_mul_f32_e32 v85, v85, v85
	v_cvt_pk_bf16_f32 v82, v86, v82
	v_max_f32_e32 v74, v74, v74
	v_cvt_pk_bf16_f32 v83, v83, v84
	v_cvt_pk_bf16_f32 v84, v90, v87
	v_cvt_pk_bf16_f32 v85, v88, v85
	global_store_dwordx4 v[98:99], v[82:85], off offset:256
	v_max_f32_e32 v74, 0, v74
	v_max_f32_e32 v75, v75, v75
	v_or_b32_e32 v82, 48, v158
	v_max_f32_e32 v76, v76, v76
	v_ashrrev_i32_e32 v83, 31, v82
	v_mul_f32_e32 v84, v74, v74
	v_max_f32_e32 v74, v79, v79
	v_max_f32_e32 v75, 0, v75
	v_max_f32_e32 v76, 0, v76
	v_lshlrev_b64 v[82:83], 14, v[82:83]
	v_max_f32_e32 v78, v78, v78
	v_max_f32_e32 v74, 0, v74
	v_mul_f32_e32 v79, v75, v75
	v_max_f32_e32 v75, v80, v80
	v_mul_f32_e32 v80, v76, v76
	v_max_f32_e32 v76, v81, v81
	v_max_f32_e32 v77, v77, v77
	v_lshl_add_u64 v[82:83], s[78:79], 0, v[82:83]
	v_max_f32_e32 v78, 0, v78
	v_mul_f32_e32 v74, v74, v74
	v_max_f32_e32 v75, 0, v75
	v_max_f32_e32 v76, 0, v76
	v_max_f32_e32 v77, 0, v77
	v_max_f32_e32 v66, v66, v66
	v_max_f32_e32 v67, v67, v67
	v_max_f32_e32 v68, v68, v68
	v_lshl_add_u64 v[82:83], v[82:83], 0, v[182:183]
	v_mul_f32_e32 v78, v78, v78
	v_mul_f32_e32 v75, v75, v75
	v_mul_f32_e32 v76, v76, v76
	v_mul_f32_e32 v77, v77, v77
	v_cvt_pk_bf16_f32 v74, v78, v74
	v_max_f32_e32 v66, 0, v66
	v_max_f32_e32 v67, 0, v67
	v_max_f32_e32 v68, 0, v68
	v_cvt_pk_bf16_f32 v75, v75, v76
	v_cvt_pk_bf16_f32 v76, v84, v79
	v_cvt_pk_bf16_f32 v77, v80, v77
	global_store_dwordx4 v[82:83], v[74:77], off
	v_max_f32_e32 v69, v69, v69
	v_max_f32_e32 v70, v70, v70
	v_mul_f32_e32 v74, v66, v66
	v_max_f32_e32 v66, v71, v71
	v_mul_f32_e32 v71, v67, v67
	v_max_f32_e32 v67, v72, v72
	v_mul_f32_e32 v72, v68, v68
	v_max_f32_e32 v68, v73, v73
	v_max_f32_e32 v67, 0, v67
	v_max_f32_e32 v68, 0, v68
	v_max_f32_e32 v66, 0, v66
	v_mul_f32_e32 v67, v67, v67
	v_max_f32_e32 v69, 0, v69
	v_mul_f32_e32 v68, v68, v68
	v_max_f32_e32 v58, v58, v58
	v_max_f32_e32 v70, 0, v70
	v_mul_f32_e32 v66, v66, v66
	v_mul_f32_e32 v69, v69, v69
	v_cvt_pk_bf16_f32 v67, v67, v68
	v_cvt_pk_bf16_f32 v68, v74, v71
	v_max_f32_e32 v58, 0, v58
	v_max_f32_e32 v59, v59, v59
	v_max_f32_e32 v60, v60, v60
	v_mul_f32_e32 v70, v70, v70
	v_cvt_pk_bf16_f32 v66, v70, v66
	v_cvt_pk_bf16_f32 v69, v72, v69
	global_store_dwordx4 v[82:83], v[66:69], off offset:256
	v_max_f32_e32 v62, v62, v62
	v_max_f32_e32 v59, 0, v59
	v_mul_f32_e32 v68, v58, v58
	v_max_f32_e32 v58, v63, v63
	v_max_f32_e32 v60, 0, v60
	v_max_f32_e32 v62, 0, v62
	v_max_f32_e32 v58, 0, v58
	v_mul_f32_e32 v63, v59, v59
	v_max_f32_e32 v59, v64, v64
; __device__ __forceinline__ unsigned cvt_pk_bf16(float lo, float hi) { unsigned r; asm("v_cvt_pk_bf16_f32 %0, %1, %2" : "=v"(r) : "v"(lo), "v"(hi)); return r; }
;     __device__ __forceinline__ void operator()(const f32x4 (&acc)[2][2][4][2], const Unit& u, int wr, int wc, int fr, int fq) const {
;     ...
;             for (int m = 0; m < 4; ++m) { bf16_t* rowp = O + (size_t)(row0 + ai * HALF + m * 16) * ldc + col0;
; #pragma unroll
;                 for (int bj = 0; bj < 2; ++bj) { f32x4 v0 = acc[ai][bj][m][0], v1 = acc[ai][bj][m][1];
;                     if (ACT == 1) {
; #pragma unroll
;                         for (int j = 0; j < 4; ++j) { const float a = fmaxf(v0[j], 0.f), b = fmaxf(v1[j], 0.f); v0[j] = a * a; v1[j] = b * b; } }
;                     u32x4 w; w.x = cvt_pk_bf16(v0[0], v0[1]); w.y = cvt_pk_bf16(v0[2], v0[3]); w.z = cvt_pk_bf16(v1[0], v1[1]); w.w = cvt_pk_bf16(v1[2], v1[3]);
;                     *(u32x4*)(rowp + bj * HALF) = w; } }
	v_mul_f32_e32 v64, v60, v60
	v_max_f32_e32 v60, v65, v65
	v_mul_f32_e32 v62, v62, v62
	v_mul_f32_e32 v58, v58, v58
	v_max_f32_e32 v59, 0, v59
	v_max_f32_e32 v60, 0, v60
	v_max_f32_e32 v61, v61, v61
	s_mov_b32 s1, 0x200000
	v_mul_f32_e32 v59, v59, v59
	v_max_f32_e32 v61, 0, v61
	v_mul_f32_e32 v60, v60, v60
	v_cvt_pk_bf16_f32 v58, v62, v58
	v_add_co_u32_e32 v62, vcc, s1, v152
	v_max_f32_e32 v50, v50, v50
	v_max_f32_e32 v51, v51, v51
	v_max_f32_e32 v52, v52, v52
	v_mul_f32_e32 v61, v61, v61
	v_cvt_pk_bf16_f32 v59, v59, v60
	v_cvt_pk_bf16_f32 v60, v68, v63
	v_addc_co_u32_e32 v63, vcc, 0, v153, vcc
	v_max_f32_e32 v50, 0, v50
	v_max_f32_e32 v51, 0, v51
	v_max_f32_e32 v52, 0, v52
	v_cvt_pk_bf16_f32 v61, v64, v61
	global_store_dwordx4 v[62:63], v[58:61], off
	v_max_f32_e32 v53, v53, v53
	s_mov_b64 s[12:13], 0x200000
	v_mul_f32_e32 v58, v50, v50
	v_max_f32_e32 v50, v55, v55
	v_mul_f32_e32 v55, v51, v51
	v_max_f32_e32 v51, v56, v56
	v_mul_f32_e32 v56, v52, v52
	v_max_f32_e32 v52, v57, v57
	v_max_f32_e32 v51, 0, v51
	v_max_f32_e32 v52, 0, v52
	v_max_f32_e32 v54, v54, v54
	v_max_f32_e32 v50, 0, v50
	v_mul_f32_e32 v51, v51, v51
	v_max_f32_e32 v53, 0, v53
	v_mul_f32_e32 v52, v52, v52
	v_max_f32_e32 v42, v42, v42
	v_lshl_add_u64 v[66:67], v[152:153], 0, s[12:13]
	v_max_f32_e32 v54, 0, v54
	v_mul_f32_e32 v50, v50, v50
	v_mul_f32_e32 v53, v53, v53
	v_cvt_pk_bf16_f32 v51, v51, v52
	v_cvt_pk_bf16_f32 v52, v58, v55
	v_max_f32_e32 v42, 0, v42
	v_max_f32_e32 v43, v43, v43
	v_max_f32_e32 v44, v44, v44
	v_mul_f32_e32 v54, v54, v54
	v_cvt_pk_bf16_f32 v50, v54, v50
	v_cvt_pk_bf16_f32 v53, v56, v53
	global_store_dwordx4 v[66:67], v[50:53], off offset:256
	v_max_f32_e32 v46, v46, v46
	v_max_f32_e32 v43, 0, v43
	v_mul_f32_e32 v52, v42, v42
	v_max_f32_e32 v42, v47, v47
	v_max_f32_e32 v44, 0, v44
	v_max_f32_e32 v46, 0, v46
	v_max_f32_e32 v42, 0, v42
	v_mul_f32_e32 v47, v43, v43
	v_max_f32_e32 v43, v48, v48
	v_mul_f32_e32 v48, v44, v44
	v_max_f32_e32 v44, v49, v49
	v_mul_f32_e32 v46, v46, v46
	v_mul_f32_e32 v42, v42, v42
	v_max_f32_e32 v43, 0, v43
	v_max_f32_e32 v44, 0, v44
	v_max_f32_e32 v45, v45, v45
	s_mov_b32 s1, 0x240000
	v_mul_f32_e32 v43, v43, v43
	v_max_f32_e32 v45, 0, v45
	v_mul_f32_e32 v44, v44, v44
	v_cvt_pk_bf16_f32 v42, v46, v42
	v_add_co_u32_e32 v46, vcc, s1, v152
	v_max_f32_e32 v34, v34, v34
	v_max_f32_e32 v35, v35, v35
	v_max_f32_e32 v36, v36, v36
	v_mul_f32_e32 v45, v45, v45
	v_cvt_pk_bf16_f32 v43, v43, v44
	v_cvt_pk_bf16_f32 v44, v52, v47
	v_addc_co_u32_e32 v47, vcc, 0, v153, vcc
	v_max_f32_e32 v34, 0, v34
	v_max_f32_e32 v35, 0, v35
	v_max_f32_e32 v36, 0, v36
	v_cvt_pk_bf16_f32 v45, v48, v45
	global_store_dwordx4 v[46:47], v[42:45], off
	v_max_f32_e32 v37, v37, v37
	s_mov_b64 s[12:13], 0x240000
	v_mul_f32_e32 v42, v34, v34
	v_max_f32_e32 v34, v39, v39
	v_mul_f32_e32 v39, v35, v35
	v_max_f32_e32 v35, v40, v40
	v_mul_f32_e32 v40, v36, v36
	v_max_f32_e32 v36, v41, v41
	v_max_f32_e32 v35, 0, v35
	v_max_f32_e32 v36, 0, v36
	v_max_f32_e32 v38, v38, v38
	v_max_f32_e32 v34, 0, v34
	v_mul_f32_e32 v35, v35, v35
	v_max_f32_e32 v37, 0, v37
	v_mul_f32_e32 v36, v36, v36
	v_max_f32_e32 v26, v26, v26
	v_lshl_add_u64 v[50:51], v[152:153], 0, s[12:13]
	v_max_f32_e32 v38, 0, v38
	v_mul_f32_e32 v34, v34, v34
	v_mul_f32_e32 v37, v37, v37
	v_cvt_pk_bf16_f32 v35, v35, v36
	v_cvt_pk_bf16_f32 v36, v42, v39
	v_max_f32_e32 v26, 0, v26
	v_max_f32_e32 v27, v27, v27
	v_max_f32_e32 v28, v28, v28
	v_mul_f32_e32 v38, v38, v38
	v_cvt_pk_bf16_f32 v34, v38, v34
	v_cvt_pk_bf16_f32 v37, v40, v37
	global_store_dwordx4 v[50:51], v[34:37], off offset:256
	v_max_f32_e32 v30, v30, v30
	v_max_f32_e32 v27, 0, v27
	v_mul_f32_e32 v36, v26, v26
	v_max_f32_e32 v26, v31, v31
	v_max_f32_e32 v28, 0, v28
	v_max_f32_e32 v30, 0, v30
	v_max_f32_e32 v26, 0, v26
; __device__ __forceinline__ unsigned cvt_pk_bf16(float lo, float hi) { unsigned r; asm("v_cvt_pk_bf16_f32 %0, %1, %2" : "=v"(r) : "v"(lo), "v"(hi)); return r; }
; #define PG8_WAIT_V(n) asm volatile("s_waitcnt vmcnt(" #n ")" ::: "memory")
; #define PG8_BAR __builtin_amdgcn_s_barrier()
;     __device__ __forceinline__ void operator()(const f32x4 (&acc)[2][2][4][2], const Unit& u, int wr, int wc, int fr, int fq) const {
;     ...
;             for (int m = 0; m < 4; ++m) { bf16_t* rowp = O + (size_t)(row0 + ai * HALF + m * 16) * ldc + col0;
; #pragma unroll
;                 for (int bj = 0; bj < 2; ++bj) { f32x4 v0 = acc[ai][bj][m][0], v1 = acc[ai][bj][m][1];
;                     if (ACT == 1) {
; #pragma unroll
;                         for (int j = 0; j < 4; ++j) { const float a = fmaxf(v0[j], 0.f), b = fmaxf(v1[j], 0.f); v0[j] = a * a; v1[j] = b * b; } }
;                     u32x4 w; w.x = cvt_pk_bf16(v0[0], v0[1]); w.y = cvt_pk_bf16(v0[2], v0[3]); w.z = cvt_pk_bf16(v1[0], v1[1]); w.w = cvt_pk_bf16(v1[2], v1[3]);
;                     *(u32x4*)(rowp + bj * HALF) = w; } }
; template <class Epi, bool SEG>
; __device__ __forceinline__ void gemm_phase(LAS unsigned char* lds, const Gemm g, const StaticOrder& S, const Epi& E) {
;     ...
;         E(acc, cur, wr, wc, fr, fq);
;         if (!has_next) break;
; #pragma unroll
;         for (int a = 0; a < 2; ++a)
; #pragma unroll
;             for (int b = 0; b < 2; ++b)
; #pragma unroll
;                 for (int m = 0; m < 4; ++m)
; #pragma unroll
;                     for (int n = 0; n < 2; ++n) acc[a][b][m][n] = (f32x4){0.f, 0.f, 0.f, 0.f};
;         cur = nxt; cA = nA; cB = nB; ++ui;
;     }
;     PG8_WAIT_V(0);
;     if (wr == 0) PG8_BAR;
;     PG8_BAR;
	v_mul_f32_e32 v31, v27, v27
	v_max_f32_e32 v27, v32, v32
	v_mul_f32_e32 v32, v28, v28
	v_max_f32_e32 v28, v33, v33
	v_mul_f32_e32 v30, v30, v30
	v_mul_f32_e32 v26, v26, v26
	v_max_f32_e32 v27, 0, v27
	v_max_f32_e32 v28, 0, v28
	v_max_f32_e32 v29, v29, v29
	s_mov_b32 s1, 0x280000
	v_mul_f32_e32 v27, v27, v27
	v_max_f32_e32 v29, 0, v29
	v_mul_f32_e32 v28, v28, v28
	v_cvt_pk_bf16_f32 v26, v30, v26
	v_add_co_u32_e32 v30, vcc, s1, v152
	v_max_f32_e32 v18, v18, v18
	v_max_f32_e32 v19, v19, v19
	v_max_f32_e32 v20, v20, v20
	v_mul_f32_e32 v29, v29, v29
	v_cvt_pk_bf16_f32 v27, v27, v28
	v_cvt_pk_bf16_f32 v28, v36, v31
	v_addc_co_u32_e32 v31, vcc, 0, v153, vcc
	v_max_f32_e32 v18, 0, v18
	v_max_f32_e32 v19, 0, v19
	v_max_f32_e32 v20, 0, v20
	v_cvt_pk_bf16_f32 v29, v32, v29
	global_store_dwordx4 v[30:31], v[26:29], off
	v_max_f32_e32 v21, v21, v21
	s_mov_b64 s[12:13], 0x280000
	v_mul_f32_e32 v26, v18, v18
	v_max_f32_e32 v18, v23, v23
	v_mul_f32_e32 v23, v19, v19
	v_max_f32_e32 v19, v24, v24
	v_mul_f32_e32 v24, v20, v20
	v_max_f32_e32 v20, v25, v25
	v_max_f32_e32 v19, 0, v19
	v_max_f32_e32 v20, 0, v20
	v_max_f32_e32 v22, v22, v22
	v_max_f32_e32 v18, 0, v18
	v_mul_f32_e32 v19, v19, v19
	v_max_f32_e32 v21, 0, v21
	v_mul_f32_e32 v20, v20, v20
	v_max_f32_e32 v10, v10, v10
	v_lshl_add_u64 v[34:35], v[152:153], 0, s[12:13]
	v_max_f32_e32 v22, 0, v22
	v_mul_f32_e32 v18, v18, v18
	v_mul_f32_e32 v21, v21, v21
	v_cvt_pk_bf16_f32 v19, v19, v20
	v_cvt_pk_bf16_f32 v20, v26, v23
	v_max_f32_e32 v10, 0, v10
	v_max_f32_e32 v11, v11, v11
	v_max_f32_e32 v12, v12, v12
	v_mul_f32_e32 v22, v22, v22
	v_cvt_pk_bf16_f32 v18, v22, v18
	v_cvt_pk_bf16_f32 v21, v24, v21
	global_store_dwordx4 v[34:35], v[18:21], off offset:256
	v_max_f32_e32 v14, v14, v14
	v_max_f32_e32 v11, 0, v11
	v_mul_f32_e32 v20, v10, v10
	v_max_f32_e32 v10, v15, v15
	v_max_f32_e32 v12, 0, v12
	v_max_f32_e32 v14, 0, v14
	v_max_f32_e32 v10, 0, v10
	v_mul_f32_e32 v15, v11, v11
	v_max_f32_e32 v11, v16, v16
	v_mul_f32_e32 v16, v12, v12
	v_max_f32_e32 v12, v17, v17
	v_mul_f32_e32 v14, v14, v14
	v_mul_f32_e32 v10, v10, v10
	v_max_f32_e32 v11, 0, v11
	v_max_f32_e32 v12, 0, v12
	v_max_f32_e32 v13, v13, v13
	s_mov_b32 s1, 0x2c0000
	v_mul_f32_e32 v11, v11, v11
	v_max_f32_e32 v13, 0, v13
	v_mul_f32_e32 v12, v12, v12
	v_cvt_pk_bf16_f32 v10, v14, v10
	v_add_co_u32_e32 v14, vcc, s1, v152
	v_max_f32_e32 v2, v2, v2
	v_max_f32_e32 v3, v3, v3
	v_max_f32_e32 v4, v4, v4
	v_mul_f32_e32 v13, v13, v13
	v_cvt_pk_bf16_f32 v11, v11, v12
	v_cvt_pk_bf16_f32 v12, v20, v15
	v_addc_co_u32_e32 v15, vcc, 0, v153, vcc
	v_max_f32_e32 v2, 0, v2
	v_max_f32_e32 v3, 0, v3
	v_max_f32_e32 v4, 0, v4
	v_cvt_pk_bf16_f32 v13, v16, v13
	global_store_dwordx4 v[14:15], v[10:13], off
	v_max_f32_e32 v5, v5, v5
	s_mov_b64 s[12:13], 0x2c0000
	v_mul_f32_e32 v10, v2, v2
	v_max_f32_e32 v2, v7, v7
	v_mul_f32_e32 v7, v3, v3
	v_max_f32_e32 v3, v8, v8
	v_mul_f32_e32 v8, v4, v4
	v_max_f32_e32 v4, v9, v9
	v_max_f32_e32 v6, v6, v6
	v_max_f32_e32 v2, 0, v2
	v_max_f32_e32 v3, 0, v3
	v_max_f32_e32 v4, 0, v4
	v_max_f32_e32 v5, 0, v5
	v_lshl_add_u64 v[18:19], v[152:153], 0, s[12:13]
	v_max_f32_e32 v6, 0, v6
	v_mul_f32_e32 v2, v2, v2
	v_mul_f32_e32 v3, v3, v3
	v_mul_f32_e32 v4, v4, v4
	v_mul_f32_e32 v5, v5, v5
	s_and_b64 vcc, exec, s[2:3]
	s_mov_b32 s31, s0
	s_mov_b32 s10, s4
	s_mov_b64 s[14:15], s[8:9]
	s_mov_b64 s[12:13], s[6:7]
	v_mul_f32_e32 v6, v6, v6
	v_cvt_pk_bf16_f32 v2, v6, v2
	v_cvt_pk_bf16_f32 v3, v3, v4
	v_cvt_pk_bf16_f32 v4, v10, v7
	v_cvt_pk_bf16_f32 v5, v8, v5
	global_store_dwordx4 v[18:19], v[2:5], off offset:256
	s_cbranch_vccz .LBB0_62
	s_waitcnt vmcnt(0)
	s_cmpk_gt_u32 s21, 0xff
	s_cbranch_scc1 .LBB0_73
	s_barrier
.LBB0_73:
	v_readlane_b32 s28, v254, 6
	v_readlane_b32 s29, v254, 8
	s_setprio 0
	s_barrier

; __device__ __forceinline__ int otid() { int t = threadIdx.x; asm volatile("" : "+v"(t)); return t; }
; #define PG8_STAGE(bufoff, gbase, voff) do { _Pragma("unroll") for (int _i = 0; _i < 2; ++_i) \
;         __builtin_amdgcn_global_load_lds((const unsigned*)((const char*)(gbase) + (voff)[_i]), (LAS unsigned*)(lds + (bufoff) + ldsw + _i * 8192), 16, 0, 0); } while (0)
; #define PG8_WAIT_V(n) asm volatile("s_waitcnt vmcnt(" #n ")" ::: "memory")
; template <class Epi, bool SEG>
; __device__ __forceinline__ void gemm_phase(LAS unsigned char* lds, const Gemm g, const StaticOrder& S, const Epi& E) {
;     const int tid = otid(), wid = __builtin_amdgcn_readfirstlane(tid >> 6), lane = tid & 63, wr = wid >> 2, wc = wid & 3, fr = lane & 15, fq = lane >> 4;
;     const int K = g.K, nt = K / BK, lda = g.lda;
;     unsigned voffA[2], voffB[2];
; #pragma unroll
;     for (int i = 0; i < 2; ++i) { int R, C; stage_rc(tid * 16 + i * 8192, R, C); const int Rb = Epi::PERM ? ((R & ~31) + perm32(R & 31)) : R;
;         voffA[i] = (unsigned)(R * lda + C) * 2u; voffB[i] = (unsigned)(Rb * K + C) * 2u; }
;     const size_t kstep = (size_t)(BK * 2);
;     const size_t hstepA = (size_t)HALF * lda * 2, hstepB = (size_t)HALF * K * 2;
;     const size_t tstepA = 2 * hstepA, tstepB = 2 * hstepB;
;     const unsigned ldsw = (unsigned)wid * 1024u;
;     const int aoff = lds_byte(wr * 64 + fr, fq * 8), boff = lds_byte(wc * 32 + fr, fq * 8);
;     ...
;     Unit cur, nxt; int ui = 0;
;     if (!S.next(0, cur)) return;
;     f32x4 acc[2][2][4][2];
; #pragma unroll
;     for (int a = 0; a < 2; ++a)
; #pragma unroll
;         for (int b = 0; b < 2; ++b)
; #pragma unroll
;             for (int m = 0; m < 4; ++m)
; #pragma unroll
;                 for (int n = 0; n < 2; ++n) acc[a][b][m][n] = (f32x4){0.f, 0.f, 0.f, 0.f};
;     bf16x8 At[4][2], B0[2][2], B1[2][2];
;     const char* cA = (const char*)g.A + (size_t)cur.pm * tstepA; const char* cB = (const char*)g.Bt + (size_t)cur.pn * tstepB;
;     PG8_STAGE(PG8_SB(0, 0), cB, voffB); PG8_STAGE(PG8_SA(0, 0), cA, voffA); PG8_STAGE(PG8_SB(0, 1), cB + hstepB, voffB); PG8_STAGE(PG8_SA(0, 1), cA + hstepA, voffA);
;     if (wr == 1) PG8_BAR;
;     PG8_WAIT_V(4); PG8_BAR;
;     PG8_STAGE(PG8_SB(1, 0), cB + kstep, voffB); PG8_STAGE(PG8_SA(1, 0), cA + kstep, voffA); PG8_STAGE(PG8_SB(1, 1), cB + hstepB + kstep, voffB);
;     PG8_WAIT_V(6); PG8_BAR;
.LBB0_89:
	v_bfe_i32 v4, v2, 27, 1
	v_lshlrev_b32_e32 v3, 4, v2
	v_lshrrev_b32_e32 v4, 22, v4
	v_add_u32_e32 v4, v3, v4
	v_and_b32_e32 v4, 0xfffffc00, v4
	v_sub_u32_e32 v4, v3, v4
	v_lshrrev_b32_e32 v5, 4, v4
	v_ashrrev_i32_e32 v0, 31, v2
	v_bitop3_b32 v5, v5, v4, 32 bitop3:0x6c
	v_ashrrev_i32_e32 v4, 31, v4
	v_lshrrev_b32_e32 v0, 26, v0
	v_lshrrev_b32_e32 v4, 26, v4
	v_add_u32_e32 v0, v2, v0
	v_add_u32_e32 v4, v5, v4
	v_ashrrev_i32_e32 v0, 6, v0
	v_ashrrev_i32_e32 v4, 6, v4
	v_lshlrev_b32_e32 v6, 3, v0
	v_mul_i32_i24_e32 v7, 64, v4
	v_and_b32_e32 v6, -16, v6
	v_lshlrev_b32_e32 v0, 5, v0
	v_sub_u32_e32 v5, v5, v7
	v_add_u32_e32 v6, v4, v6
	v_and_b32_e32 v0, 32, v0
	v_ashrrev_i16_sdwa v5, v172, sext(v5) dst_sel:DWORD dst_unused:UNUSED_PAD src0_sel:DWORD src1_sel:BYTE_0
	v_add_u32_sdwa v0, v0, sext(v5) dst_sel:DWORD dst_unused:UNUSED_PAD src0_sel:DWORD src1_sel:WORD_0
	v_lshlrev_b32_e32 v5, 1, v6
	v_lshrrev_b32_e32 v7, 2, v6
	v_and_b32_e32 v4, 3, v4
	s_mov_b32 s2, 0xfffe0
	v_and_b32_e32 v5, 24, v5
	v_and_b32_e32 v7, 4, v7
	v_and_or_b32 v4, v6, s2, v4
	s_movk_i32 s4, 0x1d00
	v_or3_b32 v4, v4, v7, v5
	v_mul_lo_u32 v5, v6, s4
	v_add_lshl_u32 v142, v0, v5, 1
	v_lshlrev_b32_e32 v0, 1, v0
	v_add_u32_e32 v3, 0x2000, v3
	v_lshl_add_u32 v0, v4, 12, v0
	v_ashrrev_i32_e32 v4, 31, v3
	v_lshrrev_b32_e32 v4, 22, v4
	v_add_u32_e32 v4, v3, v4
	v_ashrrev_i32_e32 v4, 10, v4
	v_mul_i32_i24_e32 v5, 0x400, v4
	v_sub_u32_e32 v3, v3, v5
	v_lshrrev_b32_e32 v5, 4, v3
	v_bitop3_b32 v3, v5, v3, 32 bitop3:0x6c
	v_ashrrev_i32_e32 v6, 31, v3
	v_lshrrev_b32_e32 v6, 26, v6
	v_add_u32_e32 v6, v3, v6
	s_add_i32 s0, s3, s0
	v_lshlrev_b32_e32 v5, 3, v4
	v_ashrrev_i32_e32 v7, 6, v6
	v_and_b32_e32 v6, 0xc0, v6
	s_ashr_i32 s3, s0, 31
	v_and_b32_e32 v5, -16, v5
	v_lshlrev_b32_e32 v4, 5, v4
	v_sub_u32_e32 v3, v3, v6
	s_lshr_b32 s3, s3, 26
	v_add_u32_e32 v5, v7, v5
	v_and_b32_e32 v4, 32, v4
	v_ashrrev_i16_sdwa v3, v172, sext(v3) dst_sel:DWORD dst_unused:UNUSED_PAD src0_sel:DWORD src1_sel:BYTE_0
	v_and_b32_e32 v7, 3, v7
	s_add_i32 s3, s0, s3
	v_add_u32_sdwa v3, v4, sext(v3) dst_sel:DWORD dst_unused:UNUSED_PAD src0_sel:DWORD src1_sel:WORD_0
	v_lshlrev_b32_e32 v4, 1, v5
	v_lshrrev_b32_e32 v6, 2, v5
	v_and_or_b32 v7, v5, s2, v7
	v_mul_lo_u32 v5, v5, s4
	s_ashr_i32 s4, s3, 6
	s_and_b32 s3, s3, 0xffc0
	s_sub_i32 s3, s0, s3
	s_bfe_i32 s0, s3, 0x80000
	s_bfe_u32 s0, s0, 0x3000c
	s_add_i32 s5, s3, s0
	s_bfe_i32 s0, s5, 0x80000
	s_and_b32 s5, s5, 0xf8
	s_sext_i32_i16 s0, s0
	s_sub_i32 s3, s3, s5
	s_ashr_i32 s1, s17, 8
	s_lshl_b32 s4, s4, 3
	s_lshr_b32 s0, s0, 3
	s_sext_i32_i8 s3, s3
	s_ashr_i32 s2, s17, 6
	s_add_i32 s30, s4, s3
	s_bfe_i64 s[4:5], s[0:1], 0x100000
	s_lshl_b32 s20, s2, 10
	s_lshl_b64 s[4:5], s[4:5], 20
	v_readlane_b32 s8, v253, 16
	v_readlane_b32 s9, v253, 17
	s_add_u32 s12, s8, s4
	s_addc_u32 s13, s9, s5
	s_add_i32 s21, s20, 0
	v_and_b32_e32 v4, 24, v4
	v_and_b32_e32 v6, 4, v6
	s_add_i32 m0, s21, 0x10000
	v_or3_b32 v4, v7, v6, v4
	v_add_lshl_u32 v144, v3, v5, 1
	v_lshlrev_b32_e32 v3, 1, v3
	s_mul_i32 s6, s30, 0x3a0000
	global_load_lds_dwordx4 v0, s[12:13]
	s_add_i32 m0, s21, 0x12000
	v_lshl_add_u32 v146, v4, 12, v3
	s_mul_hi_i32 s3, s30, 0x3a0000
	s_add_u32 s10, s78, s6
	global_load_lds_dwordx4 v146, s[12:13]
	s_addc_u32 s11, s79, s3
	s_mov_b32 m0, s21
	s_add_i32 s23, s21, 0x2000
	global_load_lds_dwordx4 v142, s[10:11]
	s_mov_b32 m0, s23
	s_add_u32 s4, s12, 0x80000
	global_load_lds_dwordx4 v144, s[10:11]
	s_addc_u32 s5, s13, 0
	s_add_i32 m0, s21, 0x14000
	s_nop 0
	global_load_lds_dwordx4 v0, s[4:5]
	s_add_i32 m0, s21, 0x16000
	s_nop 0
	global_load_lds_dwordx4 v146, s[4:5]
	s_add_u32 s4, s10, 0x1d0000
	s_addc_u32 s5, s11, 0
	s_add_i32 s24, s21, 0x4000
	s_mov_b32 m0, s24
	s_add_i32 s25, s21, 0x6000
	global_load_lds_dwordx4 v142, s[4:5]
	s_mov_b32 m0, s25
	s_cmp_lg_u32 s1, 1
	global_load_lds_dwordx4 v144, s[4:5]
	s_cbranch_scc1 .LBB0_91
	s_setprio 1
	s_barrier

; #define PG8_STAGE(bufoff, gbase, voff) do { _Pragma("unroll") for (int _i = 0; _i < 2; ++_i) \
;         __builtin_amdgcn_global_load_lds((const unsigned*)((const char*)(gbase) + (voff)[_i]), (LAS unsigned*)(lds + (bufoff) + ldsw + _i * 8192), 16, 0, 0); } while (0)
; #define PG8_LDA(dst, b, h) do { _Pragma("unroll") for (int m = 0; m < 4; ++m) _Pragma("unroll") for (int k = 0; k < 2; ++k) dst[m][k] = *(const LAS bf16x8*)(lds + PG8_SA(b, h) + aoff + m * 2048 + k * 1024); } while (0)
; #define PG8_LDB(dst, b, h) do { _Pragma("unroll") for (int n = 0; n < 2; ++n) _Pragma("unroll") for (int k = 0; k < 2; ++k) dst[n][k] = *(const LAS bf16x8*)(lds + PG8_SB(b, h) + boff + n * 2048 + k * 1024); } while (0)
; #define PG8_MMA(ai, bj, At, Bt) do { __builtin_amdgcn_s_setprio(1); _Pragma("unroll") for (int m = 0; m < 4; ++m) _Pragma("unroll") for (int n = 0; n < 2; ++n) _Pragma("unroll") for (int k = 0; k < 2; ++k) \
;         acc[ai][bj][m][n] = __builtin_amdgcn_mfma_f32_16x16x32_bf16(Bt[n][k], At[m][k], acc[ai][bj][m][n], 0, 0, 0); __builtin_amdgcn_s_setprio(0); } while (0)
; #define PG8_WAIT_L(n) asm volatile("s_waitcnt lgkmcnt(" #n ")" ::: "memory")
; template <bool SEG> __device__ __forceinline__ size_t akoff(int t) {
;     if (!SEG) return (size_t)t * (BK * 2);
;     const int kk = t * BK; const int col = kk < 512 ? kk : (kk < 1280 ? kk + 1024 : kk + 5248); return (size_t)col * 2;
; }
; template <class Epi, bool SEG>
; __device__ __forceinline__ void gemm_phase(LAS unsigned char* lds, const Gemm g, const StaticOrder& S, const Epi& E) {
;     ...
;         for (int t = 0; t < nt; t += 2) {
;             const bool last = (t == nt - 2);
;             const char* a1 = cA + akoff<SEG>(t) + kstep;
;             const char* a2 = last ? nA : cA + akoff<SEG>(t + 2); const char* b2 = last ? nB : cB + (size_t)(t + 2) * kstep;
;             const char* a3 = a2 + kstep; const char* b3 = b2 + kstep;
;             PG8_LDB(B0, 0, 0); PG8_SCHED; PG8_LDA(At, 0, 0); PG8_STAGE(PG8_SA(1, 1), a1 + hstepA, voffA);
;             PG8_WAIT_L(8); PG8_BAR; PG8_WAIT_L(0); PG8_MMA(0, 0, At, B0); PG8_BAR; PG8_SCHED;
;             PG8_LDB(B1, 0, 1); PG8_STAGE(PG8_SB(0, 0), b2, voffB);
;             PG8_BAR; PG8_WAIT_L(0); PG8_MMA(0, 1, At, B1); PG8_BAR;
;             PG8_LDA(At, 0, 1); PG8_STAGE(PG8_SA(0, 0), a2, voffA);
;             PG8_BAR; PG8_WAIT_L(0); PG8_MMA(1, 0, At, B0); PG8_BAR; PG8_SCHED;
.LBB0_102:
	s_cmp_lt_u32 s38, 20
	s_movk_i32 s39, 0x2900
	s_cselect_b32 s39, 0x800, s39
	s_cmp_gt_u32 s38, 7
	s_cselect_b32 s39, s39, 0
	s_add_i32 s39, s0, s39
	s_add_u32 s39, s10, s39
	s_addc_u32 s41, s11, 0
	s_add_u32 s40, s35, s0
	s_addc_u32 s42, s36, s1
	s_add_i32 s43, 0, 0x10000
	v_add_u32_e32 v148, s43, v151
	ds_read_b128 v[154:157], v148
	ds_read_b128 v[180:183], v148 offset:1024
	ds_read_b128 v[184:187], v148 offset:2048
	ds_read_b128 v[188:191], v148 offset:3072
	s_and_b64 s[14:15], exec, s[14:15]
	s_cselect_b32 s15, s5, s42
	s_cselect_b32 s14, s34, s40
	s_add_u32 s40, s39, 0x1d0080
	s_addc_u32 s41, s41, 0
	v_lshl_add_u64 v[148:149], s[40:41], 0, v[142:143]
	s_add_i32 m0, s21, 0xc000
	ds_read_b128 v[198:201], v153
	ds_read_b128 v[202:205], v153 offset:1024
	ds_read_b128 v[206:209], v153 offset:2048
	ds_read_b128 v[210:213], v153 offset:3072
	ds_read_b128 v[214:217], v153 offset:4096
	ds_read_b128 v[218:221], v153 offset:5120
	ds_read_b128 v[222:225], v153 offset:6144
	ds_read_b128 v[226:229], v153 offset:7168
	global_load_lds_dwordx4 v[148:149], off
	v_lshl_add_u64 v[148:149], s[40:41], 0, v[144:145]
	s_add_i32 m0, s21, 0xe000
	s_nop 0
	global_load_lds_dwordx4 v[148:149], off
	s_waitcnt lgkmcnt(8)
	s_barrier
	s_waitcnt lgkmcnt(0)
	s_waitcnt lgkmcnt(0)
	v_mfma_f32_16x16x32_bf16 v[126:129], v[154:157], v[198:201], v[126:129]
	v_mfma_f32_16x16x32_bf16 v[122:125], v[184:187], v[198:201], v[122:125]
	v_mfma_f32_16x16x32_bf16 v[118:121], v[154:157], v[206:209], v[118:121]
	v_mfma_f32_16x16x32_bf16 v[110:113], v[184:187], v[206:209], v[110:113]
	v_mfma_f32_16x16x32_bf16 v[102:105], v[154:157], v[214:217], v[102:105]
	v_mfma_f32_16x16x32_bf16 v[94:97], v[184:187], v[214:217], v[94:97]
	v_mfma_f32_16x16x32_bf16 v[82:85], v[154:157], v[222:225], v[82:85]
	v_mfma_f32_16x16x32_bf16 v[74:77], v[184:187], v[222:225], v[74:77]
	v_mfma_f32_16x16x32_bf16 v[126:129], v[180:183], v[202:205], v[126:129]
	v_mfma_f32_16x16x32_bf16 v[122:125], v[188:191], v[202:205], v[122:125]
	v_mfma_f32_16x16x32_bf16 v[118:121], v[180:183], v[210:213], v[118:121]
	v_mfma_f32_16x16x32_bf16 v[110:113], v[188:191], v[210:213], v[110:113]
	v_mfma_f32_16x16x32_bf16 v[102:105], v[180:183], v[218:221], v[102:105]
	v_mfma_f32_16x16x32_bf16 v[94:97], v[188:191], v[218:221], v[94:97]
	v_mfma_f32_16x16x32_bf16 v[82:85], v[180:183], v[226:229], v[82:85]
	v_mfma_f32_16x16x32_bf16 v[74:77], v[188:191], v[226:229], v[74:77]
	s_barrier
	s_add_i32 s39, 0, 0x14000
	v_add_u32_e32 v148, s39, v151
	s_add_i32 s40, s43, s20
	ds_read_b128 v[230:233], v148
	ds_read_b128 v[234:237], v148 offset:1024
	ds_read_b128 v[238:241], v148 offset:2048
	ds_read_b128 v[242:245], v148 offset:3072
	v_lshl_add_u64 v[148:149], s[14:15], 0, v[0:1]
	s_mov_b32 m0, s40
	v_lshl_add_u64 v[158:159], s[14:15], 0, v[146:147]
	global_load_lds_dwordx4 v[148:149], off
	s_add_i32 m0, s40, 0x2000
	s_nop 0
	global_load_lds_dwordx4 v[158:159], off
	s_barrier
	s_waitcnt lgkmcnt(0)
	s_waitcnt lgkmcnt(0)
	v_mfma_f32_16x16x32_bf16 v[114:117], v[230:233], v[198:201], v[114:117]
	v_mfma_f32_16x16x32_bf16 v[106:109], v[238:241], v[198:201], v[106:109]
	v_mfma_f32_16x16x32_bf16 v[98:101], v[230:233], v[206:209], v[98:101]
	v_mfma_f32_16x16x32_bf16 v[90:93], v[238:241], v[206:209], v[90:93]
	v_mfma_f32_16x16x32_bf16 v[86:89], v[230:233], v[214:217], v[86:89]
	v_mfma_f32_16x16x32_bf16 v[78:81], v[238:241], v[214:217], v[78:81]
	v_mfma_f32_16x16x32_bf16 v[70:73], v[230:233], v[222:225], v[70:73]
	v_mfma_f32_16x16x32_bf16 v[66:69], v[238:241], v[222:225], v[66:69]
	v_mfma_f32_16x16x32_bf16 v[114:117], v[234:237], v[202:205], v[114:117]
	v_mfma_f32_16x16x32_bf16 v[106:109], v[242:245], v[202:205], v[106:109]
	v_mfma_f32_16x16x32_bf16 v[98:101], v[234:237], v[210:213], v[98:101]
	v_mfma_f32_16x16x32_bf16 v[90:93], v[242:245], v[210:213], v[90:93]
	v_mfma_f32_16x16x32_bf16 v[86:89], v[234:237], v[218:221], v[86:89]
	v_mfma_f32_16x16x32_bf16 v[78:81], v[242:245], v[218:221], v[78:81]
	v_mfma_f32_16x16x32_bf16 v[70:73], v[234:237], v[226:229], v[70:73]
	v_mfma_f32_16x16x32_bf16 v[66:69], v[242:245], v[226:229], v[66:69]
	s_mov_b32 m0, s21
	v_lshl_add_u64 v[192:193], s[12:13], 0, v[142:143]
	s_barrier
	ds_read_b128 v[198:201], v153 offset:16384
	ds_read_b128 v[202:205], v153 offset:17408
	ds_read_b128 v[206:209], v153 offset:18432
	ds_read_b128 v[210:213], v153 offset:19456
	ds_read_b128 v[214:217], v153 offset:20480
	ds_read_b128 v[218:221], v153 offset:21504
	ds_read_b128 v[222:225], v153 offset:22528
	ds_read_b128 v[226:229], v153 offset:23552
	global_load_lds_dwordx4 v[192:193], off
	v_lshl_add_u64 v[246:247], s[12:13], 0, v[144:145]
	s_mov_b32 m0, s23
	s_nop 0
	global_load_lds_dwordx4 v[246:247], off
	s_barrier
	s_waitcnt lgkmcnt(0)
	s_waitcnt lgkmcnt(0)
	v_mfma_f32_16x16x32_bf16 v[62:65], v[154:157], v[198:201], v[62:65]
	v_mfma_f32_16x16x32_bf16 v[58:61], v[184:187], v[198:201], v[58:61]
	v_mfma_f32_16x16x32_bf16 v[54:57], v[154:157], v[206:209], v[54:57]
	v_mfma_f32_16x16x32_bf16 v[46:49], v[184:187], v[206:209], v[46:49]
	v_mfma_f32_16x16x32_bf16 v[38:41], v[154:157], v[214:217], v[38:41]
	v_mfma_f32_16x16x32_bf16 v[30:33], v[184:187], v[214:217], v[30:33]
	v_mfma_f32_16x16x32_bf16 v[22:25], v[154:157], v[222:225], v[22:25]
	v_mfma_f32_16x16x32_bf16 v[14:17], v[184:187], v[222:225], v[14:17]
	v_mfma_f32_16x16x32_bf16 v[62:65], v[180:183], v[202:205], v[62:65]
	v_mfma_f32_16x16x32_bf16 v[58:61], v[188:191], v[202:205], v[58:61]
	v_mfma_f32_16x16x32_bf16 v[54:57], v[180:183], v[210:213], v[54:57]
	v_mfma_f32_16x16x32_bf16 v[46:49], v[188:191], v[210:213], v[46:49]
	v_mfma_f32_16x16x32_bf16 v[38:41], v[180:183], v[218:221], v[38:41]
	v_mfma_f32_16x16x32_bf16 v[30:33], v[188:191], v[218:221], v[30:33]
	v_mfma_f32_16x16x32_bf16 v[22:25], v[180:183], v[226:229], v[22:25]
	v_mfma_f32_16x16x32_bf16 v[14:17], v[188:191], v[226:229], v[14:17]
	s_barrier
; #define PG8_STAGE(bufoff, gbase, voff) do { _Pragma("unroll") for (int _i = 0; _i < 2; ++_i) \
;         __builtin_amdgcn_global_load_lds((const unsigned*)((const char*)(gbase) + (voff)[_i]), (LAS unsigned*)(lds + (bufoff) + ldsw + _i * 8192), 16, 0, 0); } while (0)
; #define PG8_LDA(dst, b, h) do { _Pragma("unroll") for (int m = 0; m < 4; ++m) _Pragma("unroll") for (int k = 0; k < 2; ++k) dst[m][k] = *(const LAS bf16x8*)(lds + PG8_SA(b, h) + aoff + m * 2048 + k * 1024); } while (0)
; #define PG8_LDB(dst, b, h) do { _Pragma("unroll") for (int n = 0; n < 2; ++n) _Pragma("unroll") for (int k = 0; k < 2; ++k) dst[n][k] = *(const LAS bf16x8*)(lds + PG8_SB(b, h) + boff + n * 2048 + k * 1024); } while (0)
; #define PG8_MMA(ai, bj, At, Bt) do { __builtin_amdgcn_s_setprio(1); _Pragma("unroll") for (int m = 0; m < 4; ++m) _Pragma("unroll") for (int n = 0; n < 2; ++n) _Pragma("unroll") for (int k = 0; k < 2; ++k) \
;         acc[ai][bj][m][n] = __builtin_amdgcn_mfma_f32_16x16x32_bf16(Bt[n][k], At[m][k], acc[ai][bj][m][n], 0, 0, 0); __builtin_amdgcn_s_setprio(0); } while (0)
; #define PG8_WAIT_V(n) asm volatile("s_waitcnt vmcnt(" #n ")" ::: "memory")
; #define PG8_WAIT_L(n) asm volatile("s_waitcnt lgkmcnt(" #n ")" ::: "memory")
; #define PG8_BAR __builtin_amdgcn_s_barrier()
; #define PG8_SCHED __builtin_amdgcn_sched_barrier(0)
; template <class Epi, bool SEG>
; __device__ __forceinline__ void gemm_phase(LAS unsigned char* lds, const Gemm g, const StaticOrder& S, const Epi& E) {
;     ...
;             PG8_STAGE(PG8_SB(0, 1), b2 + hstepB, voffB);
;             PG8_WAIT_V(6); PG8_BAR; PG8_MMA(1, 1, At, B1); PG8_BAR;
;             PG8_LDB(B0, 1, 0); PG8_SCHED; PG8_LDA(At, 1, 0); PG8_STAGE(PG8_SA(0, 1), a2 + hstepA, voffA);
;             PG8_WAIT_L(8); PG8_BAR; PG8_WAIT_L(0); PG8_MMA(0, 0, At, B0); PG8_BAR; PG8_SCHED;
;             PG8_LDB(B1, 1, 1); PG8_STAGE(PG8_SB(1, 0), b3, voffB);
;             PG8_BAR; PG8_WAIT_L(0); PG8_MMA(0, 1, At, B1); PG8_BAR;
;             PG8_LDA(At, 1, 1); PG8_STAGE(PG8_SA(1, 0), a3, voffA);
;             PG8_BAR; PG8_WAIT_L(0); PG8_MMA(1, 0, At, B0); PG8_BAR; PG8_SCHED;
	s_add_u32 s40, s14, 0x80000
	s_addc_u32 s41, s15, 0
	s_add_i32 s39, s39, s20
	v_lshl_add_u64 v[154:155], s[40:41], 0, v[0:1]
	s_mov_b32 m0, s39
	s_nop 0
	global_load_lds_dwordx4 v[154:155], off
	v_lshl_add_u64 v[154:155], s[40:41], 0, v[146:147]
	s_add_i32 m0, s39, 0x2000
	s_nop 0
	global_load_lds_dwordx4 v[154:155], off
	s_waitcnt vmcnt(6)
	s_barrier
	v_mfma_f32_16x16x32_bf16 v[50:53], v[230:233], v[198:201], v[50:53]
	v_mfma_f32_16x16x32_bf16 v[42:45], v[238:241], v[198:201], v[42:45]
	v_mfma_f32_16x16x32_bf16 v[34:37], v[230:233], v[206:209], v[34:37]
	v_mfma_f32_16x16x32_bf16 v[26:29], v[238:241], v[206:209], v[26:29]
	v_mfma_f32_16x16x32_bf16 v[18:21], v[230:233], v[214:217], v[18:21]
	v_mfma_f32_16x16x32_bf16 v[10:13], v[238:241], v[214:217], v[10:13]
	v_mfma_f32_16x16x32_bf16 v[6:9], v[230:233], v[222:225], v[6:9]
	v_mfma_f32_16x16x32_bf16 v[2:5], v[238:241], v[222:225], v[2:5]
	v_mfma_f32_16x16x32_bf16 v[50:53], v[234:237], v[202:205], v[50:53]
	v_mfma_f32_16x16x32_bf16 v[42:45], v[242:245], v[202:205], v[42:45]
	v_mfma_f32_16x16x32_bf16 v[34:37], v[234:237], v[210:213], v[34:37]
	v_mfma_f32_16x16x32_bf16 v[26:29], v[242:245], v[210:213], v[26:29]
	v_mfma_f32_16x16x32_bf16 v[18:21], v[234:237], v[218:221], v[18:21]
	v_mfma_f32_16x16x32_bf16 v[10:13], v[242:245], v[218:221], v[10:13]
	v_mfma_f32_16x16x32_bf16 v[6:9], v[234:237], v[226:229], v[6:9]
	v_mfma_f32_16x16x32_bf16 v[2:5], v[242:245], v[226:229], v[2:5]
	s_add_i32 s39, 0, 0x18000
	v_add_u32_e32 v179, s39, v151
	s_barrier
	ds_read_b128 v[154:157], v179
	ds_read_b128 v[180:183], v179 offset:1024
	ds_read_b128 v[184:187], v179 offset:2048
	ds_read_b128 v[188:191], v179 offset:3072
	s_add_u32 s12, s12, 0x1d0000
	s_addc_u32 s13, s13, 0
	s_mov_b32 m0, s24
	v_lshl_add_u64 v[230:231], s[12:13], 0, v[142:143]
	ds_read_b128 v[198:201], v153 offset:32768
	ds_read_b128 v[202:205], v153 offset:33792
	ds_read_b128 v[206:209], v153 offset:34816
	ds_read_b128 v[210:213], v153 offset:35840
	ds_read_b128 v[214:217], v153 offset:36864
	ds_read_b128 v[218:221], v153 offset:37888
	ds_read_b128 v[222:225], v153 offset:38912
	ds_read_b128 v[226:229], v153 offset:39936
	global_load_lds_dwordx4 v[230:231], off
	v_lshl_add_u64 v[230:231], s[12:13], 0, v[144:145]
	s_mov_b32 m0, s25
	s_nop 0
	global_load_lds_dwordx4 v[230:231], off
	s_waitcnt lgkmcnt(8)
	s_barrier
	s_waitcnt lgkmcnt(0)
	s_waitcnt lgkmcnt(0)
	v_mfma_f32_16x16x32_bf16 v[126:129], v[154:157], v[198:201], v[126:129]
	v_mfma_f32_16x16x32_bf16 v[122:125], v[184:187], v[198:201], v[122:125]
	v_mfma_f32_16x16x32_bf16 v[118:121], v[154:157], v[206:209], v[118:121]
	v_mfma_f32_16x16x32_bf16 v[110:113], v[184:187], v[206:209], v[110:113]
	v_mfma_f32_16x16x32_bf16 v[102:105], v[154:157], v[214:217], v[102:105]
	v_mfma_f32_16x16x32_bf16 v[94:97], v[184:187], v[214:217], v[94:97]
	v_mfma_f32_16x16x32_bf16 v[82:85], v[154:157], v[222:225], v[82:85]
	v_mfma_f32_16x16x32_bf16 v[74:77], v[184:187], v[222:225], v[74:77]
	v_mfma_f32_16x16x32_bf16 v[126:129], v[180:183], v[202:205], v[126:129]
	v_mfma_f32_16x16x32_bf16 v[122:125], v[188:191], v[202:205], v[122:125]
	v_mfma_f32_16x16x32_bf16 v[118:121], v[180:183], v[210:213], v[118:121]
	v_mfma_f32_16x16x32_bf16 v[110:113], v[188:191], v[210:213], v[110:113]
	v_mfma_f32_16x16x32_bf16 v[102:105], v[180:183], v[218:221], v[102:105]
	v_mfma_f32_16x16x32_bf16 v[94:97], v[188:191], v[218:221], v[94:97]
	v_mfma_f32_16x16x32_bf16 v[82:85], v[180:183], v[226:229], v[82:85]
	v_mfma_f32_16x16x32_bf16 v[74:77], v[188:191], v[226:229], v[74:77]
	s_barrier
	s_add_i32 s40, 0, 0x1c000
	s_add_i32 s12, s39, s20
	v_add_u32_e32 v179, s40, v151
	v_lshl_add_u64 v[148:149], v[148:149], 0, s[96:97]
	s_mov_b32 m0, s12
	ds_read_b128 v[230:233], v179
	ds_read_b128 v[234:237], v179 offset:1024
	ds_read_b128 v[238:241], v179 offset:2048
	ds_read_b128 v[242:245], v179 offset:3072
	global_load_lds_dwordx4 v[148:149], off
	v_lshl_add_u64 v[148:149], v[158:159], 0, s[96:97]
	s_add_i32 m0, s12, 0x2000
	s_nop 0
	global_load_lds_dwordx4 v[148:149], off
	s_barrier
; #define PG8_STAGE(bufoff, gbase, voff) do { _Pragma("unroll") for (int _i = 0; _i < 2; ++_i) \
;         __builtin_amdgcn_global_load_lds((const unsigned*)((const char*)(gbase) + (voff)[_i]), (LAS unsigned*)(lds + (bufoff) + ldsw + _i * 8192), 16, 0, 0); } while (0)
; #define PG8_LDA(dst, b, h) do { _Pragma("unroll") for (int m = 0; m < 4; ++m) _Pragma("unroll") for (int k = 0; k < 2; ++k) dst[m][k] = *(const LAS bf16x8*)(lds + PG8_SA(b, h) + aoff + m * 2048 + k * 1024); } while (0)
; #define PG8_MMA(ai, bj, At, Bt) do { __builtin_amdgcn_s_setprio(1); _Pragma("unroll") for (int m = 0; m < 4; ++m) _Pragma("unroll") for (int n = 0; n < 2; ++n) _Pragma("unroll") for (int k = 0; k < 2; ++k) \
;         acc[ai][bj][m][n] = __builtin_amdgcn_mfma_f32_16x16x32_bf16(Bt[n][k], At[m][k], acc[ai][bj][m][n], 0, 0, 0); __builtin_amdgcn_s_setprio(0); } while (0)
; #define PG8_WAIT_V(n) asm volatile("s_waitcnt vmcnt(" #n ")" ::: "memory")
; #define PG8_WAIT_L(n) asm volatile("s_waitcnt lgkmcnt(" #n ")" ::: "memory")
; #define PG8_BAR __builtin_amdgcn_s_barrier()
; #define PG8_SCHED __builtin_amdgcn_sched_barrier(0)
; template <class Epi, bool SEG>
; __device__ __forceinline__ void gemm_phase(LAS unsigned char* lds, const Gemm g, const StaticOrder& S, const Epi& E) {
;     ...
;             PG8_BAR; PG8_WAIT_L(0); PG8_MMA(0, 1, At, B1); PG8_BAR;
;             PG8_LDA(At, 1, 1); PG8_STAGE(PG8_SA(1, 0), a3, voffA);
;             PG8_BAR; PG8_WAIT_L(0); PG8_MMA(1, 0, At, B0); PG8_BAR; PG8_SCHED;
;             PG8_STAGE(PG8_SB(1, 1), b3 + hstepB, voffB);
;             PG8_WAIT_V(6); PG8_BAR; PG8_MMA(1, 1, At, B1); PG8_BAR;
	s_waitcnt lgkmcnt(0)
	s_waitcnt lgkmcnt(0)
	v_mfma_f32_16x16x32_bf16 v[114:117], v[230:233], v[198:201], v[114:117]
	v_mfma_f32_16x16x32_bf16 v[106:109], v[238:241], v[198:201], v[106:109]
	v_mfma_f32_16x16x32_bf16 v[98:101], v[230:233], v[206:209], v[98:101]
	v_mfma_f32_16x16x32_bf16 v[90:93], v[238:241], v[206:209], v[90:93]
	v_mfma_f32_16x16x32_bf16 v[86:89], v[230:233], v[214:217], v[86:89]
	v_mfma_f32_16x16x32_bf16 v[78:81], v[238:241], v[214:217], v[78:81]
	v_mfma_f32_16x16x32_bf16 v[70:73], v[230:233], v[222:225], v[70:73]
	v_mfma_f32_16x16x32_bf16 v[66:69], v[238:241], v[222:225], v[66:69]
	v_mfma_f32_16x16x32_bf16 v[114:117], v[234:237], v[202:205], v[114:117]
	v_mfma_f32_16x16x32_bf16 v[106:109], v[242:245], v[202:205], v[106:109]
	v_mfma_f32_16x16x32_bf16 v[98:101], v[234:237], v[210:213], v[98:101]
	v_mfma_f32_16x16x32_bf16 v[90:93], v[242:245], v[210:213], v[90:93]
	v_mfma_f32_16x16x32_bf16 v[86:89], v[234:237], v[218:221], v[86:89]
	v_mfma_f32_16x16x32_bf16 v[78:81], v[242:245], v[218:221], v[78:81]
	v_mfma_f32_16x16x32_bf16 v[70:73], v[234:237], v[226:229], v[70:73]
	v_mfma_f32_16x16x32_bf16 v[66:69], v[242:245], v[226:229], v[66:69]
	s_mov_b32 m0, s26
	v_lshl_add_u64 v[148:149], v[192:193], 0, s[96:97]
	s_barrier
	ds_read_b128 v[198:201], v153 offset:49152
	ds_read_b128 v[202:205], v153 offset:50176
	ds_read_b128 v[206:209], v153 offset:51200
	ds_read_b128 v[210:213], v153 offset:52224
	ds_read_b128 v[214:217], v153 offset:53248
	ds_read_b128 v[218:221], v153 offset:54272
	ds_read_b128 v[222:225], v153 offset:55296
	ds_read_b128 v[226:229], v153 offset:56320
	global_load_lds_dwordx4 v[148:149], off
	v_lshl_add_u64 v[148:149], v[246:247], 0, s[96:97]
	s_mov_b32 m0, s27
	s_nop 0
	global_load_lds_dwordx4 v[148:149], off
	s_barrier
	s_waitcnt lgkmcnt(0)
	s_waitcnt lgkmcnt(0)
	v_mfma_f32_16x16x32_bf16 v[62:65], v[154:157], v[198:201], v[62:65]
	v_mfma_f32_16x16x32_bf16 v[58:61], v[184:187], v[198:201], v[58:61]
	v_mfma_f32_16x16x32_bf16 v[54:57], v[154:157], v[206:209], v[54:57]
	v_mfma_f32_16x16x32_bf16 v[46:49], v[184:187], v[206:209], v[46:49]
	v_mfma_f32_16x16x32_bf16 v[38:41], v[154:157], v[214:217], v[38:41]
	v_mfma_f32_16x16x32_bf16 v[30:33], v[184:187], v[214:217], v[30:33]
	v_mfma_f32_16x16x32_bf16 v[22:25], v[154:157], v[222:225], v[22:25]
	v_mfma_f32_16x16x32_bf16 v[14:17], v[184:187], v[222:225], v[14:17]
	v_mfma_f32_16x16x32_bf16 v[62:65], v[180:183], v[202:205], v[62:65]
	v_mfma_f32_16x16x32_bf16 v[58:61], v[188:191], v[202:205], v[58:61]
	v_mfma_f32_16x16x32_bf16 v[54:57], v[180:183], v[210:213], v[54:57]
	v_mfma_f32_16x16x32_bf16 v[46:49], v[188:191], v[210:213], v[46:49]
	v_mfma_f32_16x16x32_bf16 v[38:41], v[180:183], v[218:221], v[38:41]
	v_mfma_f32_16x16x32_bf16 v[30:33], v[188:191], v[218:221], v[30:33]
	v_mfma_f32_16x16x32_bf16 v[22:25], v[180:183], v[226:229], v[22:25]
	v_mfma_f32_16x16x32_bf16 v[14:17], v[188:191], v[226:229], v[14:17]
	s_barrier
	s_add_u32 s12, s14, 0x80080
	s_addc_u32 s13, s15, 0
	s_add_i32 s14, s40, s20
	v_lshl_add_u64 v[148:149], s[12:13], 0, v[0:1]
	s_mov_b32 m0, s14
	s_nop 0
	global_load_lds_dwordx4 v[148:149], off
	v_lshl_add_u64 v[148:149], s[12:13], 0, v[146:147]
	s_add_i32 m0, s14, 0x2000
	s_nop 0
	global_load_lds_dwordx4 v[148:149], off
	s_waitcnt vmcnt(6)
	s_barrier
	v_mfma_f32_16x16x32_bf16 v[50:53], v[230:233], v[198:201], v[50:53]
	v_mfma_f32_16x16x32_bf16 v[42:45], v[238:241], v[198:201], v[42:45]
	v_mfma_f32_16x16x32_bf16 v[34:37], v[230:233], v[206:209], v[34:37]
	v_mfma_f32_16x16x32_bf16 v[26:29], v[238:241], v[206:209], v[26:29]
	v_mfma_f32_16x16x32_bf16 v[18:21], v[230:233], v[214:217], v[18:21]
	v_mfma_f32_16x16x32_bf16 v[10:13], v[238:241], v[214:217], v[10:13]
	v_mfma_f32_16x16x32_bf16 v[6:9], v[230:233], v[222:225], v[6:9]
	v_mfma_f32_16x16x32_bf16 v[2:5], v[238:241], v[222:225], v[2:5]
	v_mfma_f32_16x16x32_bf16 v[50:53], v[234:237], v[202:205], v[50:53]
	v_mfma_f32_16x16x32_bf16 v[42:45], v[242:245], v[202:205], v[42:45]
	v_mfma_f32_16x16x32_bf16 v[34:37], v[234:237], v[210:213], v[34:37]
	v_mfma_f32_16x16x32_bf16 v[26:29], v[242:245], v[210:213], v[26:29]
	v_mfma_f32_16x16x32_bf16 v[18:21], v[234:237], v[218:221], v[18:21]
	v_mfma_f32_16x16x32_bf16 v[10:13], v[242:245], v[218:221], v[10:13]
	v_mfma_f32_16x16x32_bf16 v[6:9], v[234:237], v[226:229], v[6:9]
	v_mfma_f32_16x16x32_bf16 v[2:5], v[242:245], v[226:229], v[2:5]
	s_add_i32 s12, s38, 2
	s_addk_i32 s37, 0x80
	s_add_u32 s0, s0, 0x100
	s_addc_u32 s1, s1, 0
	s_cmp_gt_u32 s38, 29
	s_mov_b32 s38, s12
	s_barrier
	s_cbranch_scc1 .LBB0_92

;     __device__ bool next(int i, Unit& u) const {
;         const long L = (long)i * G + c; if (L >= nwg) return false;
;         int wgid = (int)L; { const int q = nwg / NXCD, r = nwg % NXCD, xcd = wgid % NXCD, off = wgid / NXCD; wgid = (xcd < r ? xcd * (q + 1) : r * (q + 1) + (xcd - r) * q) + off; }
;         const int nig = WGM * nN, gid = wgid / nig, fm = gid * WGM, gsz = (nM - fm) < WGM ? (nM - fm) : WGM;
;         u.pm = fm + ((wgid % nig) % gsz); u.pn = (wgid % nig) / gsz; return true;
; template <class Epi, bool SEG>
; __device__ __forceinline__ void gemm_phase(LAS unsigned char* lds, const Gemm g, const StaticOrder& S, const Epi& E) {
;     const int tid = otid(), wid = __builtin_amdgcn_readfirstlane(tid >> 6), lane = tid & 63, wr = wid >> 2, wc = wid & 3, fr = lane & 15, fq = lane >> 4;
;     const int K = g.K, nt = K / BK, lda = g.lda;
;     unsigned voffA[2], voffB[2];
; #pragma unroll
;     for (int i = 0; i < 2; ++i) { int R, C; stage_rc(tid * 16 + i * 8192, R, C); const int Rb = Epi::PERM ? ((R & ~31) + perm32(R & 31)) : R;
;         voffA[i] = (unsigned)(R * lda + C) * 2u; voffB[i] = (unsigned)(Rb * K + C) * 2u; }
;     const size_t kstep = (size_t)(BK * 2);
;     const size_t hstepA = (size_t)HALF * lda * 2, hstepB = (size_t)HALF * K * 2;
;     const size_t tstepA = 2 * hstepA, tstepB = 2 * hstepB;
;     const unsigned ldsw = (unsigned)wid * 1024u;
;     const int aoff = lds_byte(wr * 64 + fr, fq * 8), boff = lds_byte(wc * 32 + fr, fq * 8);
;     ...
;     Unit cur, nxt; int ui = 0;
;     if (!S.next(0, cur)) return;
;     f32x4 acc[2][2][4][2];
; #pragma unroll
;     for (int a = 0; a < 2; ++a)
; #pragma unroll
;         for (int b = 0; b < 2; ++b)
; #pragma unroll
;             for (int m = 0; m < 4; ++m)
; #pragma unroll
;                 for (int n = 0; n < 2; ++n) acc[a][b][m][n] = (f32x4){0.f, 0.f, 0.f, 0.f};
;     bf16x8 At[4][2], B0[2][2], B1[2][2];
;     const char* cA = (const char*)g.A + (size_t)cur.pm * tstepA; const char* cB = (const char*)g.Bt + (size_t)cur.pn * tstepB;
;     PG8_STAGE(PG8_SB(0, 0), cB, voffB); PG8_STAGE(PG8_SA(0, 0), cA, voffA); PG8_STAGE(PG8_SB(0, 1), cB + hstepB, voffB); PG8_STAGE(PG8_SA(0, 1), cA + hstepA, voffA);
;     if (wr == 1) PG8_BAR;
;     PG8_WAIT_V(4); PG8_BAR;
;     PG8_STAGE(PG8_SB(1, 0), cB + kstep, voffB); PG8_STAGE(PG8_SA(1, 0), cA + kstep, voffA); PG8_STAGE(PG8_SB(1, 1), cB + hstepB + kstep, voffB);
.LBB0_509:
	s_and_b64 vcc, exec, s[0:1]
	s_cbranch_vccz .LBB0_522
	v_readlane_b32 s18, v253, 0
	s_waitcnt vmcnt(0)
	v_mov_b32_e32 v3, v160
	s_cmpk_gt_i32 s18, 0xe7f
	v_readfirstlane_b32 s19, v3
	s_cbranch_scc1 .LBB0_522
	v_lshlrev_b32_e32 v0, 4, v3
	v_add_u32_e32 v4, 0x2000, v0
	v_ashrrev_i32_e32 v2, 31, v4
	v_lshrrev_b32_e32 v2, 22, v2
	v_add_u32_e32 v2, v4, v2
	v_ashrrev_i32_e32 v2, 10, v2
	v_mul_i32_i24_e32 v5, 0x400, v2
	v_sub_u32_e32 v4, v4, v5
	v_lshrrev_b32_e32 v5, 4, v4
	v_bitop3_b32 v5, v5, v4, 32 bitop3:0x6c
	v_ashrrev_i32_e32 v4, 31, v5
	v_lshrrev_b32_e32 v4, 26, v4
	v_add_u32_e32 v6, v5, v4
	v_lshlrev_b32_e32 v7, 3, v2
	v_ashrrev_i32_e32 v4, 6, v6
	v_and_b32_e32 v7, -16, v7
	v_add_u32_e32 v7, v4, v7
	v_and_b32_e32 v8, 3, v4
	s_mov_b32 s0, 0xfffe0
	v_lshrrev_b32_e32 v9, 2, v7
	v_lshlrev_b32_e32 v10, 1, v7
	v_and_b32_e32 v6, 0xc0, v6
	v_and_or_b32 v8, v7, s0, v8
	v_and_b32_e32 v9, 4, v9
	v_and_b32_e32 v10, 24, v10
	v_sub_u32_e32 v5, v5, v6
	v_or3_b32 v8, v8, v9, v10
	v_lshlrev_b32_e32 v9, 5, v2
	v_ashrrev_i16_sdwa v5, v172, sext(v5) dst_sel:DWORD dst_unused:UNUSED_PAD src0_sel:DWORD src1_sel:BYTE_0
	v_and_b32_e32 v9, 32, v9
	v_bfe_i32 v5, v5, 0, 16
	v_add_lshl_u32 v6, v9, v5, 1
	v_lshl_add_u32 v142, v8, 12, v6
	v_lshl_add_u32 v144, v7, 12, v6
	v_bfe_i32 v6, v3, 27, 1
	v_lshrrev_b32_e32 v6, 22, v6
	v_add_u32_e32 v6, v0, v6
	v_and_b32_e32 v6, 0xfffffc00, v6
	v_sub_u32_e32 v0, v0, v6
	v_lshrrev_b32_e32 v6, 4, v0
	v_bitop3_b32 v8, v6, v0, 32 bitop3:0x6c
	v_ashrrev_i32_e32 v0, 31, v0
	v_lshrrev_b32_e32 v0, 26, v0
	v_add_u32_e32 v0, v8, v0
	v_ashrrev_i32_e32 v6, 6, v0
	v_ashrrev_i32_e32 v0, 31, v3
	v_lshrrev_b32_e32 v0, 26, v0
	v_add_u32_e32 v0, v3, v0
	v_ashrrev_i32_e32 v7, 6, v0
	v_lshlrev_b32_e32 v0, 3, v7
	v_and_b32_e32 v0, -16, v0
	v_add_u32_e32 v9, v6, v0
	v_and_b32_e32 v0, 3, v6
	s_ashr_i32 s21, s18, 31
	v_and_or_b32 v0, v9, s0, v0
	s_lshr_b32 s0, s21, 29
	s_add_i32 s0, s18, s0
	s_ashr_i32 s2, s19, 6
	s_ashr_i32 s3, s0, 3
	s_and_b32 s0, s0, -8
	s_ashr_i32 s1, s19, 8
	s_lshl_b32 s20, s2, 10
	s_sub_i32 s0, s18, s0
	s_cmp_lt_i32 s0, 0
	s_movk_i32 s4, 0x1d1
	s_cselect_b32 s4, s4, 0x1d0
	s_mul_i32 s0, s4, s0
	s_add_i32 s0, s0, s3
	s_mul_hi_i32 s3, s0, 0x8d3dcb09
	s_add_i32 s3, s3, s0
	s_lshr_b32 s4, s3, 31
	s_ashr_i32 s3, s3, 7
	s_add_i32 s3, s3, s4
	s_lshl_b32 s4, s3, 3
	s_mulk_i32 s3, 0xe8
	s_sub_i32 s3, s0, s3
	s_bfe_u32 s0, s3, 0x3001c
	s_add_i32 s5, s3, s0
	s_sext_i32_i16 s0, s5
	s_and_b32 s5, s5, 0xfff8
	v_lshrrev_b32_e32 v10, 2, v9
	v_lshlrev_b32_e32 v11, 1, v9
	s_sub_i32 s3, s3, s5
	v_and_b32_e32 v10, 4, v10
	v_and_b32_e32 v11, 24, v11
	s_sext_i32_i16 s3, s3
	v_or3_b32 v0, v0, v10, v11
	v_mul_i32_i24_e32 v11, 64, v6
	s_lshr_b32 s0, s0, 3
	s_add_i32 s10, s4, s3
	v_sub_u32_e32 v8, v8, v11
	s_ashr_i32 s11, s10, 31
	s_bfe_i64 s[6:7], s[0:1], 0x100000
	v_lshlrev_b32_e32 v10, 5, v7
	v_ashrrev_i16_sdwa v8, v172, sext(v8) dst_sel:DWORD dst_unused:UNUSED_PAD src0_sel:DWORD src1_sel:BYTE_0
	s_lshl_b64 s[4:5], s[10:11], 20
	s_lshl_b64 s[6:7], s[6:7], 20
	v_readlane_b32 s8, v253, 27
	v_and_b32_e32 v10, 32, v10
	v_bfe_i32 v8, v8, 0, 16
	v_readlane_b32 s9, v253, 28
	s_add_u32 s14, s8, s6
	v_add_lshl_u32 v10, v10, v8, 1
	s_addc_u32 s15, s9, s7
	s_add_i32 s11, s20, 0
	v_lshl_add_u32 v0, v0, 12, v10
	s_add_i32 m0, s11, 0x10000
	v_readlane_b32 s6, v253, 4
	global_load_lds_dwordx4 v0, s[14:15]
	s_add_i32 m0, s11, 0x12000
	v_readlane_b32 s7, v253, 5
	s_add_u32 s12, s6, s4
	v_lshl_add_u32 v146, v9, 12, v10
	global_load_lds_dwordx4 v142, s[14:15]
	s_addc_u32 s13, s7, s5
	s_mov_b32 m0, s11
	s_add_i32 s23, s11, 0x2000
	global_load_lds_dwordx4 v146, s[12:13]
	s_mov_b32 m0, s23
	s_add_u32 s4, s14, 0x80000
	global_load_lds_dwordx4 v144, s[12:13]
	s_addc_u32 s5, s15, 0
	s_add_i32 m0, s11, 0x14000
	s_nop 0
	global_load_lds_dwordx4 v0, s[4:5]
	s_add_i32 m0, s11, 0x16000
	s_nop 0
	global_load_lds_dwordx4 v142, s[4:5]
	s_add_u32 s4, s12, 0x80000
	s_addc_u32 s5, s13, 0
	s_add_i32 s24, s11, 0x4000
	s_mov_b32 m0, s24
	s_add_i32 s25, s11, 0x6000
	global_load_lds_dwordx4 v146, s[4:5]
	s_mov_b32 m0, s25
	s_cmp_lg_u32 s1, 1
	global_load_lds_dwordx4 v144, s[4:5]
	s_cbranch_scc1 .LBB0_513
	s_setprio 1
	s_barrier

; #define PG8_STAGE(bufoff, gbase, voff) do { _Pragma("unroll") for (int _i = 0; _i < 2; ++_i) \
;         __builtin_amdgcn_global_load_lds((const unsigned*)((const char*)(gbase) + (voff)[_i]), (LAS unsigned*)(lds + (bufoff) + ldsw + _i * 8192), 16, 0, 0); } while (0)
; #define PG8_LDA(dst, b, h) do { _Pragma("unroll") for (int m = 0; m < 4; ++m) _Pragma("unroll") for (int k = 0; k < 2; ++k) dst[m][k] = *(const LAS bf16x8*)(lds + PG8_SA(b, h) + aoff + m * 2048 + k * 1024); } while (0)
; #define PG8_LDB(dst, b, h) do { _Pragma("unroll") for (int n = 0; n < 2; ++n) _Pragma("unroll") for (int k = 0; k < 2; ++k) dst[n][k] = *(const LAS bf16x8*)(lds + PG8_SB(b, h) + boff + n * 2048 + k * 1024); } while (0)
; #define PG8_MMA(ai, bj, At, Bt) do { __builtin_amdgcn_s_setprio(1); _Pragma("unroll") for (int m = 0; m < 4; ++m) _Pragma("unroll") for (int n = 0; n < 2; ++n) _Pragma("unroll") for (int k = 0; k < 2; ++k) \
;         acc[ai][bj][m][n] = __builtin_amdgcn_mfma_f32_16x16x32_bf16(Bt[n][k], At[m][k], acc[ai][bj][m][n], 0, 0, 0); __builtin_amdgcn_s_setprio(0); } while (0)
; #define PG8_WAIT_L(n) asm volatile("s_waitcnt lgkmcnt(" #n ")" ::: "memory")
; #define PG8_BAR __builtin_amdgcn_s_barrier()
; #define PG8_SCHED __builtin_amdgcn_sched_barrier(0)
; template <class Epi, bool SEG>
; __device__ __forceinline__ void gemm_phase(LAS unsigned char* lds, const Gemm g, const StaticOrder& S, const Epi& E) {
;     ...
;         for (int t = 0; t < nt; t += 2) {
;             const bool last = (t == nt - 2);
;             const char* a1 = cA + akoff<SEG>(t) + kstep;
;             const char* a2 = last ? nA : cA + akoff<SEG>(t + 2); const char* b2 = last ? nB : cB + (size_t)(t + 2) * kstep;
;             const char* a3 = a2 + kstep; const char* b3 = b2 + kstep;
;             PG8_LDB(B0, 0, 0); PG8_SCHED; PG8_LDA(At, 0, 0); PG8_STAGE(PG8_SA(1, 1), a1 + hstepA, voffA);
;             PG8_WAIT_L(8); PG8_BAR; PG8_WAIT_L(0); PG8_MMA(0, 0, At, B0); PG8_BAR; PG8_SCHED;
;             PG8_LDB(B1, 0, 1); PG8_STAGE(PG8_SB(0, 0), b2, voffB);
;             PG8_BAR; PG8_WAIT_L(0); PG8_MMA(0, 1, At, B1); PG8_BAR;
;             PG8_LDA(At, 0, 1); PG8_STAGE(PG8_SA(0, 0), a2, voffA);
;             PG8_BAR; PG8_WAIT_L(0); PG8_MMA(1, 0, At, B0); PG8_BAR; PG8_SCHED;
.LBB0_517:
	s_add_u32 s14, s12, 0xfff80080
	s_addc_u32 s15, s13, -1
	s_add_i32 s37, 0, 0x10000
	v_add_u32_e32 v179, s37, v157
	ds_read_b128 v[152:155], v179
	ds_read_b128 v[180:183], v179 offset:1024
	ds_read_b128 v[184:187], v179 offset:2048
	ds_read_b128 v[188:191], v179 offset:3072
	s_cmp_eq_u32 s36, 28
	s_cselect_b32 s17, s5, s15
	s_cselect_b32 s16, s30, s14
	s_cselect_b32 s15, s1, s35
	s_cselect_b32 s14, s31, s34
	v_lshl_add_u64 v[192:193], s[12:13], 0, v[148:149]
	s_add_i32 m0, s11, 0xc000
	ds_read_b128 v[198:201], v159
	ds_read_b128 v[202:205], v159 offset:1024
	ds_read_b128 v[206:209], v159 offset:2048
	ds_read_b128 v[210:213], v159 offset:3072
	ds_read_b128 v[214:217], v159 offset:4096
	ds_read_b128 v[218:221], v159 offset:5120
	ds_read_b128 v[222:225], v159 offset:6144
	ds_read_b128 v[226:229], v159 offset:7168
	global_load_lds_dwordx4 v[192:193], off
	v_lshl_add_u64 v[192:193], s[12:13], 0, v[150:151]
	s_add_i32 m0, s11, 0xe000
	s_nop 0
	global_load_lds_dwordx4 v[192:193], off
	s_waitcnt lgkmcnt(8)
	s_barrier
	s_waitcnt lgkmcnt(0)
	s_waitcnt lgkmcnt(0)
	v_mfma_f32_16x16x32_bf16 v[126:129], v[152:155], v[198:201], v[126:129]
	v_mfma_f32_16x16x32_bf16 v[122:125], v[184:187], v[198:201], v[122:125]
	v_mfma_f32_16x16x32_bf16 v[118:121], v[152:155], v[206:209], v[118:121]
	v_mfma_f32_16x16x32_bf16 v[110:113], v[184:187], v[206:209], v[110:113]
	v_mfma_f32_16x16x32_bf16 v[102:105], v[152:155], v[214:217], v[102:105]
	v_mfma_f32_16x16x32_bf16 v[94:97], v[184:187], v[214:217], v[94:97]
	v_mfma_f32_16x16x32_bf16 v[86:89], v[152:155], v[222:225], v[86:89]
	v_mfma_f32_16x16x32_bf16 v[78:81], v[184:187], v[222:225], v[78:81]
	v_mfma_f32_16x16x32_bf16 v[126:129], v[180:183], v[202:205], v[126:129]
	v_mfma_f32_16x16x32_bf16 v[122:125], v[188:191], v[202:205], v[122:125]
	v_mfma_f32_16x16x32_bf16 v[118:121], v[180:183], v[210:213], v[118:121]
	v_mfma_f32_16x16x32_bf16 v[110:113], v[188:191], v[210:213], v[110:113]
	v_mfma_f32_16x16x32_bf16 v[102:105], v[180:183], v[218:221], v[102:105]
	v_mfma_f32_16x16x32_bf16 v[94:97], v[188:191], v[218:221], v[94:97]
	v_mfma_f32_16x16x32_bf16 v[86:89], v[180:183], v[226:229], v[86:89]
	v_mfma_f32_16x16x32_bf16 v[78:81], v[188:191], v[226:229], v[78:81]
	s_barrier
	s_add_i32 s40, 0, 0x14000
	s_add_i32 s37, s37, s20
	v_add_u32_e32 v179, s40, v157
	v_lshl_add_u64 v[192:193], s[14:15], 0, v[0:1]
	s_mov_b32 m0, s37
	ds_read_b128 v[230:233], v179
	ds_read_b128 v[234:237], v179 offset:1024
	ds_read_b128 v[238:241], v179 offset:2048
	ds_read_b128 v[242:245], v179 offset:3072
	global_load_lds_dwordx4 v[192:193], off
	v_lshl_add_u64 v[246:247], s[14:15], 0, v[142:143]
	s_add_i32 m0, s37, 0x2000
	s_nop 0
	global_load_lds_dwordx4 v[246:247], off
	s_barrier
	s_waitcnt lgkmcnt(0)
	s_waitcnt lgkmcnt(0)
	v_mfma_f32_16x16x32_bf16 v[114:117], v[230:233], v[198:201], v[114:117]
	v_mfma_f32_16x16x32_bf16 v[106:109], v[238:241], v[198:201], v[106:109]
	v_mfma_f32_16x16x32_bf16 v[98:101], v[230:233], v[206:209], v[98:101]
	v_mfma_f32_16x16x32_bf16 v[90:93], v[238:241], v[206:209], v[90:93]
	v_mfma_f32_16x16x32_bf16 v[82:85], v[230:233], v[214:217], v[82:85]
	v_mfma_f32_16x16x32_bf16 v[74:77], v[238:241], v[214:217], v[74:77]
	v_mfma_f32_16x16x32_bf16 v[70:73], v[230:233], v[222:225], v[70:73]
	v_mfma_f32_16x16x32_bf16 v[66:69], v[238:241], v[222:225], v[66:69]
	v_mfma_f32_16x16x32_bf16 v[114:117], v[234:237], v[202:205], v[114:117]
	v_mfma_f32_16x16x32_bf16 v[106:109], v[242:245], v[202:205], v[106:109]
	v_mfma_f32_16x16x32_bf16 v[98:101], v[234:237], v[210:213], v[98:101]
	v_mfma_f32_16x16x32_bf16 v[90:93], v[242:245], v[210:213], v[90:93]
	v_mfma_f32_16x16x32_bf16 v[82:85], v[234:237], v[218:221], v[82:85]
	v_mfma_f32_16x16x32_bf16 v[74:77], v[242:245], v[218:221], v[74:77]
	v_mfma_f32_16x16x32_bf16 v[70:73], v[234:237], v[226:229], v[70:73]
	v_mfma_f32_16x16x32_bf16 v[66:69], v[242:245], v[226:229], v[66:69]
	s_mov_b32 m0, s11
	v_lshl_add_u64 v[248:249], s[16:17], 0, v[146:147]
	s_barrier
	ds_read_b128 v[198:201], v159 offset:16384
	ds_read_b128 v[202:205], v159 offset:17408
	ds_read_b128 v[206:209], v159 offset:18432
	ds_read_b128 v[210:213], v159 offset:19456
	ds_read_b128 v[214:217], v159 offset:20480
	ds_read_b128 v[218:221], v159 offset:21504
	ds_read_b128 v[222:225], v159 offset:22528
	ds_read_b128 v[226:229], v159 offset:23552
	global_load_lds_dwordx4 v[248:249], off
	v_lshl_add_u64 v[250:251], s[16:17], 0, v[144:145]
	s_mov_b32 m0, s23
	s_nop 0
	global_load_lds_dwordx4 v[250:251], off
	s_barrier
	s_waitcnt lgkmcnt(0)
	s_waitcnt lgkmcnt(0)
	v_mfma_f32_16x16x32_bf16 v[62:65], v[152:155], v[198:201], v[62:65]
	v_mfma_f32_16x16x32_bf16 v[58:61], v[184:187], v[198:201], v[58:61]
	v_mfma_f32_16x16x32_bf16 v[54:57], v[152:155], v[206:209], v[54:57]
	v_mfma_f32_16x16x32_bf16 v[46:49], v[184:187], v[206:209], v[46:49]
	v_mfma_f32_16x16x32_bf16 v[38:41], v[152:155], v[214:217], v[38:41]
	v_mfma_f32_16x16x32_bf16 v[30:33], v[184:187], v[214:217], v[30:33]
	v_mfma_f32_16x16x32_bf16 v[22:25], v[152:155], v[222:225], v[22:25]
	v_mfma_f32_16x16x32_bf16 v[14:17], v[184:187], v[222:225], v[14:17]
	v_mfma_f32_16x16x32_bf16 v[62:65], v[180:183], v[202:205], v[62:65]
	v_mfma_f32_16x16x32_bf16 v[58:61], v[188:191], v[202:205], v[58:61]
	v_mfma_f32_16x16x32_bf16 v[54:57], v[180:183], v[210:213], v[54:57]
	v_mfma_f32_16x16x32_bf16 v[46:49], v[188:191], v[210:213], v[46:49]
	v_mfma_f32_16x16x32_bf16 v[38:41], v[180:183], v[218:221], v[38:41]
	v_mfma_f32_16x16x32_bf16 v[30:33], v[188:191], v[218:221], v[30:33]
	v_mfma_f32_16x16x32_bf16 v[22:25], v[180:183], v[226:229], v[22:25]
	v_mfma_f32_16x16x32_bf16 v[14:17], v[188:191], v[226:229], v[14:17]
	s_barrier
; #define PG8_STAGE(bufoff, gbase, voff) do { _Pragma("unroll") for (int _i = 0; _i < 2; ++_i) \
;         __builtin_amdgcn_global_load_lds((const unsigned*)((const char*)(gbase) + (voff)[_i]), (LAS unsigned*)(lds + (bufoff) + ldsw + _i * 8192), 16, 0, 0); } while (0)
; #define PG8_LDA(dst, b, h) do { _Pragma("unroll") for (int m = 0; m < 4; ++m) _Pragma("unroll") for (int k = 0; k < 2; ++k) dst[m][k] = *(const LAS bf16x8*)(lds + PG8_SA(b, h) + aoff + m * 2048 + k * 1024); } while (0)
; #define PG8_LDB(dst, b, h) do { _Pragma("unroll") for (int n = 0; n < 2; ++n) _Pragma("unroll") for (int k = 0; k < 2; ++k) dst[n][k] = *(const LAS bf16x8*)(lds + PG8_SB(b, h) + boff + n * 2048 + k * 1024); } while (0)
; #define PG8_MMA(ai, bj, At, Bt) do { __builtin_amdgcn_s_setprio(1); _Pragma("unroll") for (int m = 0; m < 4; ++m) _Pragma("unroll") for (int n = 0; n < 2; ++n) _Pragma("unroll") for (int k = 0; k < 2; ++k) \
;         acc[ai][bj][m][n] = __builtin_amdgcn_mfma_f32_16x16x32_bf16(Bt[n][k], At[m][k], acc[ai][bj][m][n], 0, 0, 0); __builtin_amdgcn_s_setprio(0); } while (0)
; #define PG8_WAIT_V(n) asm volatile("s_waitcnt vmcnt(" #n ")" ::: "memory")
; #define PG8_WAIT_L(n) asm volatile("s_waitcnt lgkmcnt(" #n ")" ::: "memory")
; #define PG8_BAR __builtin_amdgcn_s_barrier()
; #define PG8_SCHED __builtin_amdgcn_sched_barrier(0)
; template <class Epi, bool SEG>
; __device__ __forceinline__ void gemm_phase(LAS unsigned char* lds, const Gemm g, const StaticOrder& S, const Epi& E) {
;     ...
;             PG8_STAGE(PG8_SB(0, 1), b2 + hstepB, voffB);
;             PG8_WAIT_V(6); PG8_BAR; PG8_MMA(1, 1, At, B1); PG8_BAR;
;             PG8_LDB(B0, 1, 0); PG8_SCHED; PG8_LDA(At, 1, 0); PG8_STAGE(PG8_SA(0, 1), a2 + hstepA, voffA);
;             PG8_WAIT_L(8); PG8_BAR; PG8_WAIT_L(0); PG8_MMA(0, 0, At, B0); PG8_BAR; PG8_SCHED;
;             PG8_LDB(B1, 1, 1); PG8_STAGE(PG8_SB(1, 0), b3, voffB);
;             PG8_BAR; PG8_WAIT_L(0); PG8_MMA(0, 1, At, B1); PG8_BAR;
;             PG8_LDA(At, 1, 1); PG8_STAGE(PG8_SA(1, 0), a3, voffA);
;             PG8_BAR; PG8_WAIT_L(0); PG8_MMA(1, 0, At, B0); PG8_BAR; PG8_SCHED;
	s_add_u32 s38, s14, 0x80000
	s_addc_u32 s39, s15, 0
	s_add_i32 s37, s40, s20
	v_lshl_add_u64 v[152:153], s[38:39], 0, v[0:1]
	s_mov_b32 m0, s37
	s_nop 0
	global_load_lds_dwordx4 v[152:153], off
	v_lshl_add_u64 v[152:153], s[38:39], 0, v[142:143]
	s_add_i32 m0, s37, 0x2000
	s_nop 0
	global_load_lds_dwordx4 v[152:153], off
	s_waitcnt vmcnt(6)
	s_barrier
	v_mfma_f32_16x16x32_bf16 v[50:53], v[230:233], v[198:201], v[50:53]
	v_mfma_f32_16x16x32_bf16 v[42:45], v[238:241], v[198:201], v[42:45]
	v_mfma_f32_16x16x32_bf16 v[34:37], v[230:233], v[206:209], v[34:37]
	v_mfma_f32_16x16x32_bf16 v[26:29], v[238:241], v[206:209], v[26:29]
	v_mfma_f32_16x16x32_bf16 v[18:21], v[230:233], v[214:217], v[18:21]
	v_mfma_f32_16x16x32_bf16 v[10:13], v[238:241], v[214:217], v[10:13]
	v_mfma_f32_16x16x32_bf16 v[6:9], v[230:233], v[222:225], v[6:9]
	v_mfma_f32_16x16x32_bf16 v[2:5], v[238:241], v[222:225], v[2:5]
	v_mfma_f32_16x16x32_bf16 v[50:53], v[234:237], v[202:205], v[50:53]
	v_mfma_f32_16x16x32_bf16 v[42:45], v[242:245], v[202:205], v[42:45]
	v_mfma_f32_16x16x32_bf16 v[34:37], v[234:237], v[210:213], v[34:37]
	v_mfma_f32_16x16x32_bf16 v[26:29], v[242:245], v[210:213], v[26:29]
	v_mfma_f32_16x16x32_bf16 v[18:21], v[234:237], v[218:221], v[18:21]
	v_mfma_f32_16x16x32_bf16 v[10:13], v[242:245], v[218:221], v[10:13]
	v_mfma_f32_16x16x32_bf16 v[6:9], v[234:237], v[226:229], v[6:9]
	v_mfma_f32_16x16x32_bf16 v[2:5], v[242:245], v[226:229], v[2:5]
	s_add_i32 s37, 0, 0x18000
	v_add_u32_e32 v179, s37, v157
	s_barrier
	ds_read_b128 v[152:155], v179
	ds_read_b128 v[180:183], v179 offset:1024
	ds_read_b128 v[184:187], v179 offset:2048
	ds_read_b128 v[188:191], v179 offset:3072
	s_add_u32 s16, s16, 0x80000
	s_addc_u32 s17, s17, 0
	s_mov_b32 m0, s24
	v_lshl_add_u64 v[230:231], s[16:17], 0, v[146:147]
	ds_read_b128 v[198:201], v159 offset:32768
	ds_read_b128 v[202:205], v159 offset:33792
	ds_read_b128 v[206:209], v159 offset:34816
	ds_read_b128 v[210:213], v159 offset:35840
	ds_read_b128 v[214:217], v159 offset:36864
	ds_read_b128 v[218:221], v159 offset:37888
	ds_read_b128 v[222:225], v159 offset:38912
	ds_read_b128 v[226:229], v159 offset:39936
	global_load_lds_dwordx4 v[230:231], off
	v_lshl_add_u64 v[230:231], s[16:17], 0, v[144:145]
	s_mov_b32 m0, s25
	s_nop 0
	global_load_lds_dwordx4 v[230:231], off
	s_waitcnt lgkmcnt(8)
	s_barrier
	s_waitcnt lgkmcnt(0)
	s_waitcnt lgkmcnt(0)
	v_mfma_f32_16x16x32_bf16 v[126:129], v[152:155], v[198:201], v[126:129]
	v_mfma_f32_16x16x32_bf16 v[122:125], v[184:187], v[198:201], v[122:125]
	v_mfma_f32_16x16x32_bf16 v[118:121], v[152:155], v[206:209], v[118:121]
	v_mfma_f32_16x16x32_bf16 v[110:113], v[184:187], v[206:209], v[110:113]
	v_mfma_f32_16x16x32_bf16 v[102:105], v[152:155], v[214:217], v[102:105]
	v_mfma_f32_16x16x32_bf16 v[94:97], v[184:187], v[214:217], v[94:97]
	v_mfma_f32_16x16x32_bf16 v[86:89], v[152:155], v[222:225], v[86:89]
	v_mfma_f32_16x16x32_bf16 v[78:81], v[184:187], v[222:225], v[78:81]
	v_mfma_f32_16x16x32_bf16 v[126:129], v[180:183], v[202:205], v[126:129]
	v_mfma_f32_16x16x32_bf16 v[122:125], v[188:191], v[202:205], v[122:125]
	v_mfma_f32_16x16x32_bf16 v[118:121], v[180:183], v[210:213], v[118:121]
	v_mfma_f32_16x16x32_bf16 v[110:113], v[188:191], v[210:213], v[110:113]
	v_mfma_f32_16x16x32_bf16 v[102:105], v[180:183], v[218:221], v[102:105]
	v_mfma_f32_16x16x32_bf16 v[94:97], v[188:191], v[218:221], v[94:97]
	v_mfma_f32_16x16x32_bf16 v[86:89], v[180:183], v[226:229], v[86:89]
	v_mfma_f32_16x16x32_bf16 v[78:81], v[188:191], v[226:229], v[78:81]
	s_barrier
	s_add_i32 s16, 0, 0x1c000
	s_add_i32 s17, s37, s20
	v_add_u32_e32 v179, s16, v157
	v_lshl_add_u64 v[192:193], v[192:193], 0, s[96:97]
	s_mov_b32 m0, s17
	ds_read_b128 v[230:233], v179
	ds_read_b128 v[234:237], v179 offset:1024
	ds_read_b128 v[238:241], v179 offset:2048
	ds_read_b128 v[242:245], v179 offset:3072
	global_load_lds_dwordx4 v[192:193], off
	v_lshl_add_u64 v[192:193], v[246:247], 0, s[96:97]
	s_add_i32 m0, s17, 0x2000
	s_nop 0
	global_load_lds_dwordx4 v[192:193], off
	s_barrier
	s_waitcnt lgkmcnt(0)
	s_waitcnt lgkmcnt(0)
	v_mfma_f32_16x16x32_bf16 v[114:117], v[230:233], v[198:201], v[114:117]
	v_mfma_f32_16x16x32_bf16 v[106:109], v[238:241], v[198:201], v[106:109]
	v_mfma_f32_16x16x32_bf16 v[98:101], v[230:233], v[206:209], v[98:101]
	v_mfma_f32_16x16x32_bf16 v[90:93], v[238:241], v[206:209], v[90:93]
	v_mfma_f32_16x16x32_bf16 v[82:85], v[230:233], v[214:217], v[82:85]
	v_mfma_f32_16x16x32_bf16 v[74:77], v[238:241], v[214:217], v[74:77]
	v_mfma_f32_16x16x32_bf16 v[70:73], v[230:233], v[222:225], v[70:73]
	v_mfma_f32_16x16x32_bf16 v[66:69], v[238:241], v[222:225], v[66:69]
	v_mfma_f32_16x16x32_bf16 v[114:117], v[234:237], v[202:205], v[114:117]
	v_mfma_f32_16x16x32_bf16 v[106:109], v[242:245], v[202:205], v[106:109]
	v_mfma_f32_16x16x32_bf16 v[98:101], v[234:237], v[210:213], v[98:101]
	v_mfma_f32_16x16x32_bf16 v[90:93], v[242:245], v[210:213], v[90:93]
	v_mfma_f32_16x16x32_bf16 v[82:85], v[234:237], v[218:221], v[82:85]
	v_mfma_f32_16x16x32_bf16 v[74:77], v[242:245], v[218:221], v[74:77]
	v_mfma_f32_16x16x32_bf16 v[70:73], v[234:237], v[226:229], v[70:73]
	v_mfma_f32_16x16x32_bf16 v[66:69], v[242:245], v[226:229], v[66:69]
	s_mov_b32 m0, s26
	v_lshl_add_u64 v[192:193], v[248:249], 0, s[96:97]
	s_barrier
	ds_read_b128 v[198:201], v159 offset:49152
	ds_read_b128 v[202:205], v159 offset:50176
	ds_read_b128 v[206:209], v159 offset:51200
	ds_read_b128 v[210:213], v159 offset:52224
	ds_read_b128 v[214:217], v159 offset:53248
	ds_read_b128 v[218:221], v159 offset:54272
	ds_read_b128 v[222:225], v159 offset:55296
	ds_read_b128 v[226:229], v159 offset:56320
	global_load_lds_dwordx4 v[192:193], off
	v_lshl_add_u64 v[192:193], v[250:251], 0, s[96:97]
	s_mov_b32 m0, s27
	s_nop 0
	global_load_lds_dwordx4 v[192:193], off
	s_barrier
; #define PG8_STAGE(bufoff, gbase, voff) do { _Pragma("unroll") for (int _i = 0; _i < 2; ++_i) \
;         __builtin_amdgcn_global_load_lds((const unsigned*)((const char*)(gbase) + (voff)[_i]), (LAS unsigned*)(lds + (bufoff) + ldsw + _i * 8192), 16, 0, 0); } while (0)
; #define PG8_LDA(dst, b, h) do { _Pragma("unroll") for (int m = 0; m < 4; ++m) _Pragma("unroll") for (int k = 0; k < 2; ++k) dst[m][k] = *(const LAS bf16x8*)(lds + PG8_SA(b, h) + aoff + m * 2048 + k * 1024); } while (0)
; #define PG8_MMA(ai, bj, At, Bt) do { __builtin_amdgcn_s_setprio(1); _Pragma("unroll") for (int m = 0; m < 4; ++m) _Pragma("unroll") for (int n = 0; n < 2; ++n) _Pragma("unroll") for (int k = 0; k < 2; ++k) \
;         acc[ai][bj][m][n] = __builtin_amdgcn_mfma_f32_16x16x32_bf16(Bt[n][k], At[m][k], acc[ai][bj][m][n], 0, 0, 0); __builtin_amdgcn_s_setprio(0); } while (0)
; #define PG8_WAIT_V(n) asm volatile("s_waitcnt vmcnt(" #n ")" ::: "memory")
; #define PG8_WAIT_L(n) asm volatile("s_waitcnt lgkmcnt(" #n ")" ::: "memory")
; #define PG8_BAR __builtin_amdgcn_s_barrier()
; #define PG8_SCHED __builtin_amdgcn_sched_barrier(0)
; template <class Epi, bool SEG>
; __device__ __forceinline__ void gemm_phase(LAS unsigned char* lds, const Gemm g, const StaticOrder& S, const Epi& E) {
;     ...
;             PG8_BAR; PG8_WAIT_L(0); PG8_MMA(0, 1, At, B1); PG8_BAR;
;             PG8_LDA(At, 1, 1); PG8_STAGE(PG8_SA(1, 0), a3, voffA);
;             PG8_BAR; PG8_WAIT_L(0); PG8_MMA(1, 0, At, B0); PG8_BAR; PG8_SCHED;
;             PG8_STAGE(PG8_SB(1, 1), b3 + hstepB, voffB);
;             PG8_WAIT_V(6); PG8_BAR; PG8_MMA(1, 1, At, B1); PG8_BAR;
	s_waitcnt lgkmcnt(0)
	s_waitcnt lgkmcnt(0)
	v_mfma_f32_16x16x32_bf16 v[62:65], v[152:155], v[198:201], v[62:65]
	v_mfma_f32_16x16x32_bf16 v[58:61], v[184:187], v[198:201], v[58:61]
	v_mfma_f32_16x16x32_bf16 v[54:57], v[152:155], v[206:209], v[54:57]
	v_mfma_f32_16x16x32_bf16 v[46:49], v[184:187], v[206:209], v[46:49]
	v_mfma_f32_16x16x32_bf16 v[38:41], v[152:155], v[214:217], v[38:41]
	v_mfma_f32_16x16x32_bf16 v[30:33], v[184:187], v[214:217], v[30:33]
	v_mfma_f32_16x16x32_bf16 v[22:25], v[152:155], v[222:225], v[22:25]
	v_mfma_f32_16x16x32_bf16 v[14:17], v[184:187], v[222:225], v[14:17]
	v_mfma_f32_16x16x32_bf16 v[62:65], v[180:183], v[202:205], v[62:65]
	v_mfma_f32_16x16x32_bf16 v[58:61], v[188:191], v[202:205], v[58:61]
	v_mfma_f32_16x16x32_bf16 v[54:57], v[180:183], v[210:213], v[54:57]
	v_mfma_f32_16x16x32_bf16 v[46:49], v[188:191], v[210:213], v[46:49]
	v_mfma_f32_16x16x32_bf16 v[38:41], v[180:183], v[218:221], v[38:41]
	v_mfma_f32_16x16x32_bf16 v[30:33], v[188:191], v[218:221], v[30:33]
	v_mfma_f32_16x16x32_bf16 v[22:25], v[180:183], v[226:229], v[22:25]
	v_mfma_f32_16x16x32_bf16 v[14:17], v[188:191], v[226:229], v[14:17]
	s_barrier
	s_add_u32 s14, s14, 0x80080
	s_addc_u32 s15, s15, 0
	s_add_i32 s16, s16, s20
	v_lshl_add_u64 v[152:153], s[14:15], 0, v[0:1]
	s_mov_b32 m0, s16
	s_nop 0
	global_load_lds_dwordx4 v[152:153], off
	v_lshl_add_u64 v[152:153], s[14:15], 0, v[142:143]
	s_add_i32 m0, s16, 0x2000
	s_nop 0
	global_load_lds_dwordx4 v[152:153], off
	s_waitcnt vmcnt(6)
	s_barrier
	v_mfma_f32_16x16x32_bf16 v[50:53], v[230:233], v[198:201], v[50:53]
	v_mfma_f32_16x16x32_bf16 v[42:45], v[238:241], v[198:201], v[42:45]
	v_mfma_f32_16x16x32_bf16 v[34:37], v[230:233], v[206:209], v[34:37]
	v_mfma_f32_16x16x32_bf16 v[26:29], v[238:241], v[206:209], v[26:29]
	v_mfma_f32_16x16x32_bf16 v[18:21], v[230:233], v[214:217], v[18:21]
	v_mfma_f32_16x16x32_bf16 v[10:13], v[238:241], v[214:217], v[10:13]
	v_mfma_f32_16x16x32_bf16 v[6:9], v[230:233], v[222:225], v[6:9]
	v_mfma_f32_16x16x32_bf16 v[2:5], v[238:241], v[222:225], v[2:5]
	v_mfma_f32_16x16x32_bf16 v[50:53], v[234:237], v[202:205], v[50:53]
	v_mfma_f32_16x16x32_bf16 v[42:45], v[242:245], v[202:205], v[42:45]
	v_mfma_f32_16x16x32_bf16 v[34:37], v[234:237], v[210:213], v[34:37]
	v_mfma_f32_16x16x32_bf16 v[26:29], v[242:245], v[210:213], v[26:29]
	v_mfma_f32_16x16x32_bf16 v[18:21], v[234:237], v[218:221], v[18:21]
	v_mfma_f32_16x16x32_bf16 v[10:13], v[242:245], v[218:221], v[10:13]
	v_mfma_f32_16x16x32_bf16 v[6:9], v[234:237], v[226:229], v[6:9]
	v_mfma_f32_16x16x32_bf16 v[2:5], v[242:245], v[226:229], v[2:5]
	s_add_i32 s36, s36, 2
	s_add_u32 s12, s12, 0x100
	s_addc_u32 s13, s13, 0
	s_add_u32 s34, s34, 0x100
	s_addc_u32 s35, s35, 0
	s_cmp_gt_u32 s36, 29
	s_barrier
	s_cbranch_scc0 .LBB0_517
; __device__ __forceinline__ unsigned cvt_pk_bf16(float lo, float hi) { unsigned r; asm("v_cvt_pk_bf16_f32 %0, %1, %2" : "=v"(r) : "v"(lo), "v"(hi)); return r; }
; #define PG8_WAIT_V(n) asm volatile("s_waitcnt vmcnt(" #n ")" ::: "memory")
; #define PG8_BAR __builtin_amdgcn_s_barrier()
;     __device__ __forceinline__ void operator()(const f32x4 (&acc)[2][2][4][2], const Unit& u, int wr, int wc, int fr, int fq) const {
;         const int row0 = u.pm * BM + wr * 64 + fr, col0 = u.pn * BM + wc * 32 + 8 * fq;
; #pragma unroll
;         for (int ai = 0; ai < 2; ++ai)
; #pragma unroll
;             for (int m = 0; m < 4; ++m) { bf16_t* rowp = O + (size_t)(row0 + ai * HALF + m * 16) * ldc + col0;
; #pragma unroll
;                 for (int bj = 0; bj < 2; ++bj) { f32x4 v0 = acc[ai][bj][m][0], v1 = acc[ai][bj][m][1];
;                     if (ACT == 1) {
; #pragma unroll
;                         for (int j = 0; j < 4; ++j) { const float a = fmaxf(v0[j], 0.f), b = fmaxf(v1[j], 0.f); v0[j] = a * a; v1[j] = b * b; } }
;                     u32x4 w; w.x = cvt_pk_bf16(v0[0], v0[1]); w.y = cvt_pk_bf16(v0[2], v0[3]); w.z = cvt_pk_bf16(v1[0], v1[1]); w.w = cvt_pk_bf16(v1[2], v1[3]);
;                     *(u32x4*)(rowp + bj * HALF) = w; } }
; template <class Epi, bool SEG>
; __device__ __forceinline__ void gemm_phase(LAS unsigned char* lds, const Gemm g, const StaticOrder& S, const Epi& E) {
;     ...
;         E(acc, cur, wr, wc, fr, fq);
;         if (!has_next) break;
; #pragma unroll
;         for (int a = 0; a < 2; ++a)
; #pragma unroll
;             for (int b = 0; b < 2; ++b)
; #pragma unroll
;                 for (int m = 0; m < 4; ++m)
; #pragma unroll
;                     for (int n = 0; n < 2; ++n) acc[a][b][m][n] = (f32x4){0.f, 0.f, 0.f, 0.f};
;         cur = nxt; cA = nA; cB = nB; ++ui;
;     }
;     PG8_WAIT_V(0);
;     if (wr == 0) PG8_BAR;
;     PG8_BAR;
	v_lshl_add_u32 v179, s10, 8, v156
	v_lshl_or_b32 v154, s29, 8, v158
	v_ashrrev_i32_e32 v155, 31, v154
	v_mov_b64_e32 v[152:153], s[78:79]
	v_cvt_pk_bf16_f32 v70, v70, v71
	v_cvt_pk_bf16_f32 v71, v72, v73
	v_cvt_pk_bf16_f32 v72, v66, v67
	v_add_u32_e32 v66, 0x80, v179
	v_mad_i64_i32 v[180:181], s[12:13], v179, s22, v[152:153]
	v_lshlrev_b64 v[154:155], 1, v[154:155]
	v_cvt_pk_bf16_f32 v114, v114, v115
	v_cvt_pk_bf16_f32 v115, v116, v117
	v_cvt_pk_bf16_f32 v116, v106, v107
	v_or_b32_e32 v106, 16, v179
	v_mad_i64_i32 v[66:67], s[12:13], v66, s22, v[152:153]
	v_cvt_pk_bf16_f32 v50, v50, v51
	v_cvt_pk_bf16_f32 v51, v52, v53
	v_cvt_pk_bf16_f32 v52, v42, v43
	v_add_u32_e32 v42, 0x90, v179
	v_lshl_add_u64 v[180:181], v[180:181], 0, v[154:155]
	v_mad_i64_i32 v[106:107], s[12:13], v106, s22, v[152:153]
	v_cvt_pk_bf16_f32 v98, v98, v99
	v_cvt_pk_bf16_f32 v99, v100, v101
	v_cvt_pk_bf16_f32 v100, v90, v91
	v_or_b32_e32 v90, 32, v179
	v_lshl_add_u64 v[66:67], v[66:67], 0, v[154:155]
	v_mad_i64_i32 v[42:43], s[12:13], v42, s22, v[152:153]
	v_cvt_pk_bf16_f32 v34, v34, v35
	v_cvt_pk_bf16_f32 v35, v36, v37
	v_cvt_pk_bf16_f32 v36, v26, v27
	v_add_u32_e32 v26, 0xa0, v179
	v_cvt_pk_bf16_f32 v117, v108, v109
	global_store_dwordx4 v[180:181], v[114:117], off offset:256
	v_mad_i64_i32 v[90:91], s[12:13], v90, s22, v[152:153]
	s_nop 0
	v_lshl_add_u64 v[114:115], v[106:107], 0, v[154:155]
	v_cvt_pk_bf16_f32 v82, v82, v83
	v_cvt_pk_bf16_f32 v83, v84, v85
	v_cvt_pk_bf16_f32 v84, v74, v75
	v_or_b32_e32 v74, 48, v179
	v_cvt_pk_bf16_f32 v53, v44, v45
	global_store_dwordx4 v[66:67], v[50:53], off offset:256
	v_mad_i64_i32 v[26:27], s[12:13], v26, s22, v[152:153]
	s_nop 0
	v_lshl_add_u64 v[50:51], v[42:43], 0, v[154:155]
	v_cvt_pk_bf16_f32 v18, v18, v19
	v_cvt_pk_bf16_f32 v19, v20, v21
	v_cvt_pk_bf16_f32 v20, v10, v11
	v_add_u32_e32 v10, 0xb0, v179
	v_cvt_pk_bf16_f32 v101, v92, v93
	global_store_dwordx4 v[114:115], v[98:101], off offset:256
	v_mad_i64_i32 v[74:75], s[12:13], v74, s22, v[152:153]
	s_nop 0
	v_lshl_add_u64 v[98:99], v[90:91], 0, v[154:155]
	v_cvt_pk_bf16_f32 v37, v28, v29
	global_store_dwordx4 v[50:51], v[34:37], off offset:256
	v_mad_i64_i32 v[10:11], s[12:13], v10, s22, v[152:153]
	s_nop 0
	v_lshl_add_u64 v[34:35], v[26:27], 0, v[154:155]
	v_cvt_pk_bf16_f32 v85, v76, v77
	global_store_dwordx4 v[98:99], v[82:85], off offset:256
	v_cvt_pk_bf16_f32 v21, v12, v13
	global_store_dwordx4 v[34:35], v[18:21], off offset:256
	s_and_b64 vcc, exec, s[2:3]
	v_lshl_add_u64 v[82:83], v[74:75], 0, v[154:155]
	v_lshl_add_u64 v[18:19], v[10:11], 0, v[154:155]
	s_mov_b32 s29, s0
	s_mov_b32 s10, s4
	s_mov_b64 s[14:15], s[8:9]
	s_mov_b64 s[12:13], s[6:7]
	v_cvt_pk_bf16_f32 v126, v126, v127
	v_cvt_pk_bf16_f32 v127, v128, v129
	v_cvt_pk_bf16_f32 v128, v122, v123
	v_cvt_pk_bf16_f32 v129, v124, v125
	global_store_dwordx4 v[180:181], v[126:129], off
	v_cvt_pk_bf16_f32 v106, v118, v119
	v_cvt_pk_bf16_f32 v107, v120, v121
	v_cvt_pk_bf16_f32 v108, v110, v111
	v_cvt_pk_bf16_f32 v109, v112, v113
	global_store_dwordx4 v[114:115], v[106:109], off
	v_cvt_pk_bf16_f32 v90, v102, v103
	v_cvt_pk_bf16_f32 v91, v104, v105
	v_cvt_pk_bf16_f32 v92, v94, v95
	v_cvt_pk_bf16_f32 v93, v96, v97
	global_store_dwordx4 v[98:99], v[90:93], off
	v_cvt_pk_bf16_f32 v74, v86, v87
	v_cvt_pk_bf16_f32 v75, v88, v89
	v_cvt_pk_bf16_f32 v76, v78, v79
	v_cvt_pk_bf16_f32 v77, v80, v81
	global_store_dwordx4 v[82:83], v[74:77], off
	v_cvt_pk_bf16_f32 v73, v68, v69
	global_store_dwordx4 v[82:83], v[70:73], off offset:256
	v_cvt_pk_bf16_f32 v62, v62, v63
	v_cvt_pk_bf16_f32 v63, v64, v65
	v_cvt_pk_bf16_f32 v64, v58, v59
	v_cvt_pk_bf16_f32 v65, v60, v61
	global_store_dwordx4 v[66:67], v[62:65], off
	v_cvt_pk_bf16_f32 v42, v54, v55
	v_cvt_pk_bf16_f32 v43, v56, v57
	v_cvt_pk_bf16_f32 v44, v46, v47
	v_cvt_pk_bf16_f32 v45, v48, v49
	global_store_dwordx4 v[50:51], v[42:45], off
	v_cvt_pk_bf16_f32 v26, v38, v39
	v_cvt_pk_bf16_f32 v27, v40, v41
	v_cvt_pk_bf16_f32 v28, v30, v31
	v_cvt_pk_bf16_f32 v29, v32, v33
	global_store_dwordx4 v[34:35], v[26:29], off
	v_cvt_pk_bf16_f32 v10, v22, v23
	v_cvt_pk_bf16_f32 v11, v24, v25
	v_cvt_pk_bf16_f32 v12, v14, v15
	v_cvt_pk_bf16_f32 v13, v16, v17
	global_store_dwordx4 v[18:19], v[10:13], off
	v_cvt_pk_bf16_f32 v6, v6, v7
	v_cvt_pk_bf16_f32 v7, v8, v9
	v_cvt_pk_bf16_f32 v8, v2, v3
	v_cvt_pk_bf16_f32 v9, v4, v5
	global_store_dwordx4 v[18:19], v[6:9], off offset:256
	s_cbranch_vccz .LBB0_514
	s_waitcnt vmcnt(0)
	s_cmpk_gt_u32 s19, 0xff
	v_readlane_b32 s29, v254, 8
	s_cbranch_scc1 .LBB0_521
	s_barrier
